# v22: v21 + every MMA block issues its first 4 MFMAs before the block's opening barrier (counted lgkmcnt wait), to keep the matrix pipe fed across the barrier hand-over
# baseline (speedup 1.0000x reference)
; #define PG8_STAGE(bufoff, gbase, voff) do { _Pragma("unroll") for (int _i = 0; _i < 2; ++_i) \
;         __builtin_amdgcn_global_load_lds((const unsigned*)((const char*)(gbase) + (voff)[_i]), (LAS unsigned*)(lds + (bufoff) + ldsw + _i * 8192), 16, 0, 0); } while (0)
; #define PG8_WAIT_V(n) asm volatile("s_waitcnt vmcnt(" #n ")" ::: "memory")
; #define PG8_BAR __builtin_amdgcn_s_barrier()
; template <class Epi, class Ptrs>
; __device__ __forceinline__ void gemm_phase(LAS unsigned char* lds, const int K, const StaticOrder& S, const Ptrs& P, const Epi& E) {
;     ...
;     for (int i = 0; i < 2; ++i) { int R, C; stage_rc(tid * 16 + i * 8192, R, C); const int Rb = (R & ~31) + perm32(R & 31);
;         voffA[i] = (unsigned)(R * K + C) * 2u; voffB[i] = (unsigned)(Rb * K + C) * 2u; }
;     const size_t kstep = (size_t)(BK * 2);
;     const size_t hstep = (size_t)HALF * K * 2;
;     const unsigned ldsw = (unsigned)wid * 1024u;
;     const int aoff = lds_byte(wr * 64 + fr, fq * 8), boff = lds_byte(wc * 32 + fr, fq * 8);
;     ...
;     Unit cur, nxt; int ui = 0;
;     if (!S.next(0, cur)) return;
;     f32x4 acc[2][2][4][2];
; #pragma unroll
;     for (int a = 0; a < 2; ++a)
; #pragma unroll
;         for (int b = 0; b < 2; ++b)
; #pragma unroll
;             for (int m = 0; m < 4; ++m)
; #pragma unroll
;                 for (int n = 0; n < 2; ++n) acc[a][b][m][n] = (f32x4){0.f, 0.f, 0.f, 0.f};
;     bf16x8 At[4][2], B0[2][2], B1[2][2];
;     const char* cA; const char* cB; P.get(cur, cA, cB);
;     PG8_STAGE(PG8_SB(0, 0), cB, voffB); PG8_STAGE(PG8_SA(0, 0), cA, voffA); PG8_STAGE(PG8_SB(0, 1), cB + hstep, voffB); PG8_STAGE(PG8_SA(0, 1), cA + hstep, voffA);
;     if (wr == 1) PG8_BAR;
;     PG8_WAIT_V(4); PG8_BAR;
;     PG8_STAGE(PG8_SB(1, 0), cB + kstep, voffB); PG8_STAGE(PG8_SA(1, 0), cA + kstep, voffA); PG8_STAGE(PG8_SB(1, 1), cB + hstep + kstep, voffB);
;     PG8_WAIT_V(6); PG8_BAR;
.LBB0_120:
	s_add_u32 s4, s28, 0x35000000
	s_addc_u32 s5, s29, 0
	s_mov_b64 s[58:59], 0x80
	v_writelane_b32 v254, s4, 0
	v_lshl_add_u64 v[6:7], v[6:7], 0, s[58:59]
	s_waitcnt vmcnt(4)
	s_barrier
	v_writelane_b32 v254, s5, 1
	s_add_u32 s4, s28, 0x26000000
	s_addc_u32 s5, s29, 0
	s_add_u32 s42, s28, 0x32000000
	s_addc_u32 s43, s29, 0
	s_add_u32 s44, s28, 0x2000000
	s_addc_u32 s45, s29, 0
	s_add_u32 s48, s26, 0xc000000
	s_addc_u32 s49, s27, 0
	s_add_u32 s54, s28, 0x3e000000
	s_addc_u32 s55, s29, 0
	s_add_u32 s56, s28, 0xe000000
	s_addc_u32 s57, s29, 0
	s_lshl_b32 s1, s1, 5
	s_and_b32 s88, s1, 0x60
	s_add_i32 m0, s67, 0x18000
	v_writelane_b32 v254, s4, 2
	s_ashr_i32 s86, s3, 31
	s_ashr_i32 s87, s2, 31
	s_lshl_b32 s20, s0, 13
	s_lshl_b32 s1, s88, 7
	global_load_lds_dwordx4 v[6:7], off
	v_lshl_add_u64 v[4:5], v[4:5], 0, s[58:59]
	s_add_i32 m0, s67, 0x1a000
	s_add_i32 s89, s67, 0x8000
	s_add_i32 s90, s67, 0xa000
	v_writelane_b32 v254, s5, 3
	global_load_lds_dwordx4 v[4:5], off
	v_lshl_add_u64 v[2:3], v[2:3], 0, s[58:59]
	s_mov_b32 m0, s89
	s_add_u32 s4, s78, 0x40080
	global_load_lds_dwordx4 v[2:3], off
	v_lshl_add_u64 v[0:1], v[0:1], 0, s[58:59]
	s_mov_b32 m0, s90
	s_addc_u32 s5, s79, 0
	global_load_lds_dwordx4 v[0:1], off
	s_add_i32 m0, s67, 0x1c000
	v_lshl_add_u64 v[0:1], s[4:5], 0, v[134:135]
	global_load_lds_dwordx4 v[0:1], off
	v_lshl_add_u64 v[0:1], s[4:5], 0, v[138:139]
	s_add_i32 m0, s67, 0x1e000
	v_lshlrev_b32_e32 v2, 6, v208
	global_load_lds_dwordx4 v[0:1], off
	v_and_b32_e32 v0, 15, v208
	v_lshlrev_b32_e32 v1, 1, v130
	s_movk_i32 s4, 0x3c0
	v_lshlrev_b32_e32 v3, 2, v208
	v_and_or_b32 v2, v2, s4, v1
	v_and_b32_e32 v3, 32, v3
	v_cmp_eq_u32_e64 s[10:11], 0, v0
	v_lshl_or_b32 v129, s0, 6, v0
	v_lshl_or_b32 v0, v0, 6, v1
	v_lshlrev_b32_e32 v1, 8, v208
	v_bitop3_b32 v131, s1, v2, v3 bitop3:0xf6
	v_and_b32_e32 v1, 0x38000, v1
	v_lshlrev_b32_e32 v2, 11, v10
	v_or3_b32 v1, v8, v1, v2
	v_add_u32_e32 v142, v1, v9
	v_lshlrev_b32_e32 v1, 4, v11
	s_waitcnt vmcnt(6)
	v_and_b32_e32 v1, 0x78000, v1
	v_bitop3_b32 v0, v0, s20, v3 bitop3:0xde
	v_or3_b32 v1, v8, v1, v2
	s_add_i32 s91, 0, 0x10000
	s_add_i32 s92, 0, 0x14000
	v_or_b32_e32 v204, s88, v130
	v_mov_b32_e32 v143, v141
	v_add_u32_e32 v144, v1, v9
	v_mov_b32_e32 v145, v141
	v_mov_b64_e32 v[146:147], 0x2100
	v_mov_b64_e32 v[148:149], 0x20ff
	v_add_u32_e32 v205, s91, v131
	v_add_u32_e32 v206, 0, v0
	v_add_u32_e32 v207, s92, v131
	s_mov_b32 s60, 0xbfb8aa3b
	s_lshl_b32 s62, s0, 2
	s_mov_b32 s64, 0x3dd2d3e7
	s_mov_b32 s66, 0xc0135761
	s_mov_b32 s93, 0x600000
	s_mov_b32 s94, 0x900000
	s_mov_b32 s95, 0x1800000
	s_mov_b32 s96, 0x1b00000
	s_mov_b32 s97, 0x1e00000
	s_mov_b32 s98, 0x2100000
	s_mov_b32 s99, 0x40000
	s_mov_b32 s22, 0x48000
	s_mov_b32 s23, 0x50000
	s_nop 0
	s_nop 0
	s_nop 0
	s_nop 0
	s_nop 0
	s_nop 0
	s_nop 0
	s_nop 0
	s_nop 0
	s_nop 0
	s_nop 0
	s_nop 0
	s_nop 0
	s_nop 0
	s_nop 0
	s_nop 0
	s_nop 0
	s_nop 0
	s_nop 0
	s_nop 0
	s_nop 0
	s_nop 0
	s_nop 0
	s_nop 0
	s_nop 0
	s_nop 0
	s_nop 0
	s_nop 0
	s_nop 0
	s_nop 0
	s_nop 0
	s_nop 0
	s_nop 0
	s_nop 0
	s_nop 0
	s_nop 0
	s_nop 0
	s_nop 0
	s_nop 0
	s_nop 0
	s_nop 0
	s_nop 0
	s_nop 0
	s_nop 0
	s_nop 0
	s_nop 0
	s_nop 0
	s_nop 0
	s_nop 0
	s_mov_b32 s24, 0
	s_cmpk_lt_u32 s61, 0x100
	s_cbranch_scc1 .Lsprio_0
	s_setprio 1

; #define PG8_STAGE(bufoff, gbase, voff) do { _Pragma("unroll") for (int _i = 0; _i < 2; ++_i) \
;         __builtin_amdgcn_global_load_lds((const unsigned*)((const char*)(gbase) + (voff)[_i]), (LAS unsigned*)(lds + (bufoff) + ldsw + _i * 8192), 16, 0, 0); } while (0)
; #define PG8_LDA(dst, b, h) do { _Pragma("unroll") for (int m = 0; m < 4; ++m) _Pragma("unroll") for (int k = 0; k < 2; ++k) dst[m][k] = *(const LAS bf16x8*)(lds + PG8_SA(b, h) + aoff + m * 2048 + k * 1024); } while (0)
; #define PG8_WAIT_V(n) asm volatile("s_waitcnt vmcnt(" #n ")" ::: "memory")
; #define PG8_BAR __builtin_amdgcn_s_barrier()
; template <class Epi, class Ptrs>
; __device__ __forceinline__ void gemm_phase(LAS unsigned char* lds, const int K, const StaticOrder& S, const Ptrs& P, const Epi& E) {
;     ...
;         for (int t = 0; t < nt; t += 2) {
;             const bool last = (t == nt - 2);
;             const char* a1 = cA + (size_t)(t + 1) * kstep;
;             const char* a2 = last ? nA : cA + (size_t)(t + 2) * kstep; const char* b2 = last ? nB : cB + (size_t)(t + 2) * kstep;
;             const char* a3 = a2 + kstep; const char* b3 = b2 + kstep;
;             PG8_LDB(B0, 0, 0); PG8_SCHED; PG8_LDA(At, 0, 0); PG8_STAGE(PG8_SA(1, 1), a1 + hstep, voffA);
;             PG8_WAIT_L(8); PG8_BAR; PG8_WAIT_L(0); PG8_MMA(0, 0, At, B0); PG8_BAR; PG8_SCHED;
;             PG8_LDB(B1, 0, 1); PG8_STAGE(PG8_SB(0, 0), b2, voffB);
;             PG8_BAR; PG8_WAIT_L(0); PG8_MMA(0, 1, At, B1); PG8_BAR;
;             PG8_LDA(At, 0, 1); PG8_STAGE(PG8_SA(0, 0), a2, voffA);
;             PG8_BAR; PG8_WAIT_L(0); PG8_MMA(1, 0, At, B0); PG8_BAR; PG8_SCHED;
;             PG8_STAGE(PG8_SB(0, 1), b2 + hstep, voffB);
;             PG8_WAIT_V(6); PG8_BAR; PG8_MMA(1, 1, At, B1); PG8_BAR;
;             PG8_LDB(B0, 1, 0); PG8_SCHED; PG8_LDA(At, 1, 0); PG8_STAGE(PG8_SA(0, 1), a2 + hstep, voffA);
;             PG8_WAIT_L(8); PG8_BAR; PG8_WAIT_L(0); PG8_MMA(0, 0, At, B0); PG8_BAR; PG8_SCHED;
;             PG8_LDB(B1, 1, 1); PG8_STAGE(PG8_SB(1, 0), b3, voffB);
;             PG8_BAR; PG8_WAIT_L(0); PG8_MMA(0, 1, At, B1); PG8_BAR;
;             PG8_LDA(At, 1, 1); PG8_STAGE(PG8_SA(1, 0), a3, voffA);
;             PG8_BAR; PG8_WAIT_L(0); PG8_MMA(1, 0, At, B0); PG8_BAR; PG8_SCHED;
;             PG8_STAGE(PG8_SB(1, 1), b3 + hstep, voffB);
;             PG8_WAIT_V(6); PG8_BAR; PG8_MMA(1, 1, At, B1); PG8_BAR;
.LBB0_126:
	s_add_u32 s6, s6, 0x40080
	s_addc_u32 s7, s7, 0
	s_add_u32 s20, s78, 0x100
	s_addc_u32 s25, s79, 0
	s_mov_b32 s63, -2
	v_add_u32_e32 v252, 0x18000, v131
	v_add_u32_e32 v253, 0x1c000, v131
	ds_read_b128 v[150:153], v205
	ds_read_b128 v[154:157], v205 offset:1024
	ds_read_b128 v[158:161], v205 offset:2048
	ds_read_b128 v[162:165], v205 offset:3072
	s_add_u32 s69, s6, 0xfffc0080
	s_addc_u32 s71, s7, -1
	s_cmp_eq_u32 s63, 12
	s_cselect_b32 s81, s1, s71
	s_cselect_b32 s80, s0, s69
	s_cselect_b32 s79, s73, s25
	s_cselect_b32 s78, s72, s20
	s_add_i32 m0, s67, 0xc000
	ds_read_b128 v[166:169], v206
	ds_read_b128 v[170:173], v206 offset:1024
	ds_read_b128 v[174:177], v206 offset:2048
	ds_read_b128 v[178:181], v206 offset:3072
	ds_read_b128 v[182:185], v206 offset:4096
	ds_read_b128 v[186:189], v206 offset:5120
	ds_read_b128 v[190:193], v206 offset:6144
	ds_read_b128 v[194:197], v206 offset:7168
	global_load_lds_dwordx4 v142, s[6:7]
	s_add_i32 m0, s67, 0xe000
	s_nop 0
	global_load_lds_dwordx4 v144, s[6:7]
	s_waitcnt lgkmcnt(8)
	s_waitcnt lgkmcnt(6)
	v_mfma_f32_16x16x32_bf16 v[120:123], v[150:153], v[166:169], 0
	v_mfma_f32_16x16x32_bf16 v[120:123], v[154:157], v[170:173], v[120:123]
	v_mfma_f32_16x16x32_bf16 v[116:119], v[162:165], v[170:173], 0
	v_mfma_f32_16x16x32_bf16 v[116:119], v[158:161], v[166:169], v[116:119]
	s_barrier
	s_waitcnt lgkmcnt(0)
	v_mfma_f32_16x16x32_bf16 v[100:103], v[158:161], v[174:177], 0
	v_mfma_f32_16x16x32_bf16 v[100:103], v[162:165], v[178:181], v[100:103]
	v_mfma_f32_16x16x32_bf16 v[104:107], v[154:157], v[178:181], 0
	v_mfma_f32_16x16x32_bf16 v[104:107], v[150:153], v[174:177], v[104:107]
	v_mfma_f32_16x16x32_bf16 v[88:91], v[150:153], v[182:185], 0
	v_mfma_f32_16x16x32_bf16 v[88:91], v[154:157], v[186:189], v[88:91]
	v_mfma_f32_16x16x32_bf16 v[84:87], v[162:165], v[186:189], 0
	v_mfma_f32_16x16x32_bf16 v[84:87], v[158:161], v[182:185], v[84:87]
	v_mfma_f32_16x16x32_bf16 v[68:71], v[158:161], v[190:193], 0
	v_mfma_f32_16x16x32_bf16 v[68:71], v[162:165], v[194:197], v[68:71]
	v_mfma_f32_16x16x32_bf16 v[72:75], v[154:157], v[194:197], 0
	v_mfma_f32_16x16x32_bf16 v[72:75], v[150:153], v[190:193], v[72:75]
	s_barrier
	s_add_i32 s69, s91, s65
	s_add_u32 s100, s78, 0x80
	s_addc_u32 s101, s79, 0
	s_mov_b32 m0, s69
	ds_read_b128 v[198:201], v207
	ds_read_b128 v[210:213], v207 offset:1024
	ds_read_b128 v[214:217], v207 offset:2048
	ds_read_b128 v[218:221], v207 offset:3072
	global_load_lds_dwordx4 v134, s[78:79]
	s_add_i32 m0, s69, 0x2000
	s_nop 0
	global_load_lds_dwordx4 v138, s[78:79]
	s_waitcnt lgkmcnt(0)
	v_mfma_f32_16x16x32_bf16 v[124:127], v[198:201], v[166:169], 0
	v_mfma_f32_16x16x32_bf16 v[124:127], v[210:213], v[170:173], v[124:127]
	v_mfma_f32_16x16x32_bf16 v[112:115], v[218:221], v[170:173], 0
	v_mfma_f32_16x16x32_bf16 v[112:115], v[214:217], v[166:169], v[112:115]
	s_barrier
	s_waitcnt lgkmcnt(0)
	v_mfma_f32_16x16x32_bf16 v[96:99], v[214:217], v[174:177], 0
	v_mfma_f32_16x16x32_bf16 v[96:99], v[218:221], v[178:181], v[96:99]
	v_mfma_f32_16x16x32_bf16 v[108:111], v[210:213], v[178:181], 0
	v_mfma_f32_16x16x32_bf16 v[108:111], v[198:201], v[174:177], v[108:111]
	v_mfma_f32_16x16x32_bf16 v[92:95], v[198:201], v[182:185], 0
	v_mfma_f32_16x16x32_bf16 v[92:95], v[210:213], v[186:189], v[92:95]
	v_mfma_f32_16x16x32_bf16 v[80:83], v[218:221], v[186:189], 0
	v_mfma_f32_16x16x32_bf16 v[80:83], v[214:217], v[182:185], v[80:83]
	v_mfma_f32_16x16x32_bf16 v[64:67], v[214:217], v[190:193], 0
	v_mfma_f32_16x16x32_bf16 v[64:67], v[218:221], v[194:197], v[64:67]
	v_mfma_f32_16x16x32_bf16 v[76:79], v[210:213], v[194:197], 0
	v_mfma_f32_16x16x32_bf16 v[76:79], v[198:201], v[190:193], v[76:79]
	s_barrier
	s_mov_b32 m0, s67
	ds_read_b128 v[166:169], v206 offset:16384
	ds_read_b128 v[170:173], v206 offset:17408
	ds_read_b128 v[174:177], v206 offset:18432
	ds_read_b128 v[178:181], v206 offset:19456
	ds_read_b128 v[182:185], v206 offset:20480
	ds_read_b128 v[186:189], v206 offset:21504
	ds_read_b128 v[190:193], v206 offset:22528
	ds_read_b128 v[194:197], v206 offset:23552
	global_load_lds_dwordx4 v132, s[80:81]
	s_mov_b32 m0, s75
	s_nop 0
	global_load_lds_dwordx4 v136, s[80:81]
	s_waitcnt lgkmcnt(6)
	v_mfma_f32_16x16x32_bf16 v[56:59], v[150:153], v[166:169], 0
	v_mfma_f32_16x16x32_bf16 v[56:59], v[154:157], v[170:173], v[56:59]
	v_mfma_f32_16x16x32_bf16 v[52:55], v[162:165], v[170:173], 0
	v_mfma_f32_16x16x32_bf16 v[52:55], v[158:161], v[166:169], v[52:55]
	s_barrier
	s_waitcnt lgkmcnt(0)
	v_mfma_f32_16x16x32_bf16 v[36:39], v[158:161], v[174:177], 0
	v_mfma_f32_16x16x32_bf16 v[36:39], v[162:165], v[178:181], v[36:39]
	v_mfma_f32_16x16x32_bf16 v[40:43], v[154:157], v[178:181], 0
	v_mfma_f32_16x16x32_bf16 v[40:43], v[150:153], v[174:177], v[40:43]
	v_mfma_f32_16x16x32_bf16 v[24:27], v[150:153], v[182:185], 0
	v_mfma_f32_16x16x32_bf16 v[24:27], v[154:157], v[186:189], v[24:27]
	v_mfma_f32_16x16x32_bf16 v[20:23], v[162:165], v[186:189], 0
	v_mfma_f32_16x16x32_bf16 v[20:23], v[158:161], v[182:185], v[20:23]
	v_mfma_f32_16x16x32_bf16 v[4:7], v[158:161], v[190:193], 0
	v_mfma_f32_16x16x32_bf16 v[4:7], v[162:165], v[194:197], v[4:7]
	v_mfma_f32_16x16x32_bf16 v[8:11], v[154:157], v[194:197], 0
	v_mfma_f32_16x16x32_bf16 v[8:11], v[150:153], v[190:193], v[8:11]
	s_barrier
	s_add_u32 s82, s78, 0x40000
	s_addc_u32 s83, s79, 0
	s_add_i32 s69, s92, s65
	s_mov_b32 m0, s69
	s_nop 0
	global_load_lds_dwordx4 v134, s[82:83]
	s_add_i32 m0, s69, 0x2000
	s_nop 0
	global_load_lds_dwordx4 v138, s[82:83]
	s_waitcnt vmcnt(6)
	v_mfma_f32_16x16x32_bf16 v[60:63], v[198:201], v[166:169], 0
	v_mfma_f32_16x16x32_bf16 v[60:63], v[210:213], v[170:173], v[60:63]
	v_mfma_f32_16x16x32_bf16 v[48:51], v[218:221], v[170:173], 0
	v_mfma_f32_16x16x32_bf16 v[48:51], v[214:217], v[166:169], v[48:51]
	s_barrier
; #define PG8_STAGE(bufoff, gbase, voff) do { _Pragma("unroll") for (int _i = 0; _i < 2; ++_i) \
;         __builtin_amdgcn_global_load_lds((const unsigned*)((const char*)(gbase) + (voff)[_i]), (LAS unsigned*)(lds + (bufoff) + ldsw + _i * 8192), 16, 0, 0); } while (0)
; #define PG8_LDA(dst, b, h) do { _Pragma("unroll") for (int m = 0; m < 4; ++m) _Pragma("unroll") for (int k = 0; k < 2; ++k) dst[m][k] = *(const LAS bf16x8*)(lds + PG8_SA(b, h) + aoff + m * 2048 + k * 1024); } while (0)
; #define PG8_WAIT_V(n) asm volatile("s_waitcnt vmcnt(" #n ")" ::: "memory")
; #define PG8_BAR __builtin_amdgcn_s_barrier()
; template <class Epi, class Ptrs>
; __device__ __forceinline__ void gemm_phase(LAS unsigned char* lds, const int K, const StaticOrder& S, const Ptrs& P, const Epi& E) {
;     ...
;         for (int t = 0; t < nt; t += 2) {
;             const bool last = (t == nt - 2);
;             const char* a1 = cA + (size_t)(t + 1) * kstep;
;             const char* a2 = last ? nA : cA + (size_t)(t + 2) * kstep; const char* b2 = last ? nB : cB + (size_t)(t + 2) * kstep;
;             const char* a3 = a2 + kstep; const char* b3 = b2 + kstep;
;             PG8_LDB(B0, 0, 0); PG8_SCHED; PG8_LDA(At, 0, 0); PG8_STAGE(PG8_SA(1, 1), a1 + hstep, voffA);
;             PG8_WAIT_L(8); PG8_BAR; PG8_WAIT_L(0); PG8_MMA(0, 0, At, B0); PG8_BAR; PG8_SCHED;
;             PG8_LDB(B1, 0, 1); PG8_STAGE(PG8_SB(0, 0), b2, voffB);
;             PG8_BAR; PG8_WAIT_L(0); PG8_MMA(0, 1, At, B1); PG8_BAR;
;             PG8_LDA(At, 0, 1); PG8_STAGE(PG8_SA(0, 0), a2, voffA);
;             PG8_BAR; PG8_WAIT_L(0); PG8_MMA(1, 0, At, B0); PG8_BAR; PG8_SCHED;
;             PG8_STAGE(PG8_SB(0, 1), b2 + hstep, voffB);
;             PG8_WAIT_V(6); PG8_BAR; PG8_MMA(1, 1, At, B1); PG8_BAR;
;             PG8_LDB(B0, 1, 0); PG8_SCHED; PG8_LDA(At, 1, 0); PG8_STAGE(PG8_SA(0, 1), a2 + hstep, voffA);
;             PG8_WAIT_L(8); PG8_BAR; PG8_WAIT_L(0); PG8_MMA(0, 0, At, B0); PG8_BAR; PG8_SCHED;
;             PG8_LDB(B1, 1, 1); PG8_STAGE(PG8_SB(1, 0), b3, voffB);
;             PG8_BAR; PG8_WAIT_L(0); PG8_MMA(0, 1, At, B1); PG8_BAR;
;             PG8_LDA(At, 1, 1); PG8_STAGE(PG8_SA(1, 0), a3, voffA);
;             PG8_BAR; PG8_WAIT_L(0); PG8_MMA(1, 0, At, B0); PG8_BAR; PG8_SCHED;
;             PG8_STAGE(PG8_SB(1, 1), b3 + hstep, voffB);
;             PG8_WAIT_V(6); PG8_BAR; PG8_MMA(1, 1, At, B1); PG8_BAR;
	v_mfma_f32_16x16x32_bf16 v[32:35], v[214:217], v[174:177], 0
	v_mfma_f32_16x16x32_bf16 v[32:35], v[218:221], v[178:181], v[32:35]
	v_mfma_f32_16x16x32_bf16 v[44:47], v[210:213], v[178:181], 0
	v_mfma_f32_16x16x32_bf16 v[44:47], v[198:201], v[174:177], v[44:47]
	v_mfma_f32_16x16x32_bf16 v[28:31], v[198:201], v[182:185], 0
	v_mfma_f32_16x16x32_bf16 v[28:31], v[210:213], v[186:189], v[28:31]
	v_mfma_f32_16x16x32_bf16 v[16:19], v[218:221], v[186:189], 0
	v_mfma_f32_16x16x32_bf16 v[16:19], v[214:217], v[182:185], v[16:19]
	v_mfma_f32_16x16x32_bf16 v[0:3], v[214:217], v[190:193], 0
	v_mfma_f32_16x16x32_bf16 v[0:3], v[218:221], v[194:197], v[0:3]
	v_mfma_f32_16x16x32_bf16 v[12:15], v[210:213], v[194:197], 0
	v_mfma_f32_16x16x32_bf16 v[12:15], v[198:201], v[190:193], v[12:15]
	s_barrier
	s_add_i32 s69, 0, 0x18000
	ds_read_b128 v[150:153], v252
	ds_read_b128 v[154:157], v252 offset:1024
	ds_read_b128 v[158:161], v252 offset:2048
	ds_read_b128 v[162:165], v252 offset:3072
	s_add_u32 s80, s80, 0x40000
	s_addc_u32 s81, s81, 0
	s_mov_b32 m0, s77
	ds_read_b128 v[166:169], v206 offset:32768
	ds_read_b128 v[170:173], v206 offset:33792
	ds_read_b128 v[174:177], v206 offset:34816
	ds_read_b128 v[178:181], v206 offset:35840
	ds_read_b128 v[182:185], v206 offset:36864
	ds_read_b128 v[186:189], v206 offset:37888
	ds_read_b128 v[190:193], v206 offset:38912
	ds_read_b128 v[194:197], v206 offset:39936
	global_load_lds_dwordx4 v132, s[80:81]
	s_mov_b32 m0, s85
	s_nop 0
	global_load_lds_dwordx4 v136, s[80:81]
	s_waitcnt lgkmcnt(8)
	s_waitcnt lgkmcnt(6)
	v_mfma_f32_16x16x32_bf16 v[120:123], v[150:153], v[166:169], v[120:123]
	v_mfma_f32_16x16x32_bf16 v[120:123], v[154:157], v[170:173], v[120:123]
	v_mfma_f32_16x16x32_bf16 v[116:119], v[162:165], v[170:173], v[116:119]
	v_mfma_f32_16x16x32_bf16 v[116:119], v[158:161], v[166:169], v[116:119]
	s_barrier
	s_waitcnt lgkmcnt(0)
	v_mfma_f32_16x16x32_bf16 v[100:103], v[158:161], v[174:177], v[100:103]
	v_mfma_f32_16x16x32_bf16 v[100:103], v[162:165], v[178:181], v[100:103]
	v_mfma_f32_16x16x32_bf16 v[104:107], v[154:157], v[178:181], v[104:107]
	v_mfma_f32_16x16x32_bf16 v[104:107], v[150:153], v[174:177], v[104:107]
	v_mfma_f32_16x16x32_bf16 v[88:91], v[150:153], v[182:185], v[88:91]
	v_mfma_f32_16x16x32_bf16 v[88:91], v[154:157], v[186:189], v[88:91]
	v_mfma_f32_16x16x32_bf16 v[84:87], v[162:165], v[186:189], v[84:87]
	v_mfma_f32_16x16x32_bf16 v[84:87], v[158:161], v[182:185], v[84:87]
	v_mfma_f32_16x16x32_bf16 v[68:71], v[158:161], v[190:193], v[68:71]
	v_mfma_f32_16x16x32_bf16 v[68:71], v[162:165], v[194:197], v[68:71]
	v_mfma_f32_16x16x32_bf16 v[72:75], v[154:157], v[194:197], v[72:75]
	v_mfma_f32_16x16x32_bf16 v[72:75], v[150:153], v[190:193], v[72:75]
	s_barrier
	s_add_i32 s71, 0, 0x1c000
	s_add_i32 s69, s69, s65
	s_mov_b32 m0, s69
	ds_read_b128 v[198:201], v253
	ds_read_b128 v[210:213], v253 offset:1024
	ds_read_b128 v[214:217], v253 offset:2048
	ds_read_b128 v[218:221], v253 offset:3072
	global_load_lds_dwordx4 v134, s[100:101]
	s_add_i32 m0, s69, 0x2000
	s_nop 0
	global_load_lds_dwordx4 v138, s[100:101]
	s_waitcnt lgkmcnt(0)
	v_mfma_f32_16x16x32_bf16 v[124:127], v[198:201], v[166:169], v[124:127]
	v_mfma_f32_16x16x32_bf16 v[124:127], v[210:213], v[170:173], v[124:127]
	v_mfma_f32_16x16x32_bf16 v[112:115], v[218:221], v[170:173], v[112:115]
	v_mfma_f32_16x16x32_bf16 v[112:115], v[214:217], v[166:169], v[112:115]
	s_barrier
	s_waitcnt lgkmcnt(0)
	v_mfma_f32_16x16x32_bf16 v[96:99], v[214:217], v[174:177], v[96:99]
	v_mfma_f32_16x16x32_bf16 v[96:99], v[218:221], v[178:181], v[96:99]
	v_mfma_f32_16x16x32_bf16 v[108:111], v[210:213], v[178:181], v[108:111]
	v_mfma_f32_16x16x32_bf16 v[108:111], v[198:201], v[174:177], v[108:111]
	v_mfma_f32_16x16x32_bf16 v[92:95], v[198:201], v[182:185], v[92:95]
	v_mfma_f32_16x16x32_bf16 v[92:95], v[210:213], v[186:189], v[92:95]
	v_mfma_f32_16x16x32_bf16 v[80:83], v[218:221], v[186:189], v[80:83]
	v_mfma_f32_16x16x32_bf16 v[80:83], v[214:217], v[182:185], v[80:83]
	v_mfma_f32_16x16x32_bf16 v[64:67], v[214:217], v[190:193], v[64:67]
	v_mfma_f32_16x16x32_bf16 v[64:67], v[218:221], v[194:197], v[64:67]
	v_mfma_f32_16x16x32_bf16 v[76:79], v[210:213], v[194:197], v[76:79]
	v_mfma_f32_16x16x32_bf16 v[76:79], v[198:201], v[190:193], v[76:79]
	s_barrier
	s_mov_b32 m0, s89
	s_add_u32 s100, s80, 0xfffc0080
	s_addc_u32 s101, s81, -1
	ds_read_b128 v[166:169], v206 offset:49152
	ds_read_b128 v[170:173], v206 offset:50176
	ds_read_b128 v[174:177], v206 offset:51200
	ds_read_b128 v[178:181], v206 offset:52224
	ds_read_b128 v[182:185], v206 offset:53248
	ds_read_b128 v[186:189], v206 offset:54272
	ds_read_b128 v[190:193], v206 offset:55296
	ds_read_b128 v[194:197], v206 offset:56320
	global_load_lds_dwordx4 v132, s[100:101]
	s_mov_b32 m0, s90
	s_nop 0
	global_load_lds_dwordx4 v136, s[100:101]
	s_waitcnt lgkmcnt(6)
	v_mfma_f32_16x16x32_bf16 v[56:59], v[150:153], v[166:169], v[56:59]
	v_mfma_f32_16x16x32_bf16 v[56:59], v[154:157], v[170:173], v[56:59]
	v_mfma_f32_16x16x32_bf16 v[52:55], v[162:165], v[170:173], v[52:55]
	v_mfma_f32_16x16x32_bf16 v[52:55], v[158:161], v[166:169], v[52:55]
	s_barrier
	s_waitcnt lgkmcnt(0)
	v_mfma_f32_16x16x32_bf16 v[36:39], v[158:161], v[174:177], v[36:39]
	v_mfma_f32_16x16x32_bf16 v[36:39], v[162:165], v[178:181], v[36:39]
	v_mfma_f32_16x16x32_bf16 v[40:43], v[154:157], v[178:181], v[40:43]
	v_mfma_f32_16x16x32_bf16 v[40:43], v[150:153], v[174:177], v[40:43]
	v_mfma_f32_16x16x32_bf16 v[24:27], v[150:153], v[182:185], v[24:27]
	v_mfma_f32_16x16x32_bf16 v[24:27], v[154:157], v[186:189], v[24:27]
	v_mfma_f32_16x16x32_bf16 v[20:23], v[162:165], v[186:189], v[20:23]
	v_mfma_f32_16x16x32_bf16 v[20:23], v[158:161], v[182:185], v[20:23]
	v_mfma_f32_16x16x32_bf16 v[4:7], v[158:161], v[190:193], v[4:7]
	v_mfma_f32_16x16x32_bf16 v[4:7], v[162:165], v[194:197], v[4:7]
	v_mfma_f32_16x16x32_bf16 v[8:11], v[154:157], v[194:197], v[8:11]
	v_mfma_f32_16x16x32_bf16 v[8:11], v[150:153], v[190:193], v[8:11]
	s_barrier
; #define PG8_STAGE(bufoff, gbase, voff) do { _Pragma("unroll") for (int _i = 0; _i < 2; ++_i) \
;         __builtin_amdgcn_global_load_lds((const unsigned*)((const char*)(gbase) + (voff)[_i]), (LAS unsigned*)(lds + (bufoff) + ldsw + _i * 8192), 16, 0, 0); } while (0)
; #define PG8_LDA(dst, b, h) do { _Pragma("unroll") for (int m = 0; m < 4; ++m) _Pragma("unroll") for (int k = 0; k < 2; ++k) dst[m][k] = *(const LAS bf16x8*)(lds + PG8_SA(b, h) + aoff + m * 2048 + k * 1024); } while (0)
; #define PG8_WAIT_V(n) asm volatile("s_waitcnt vmcnt(" #n ")" ::: "memory")
; #define PG8_BAR __builtin_amdgcn_s_barrier()
; template <class Epi, class Ptrs>
; __device__ __forceinline__ void gemm_phase(LAS unsigned char* lds, const int K, const StaticOrder& S, const Ptrs& P, const Epi& E) {
;     ...
;         for (int t = 0; t < nt; t += 2) {
;             const bool last = (t == nt - 2);
;             const char* a1 = cA + (size_t)(t + 1) * kstep;
;             const char* a2 = last ? nA : cA + (size_t)(t + 2) * kstep; const char* b2 = last ? nB : cB + (size_t)(t + 2) * kstep;
;             const char* a3 = a2 + kstep; const char* b3 = b2 + kstep;
;             PG8_LDB(B0, 0, 0); PG8_SCHED; PG8_LDA(At, 0, 0); PG8_STAGE(PG8_SA(1, 1), a1 + hstep, voffA);
;             PG8_WAIT_L(8); PG8_BAR; PG8_WAIT_L(0); PG8_MMA(0, 0, At, B0); PG8_BAR; PG8_SCHED;
;             PG8_LDB(B1, 0, 1); PG8_STAGE(PG8_SB(0, 0), b2, voffB);
;             PG8_BAR; PG8_WAIT_L(0); PG8_MMA(0, 1, At, B1); PG8_BAR;
;             PG8_LDA(At, 0, 1); PG8_STAGE(PG8_SA(0, 0), a2, voffA);
;             PG8_BAR; PG8_WAIT_L(0); PG8_MMA(1, 0, At, B0); PG8_BAR; PG8_SCHED;
;             PG8_STAGE(PG8_SB(0, 1), b2 + hstep, voffB);
;             PG8_WAIT_V(6); PG8_BAR; PG8_MMA(1, 1, At, B1); PG8_BAR;
;             PG8_LDB(B0, 1, 0); PG8_SCHED; PG8_LDA(At, 1, 0); PG8_STAGE(PG8_SA(0, 1), a2 + hstep, voffA);
;             PG8_WAIT_L(8); PG8_BAR; PG8_WAIT_L(0); PG8_MMA(0, 0, At, B0); PG8_BAR; PG8_SCHED;
;             PG8_LDB(B1, 1, 1); PG8_STAGE(PG8_SB(1, 0), b3, voffB);
;             PG8_BAR; PG8_WAIT_L(0); PG8_MMA(0, 1, At, B1); PG8_BAR;
;             PG8_LDA(At, 1, 1); PG8_STAGE(PG8_SA(1, 0), a3, voffA);
;             PG8_BAR; PG8_WAIT_L(0); PG8_MMA(1, 0, At, B0); PG8_BAR; PG8_SCHED;
;             PG8_STAGE(PG8_SB(1, 1), b3 + hstep, voffB);
;             PG8_WAIT_V(6); PG8_BAR; PG8_MMA(1, 1, At, B1); PG8_BAR;
	s_add_u32 s78, s78, 0x40080
	s_addc_u32 s79, s79, 0
	s_add_i32 s69, s71, s65
	s_mov_b32 m0, s69
	s_nop 0
	global_load_lds_dwordx4 v134, s[78:79]
	s_add_i32 m0, s69, 0x2000
	s_nop 0
	global_load_lds_dwordx4 v138, s[78:79]
	s_waitcnt vmcnt(6)
	v_mfma_f32_16x16x32_bf16 v[60:63], v[198:201], v[166:169], v[60:63]
	v_mfma_f32_16x16x32_bf16 v[60:63], v[210:213], v[170:173], v[60:63]
	v_mfma_f32_16x16x32_bf16 v[48:51], v[218:221], v[170:173], v[48:51]
	v_mfma_f32_16x16x32_bf16 v[48:51], v[214:217], v[166:169], v[48:51]
	s_barrier
	v_mfma_f32_16x16x32_bf16 v[32:35], v[214:217], v[174:177], v[32:35]
	v_mfma_f32_16x16x32_bf16 v[32:35], v[218:221], v[178:181], v[32:35]
	v_mfma_f32_16x16x32_bf16 v[44:47], v[210:213], v[178:181], v[44:47]
	v_mfma_f32_16x16x32_bf16 v[44:47], v[198:201], v[174:177], v[44:47]
	v_mfma_f32_16x16x32_bf16 v[28:31], v[198:201], v[182:185], v[28:31]
	v_mfma_f32_16x16x32_bf16 v[28:31], v[210:213], v[186:189], v[28:31]
	v_mfma_f32_16x16x32_bf16 v[16:19], v[218:221], v[186:189], v[16:19]
	v_mfma_f32_16x16x32_bf16 v[16:19], v[214:217], v[182:185], v[16:19]
	v_mfma_f32_16x16x32_bf16 v[0:3], v[214:217], v[190:193], v[0:3]
	v_mfma_f32_16x16x32_bf16 v[0:3], v[218:221], v[194:197], v[0:3]
	v_mfma_f32_16x16x32_bf16 v[12:15], v[210:213], v[194:197], v[12:15]
	v_mfma_f32_16x16x32_bf16 v[12:15], v[198:201], v[190:193], v[12:15]
	s_barrier
	s_add_i32 s63, s63, 2
	s_add_u32 s6, s6, 0x100
	s_addc_u32 s7, s7, 0
	s_add_u32 s20, s20, 0x100
	s_addc_u32 s25, s25, 0
	s_cmp_gt_u32 s63, 13
.LBB0_127:
	ds_read_b128 v[150:153], v205
	ds_read_b128 v[154:157], v205 offset:1024
	ds_read_b128 v[158:161], v205 offset:2048
	ds_read_b128 v[162:165], v205 offset:3072
	s_add_u32 s69, s6, 0xfffc0080
	s_addc_u32 s71, s7, -1
	s_cmp_eq_u32 s63, 12
	s_cselect_b32 s81, s1, s71
	s_cselect_b32 s80, s0, s69
	s_cselect_b32 s79, s73, s25
	s_cselect_b32 s78, s72, s20
	s_add_i32 m0, s67, 0xc000
	ds_read_b128 v[166:169], v206
	ds_read_b128 v[170:173], v206 offset:1024
	ds_read_b128 v[174:177], v206 offset:2048
	ds_read_b128 v[178:181], v206 offset:3072
	ds_read_b128 v[182:185], v206 offset:4096
	ds_read_b128 v[186:189], v206 offset:5120
	ds_read_b128 v[190:193], v206 offset:6144
	ds_read_b128 v[194:197], v206 offset:7168
	global_load_lds_dwordx4 v142, s[6:7]
	s_add_i32 m0, s67, 0xe000
	s_nop 0
	global_load_lds_dwordx4 v144, s[6:7]
	s_waitcnt lgkmcnt(8)
	s_waitcnt lgkmcnt(6)
	v_mfma_f32_16x16x32_bf16 v[120:123], v[150:153], v[166:169], v[120:123]
	v_mfma_f32_16x16x32_bf16 v[120:123], v[154:157], v[170:173], v[120:123]
	v_mfma_f32_16x16x32_bf16 v[116:119], v[162:165], v[170:173], v[116:119]
	v_mfma_f32_16x16x32_bf16 v[116:119], v[158:161], v[166:169], v[116:119]
	s_barrier
	s_waitcnt lgkmcnt(0)
	v_mfma_f32_16x16x32_bf16 v[100:103], v[158:161], v[174:177], v[100:103]
	v_mfma_f32_16x16x32_bf16 v[100:103], v[162:165], v[178:181], v[100:103]
	v_mfma_f32_16x16x32_bf16 v[104:107], v[154:157], v[178:181], v[104:107]
	v_mfma_f32_16x16x32_bf16 v[104:107], v[150:153], v[174:177], v[104:107]
	v_mfma_f32_16x16x32_bf16 v[88:91], v[150:153], v[182:185], v[88:91]
	v_mfma_f32_16x16x32_bf16 v[88:91], v[154:157], v[186:189], v[88:91]
	v_mfma_f32_16x16x32_bf16 v[84:87], v[162:165], v[186:189], v[84:87]
	v_mfma_f32_16x16x32_bf16 v[84:87], v[158:161], v[182:185], v[84:87]
	v_mfma_f32_16x16x32_bf16 v[68:71], v[158:161], v[190:193], v[68:71]
	v_mfma_f32_16x16x32_bf16 v[68:71], v[162:165], v[194:197], v[68:71]
	v_mfma_f32_16x16x32_bf16 v[72:75], v[154:157], v[194:197], v[72:75]
	v_mfma_f32_16x16x32_bf16 v[72:75], v[150:153], v[190:193], v[72:75]
	s_barrier
	s_add_i32 s69, s91, s65
	s_add_u32 s100, s78, 0x80
	s_addc_u32 s101, s79, 0
	s_mov_b32 m0, s69
	ds_read_b128 v[198:201], v207
	ds_read_b128 v[210:213], v207 offset:1024
	ds_read_b128 v[214:217], v207 offset:2048
	ds_read_b128 v[218:221], v207 offset:3072
	global_load_lds_dwordx4 v134, s[78:79]
	s_add_i32 m0, s69, 0x2000
	s_nop 0
	global_load_lds_dwordx4 v138, s[78:79]
	s_waitcnt lgkmcnt(0)
	v_mfma_f32_16x16x32_bf16 v[124:127], v[198:201], v[166:169], v[124:127]
	v_mfma_f32_16x16x32_bf16 v[124:127], v[210:213], v[170:173], v[124:127]
	v_mfma_f32_16x16x32_bf16 v[112:115], v[218:221], v[170:173], v[112:115]
	v_mfma_f32_16x16x32_bf16 v[112:115], v[214:217], v[166:169], v[112:115]
	s_barrier
	s_waitcnt lgkmcnt(0)
	v_mfma_f32_16x16x32_bf16 v[96:99], v[214:217], v[174:177], v[96:99]
	v_mfma_f32_16x16x32_bf16 v[96:99], v[218:221], v[178:181], v[96:99]
	v_mfma_f32_16x16x32_bf16 v[108:111], v[210:213], v[178:181], v[108:111]
	v_mfma_f32_16x16x32_bf16 v[108:111], v[198:201], v[174:177], v[108:111]
	v_mfma_f32_16x16x32_bf16 v[92:95], v[198:201], v[182:185], v[92:95]
	v_mfma_f32_16x16x32_bf16 v[92:95], v[210:213], v[186:189], v[92:95]
	v_mfma_f32_16x16x32_bf16 v[80:83], v[218:221], v[186:189], v[80:83]
	v_mfma_f32_16x16x32_bf16 v[80:83], v[214:217], v[182:185], v[80:83]
	v_mfma_f32_16x16x32_bf16 v[64:67], v[214:217], v[190:193], v[64:67]
	v_mfma_f32_16x16x32_bf16 v[64:67], v[218:221], v[194:197], v[64:67]
	v_mfma_f32_16x16x32_bf16 v[76:79], v[210:213], v[194:197], v[76:79]
	v_mfma_f32_16x16x32_bf16 v[76:79], v[198:201], v[190:193], v[76:79]
	s_barrier
	s_mov_b32 m0, s67
	ds_read_b128 v[166:169], v206 offset:16384
	ds_read_b128 v[170:173], v206 offset:17408
	ds_read_b128 v[174:177], v206 offset:18432
	ds_read_b128 v[178:181], v206 offset:19456
	ds_read_b128 v[182:185], v206 offset:20480
	ds_read_b128 v[186:189], v206 offset:21504
	ds_read_b128 v[190:193], v206 offset:22528
	ds_read_b128 v[194:197], v206 offset:23552
	global_load_lds_dwordx4 v132, s[80:81]
	s_mov_b32 m0, s75
	s_nop 0
	global_load_lds_dwordx4 v136, s[80:81]
	s_waitcnt lgkmcnt(6)
	v_mfma_f32_16x16x32_bf16 v[56:59], v[150:153], v[166:169], v[56:59]
	v_mfma_f32_16x16x32_bf16 v[56:59], v[154:157], v[170:173], v[56:59]
	v_mfma_f32_16x16x32_bf16 v[52:55], v[162:165], v[170:173], v[52:55]
	v_mfma_f32_16x16x32_bf16 v[52:55], v[158:161], v[166:169], v[52:55]
	s_barrier
; #define PG8_STAGE(bufoff, gbase, voff) do { _Pragma("unroll") for (int _i = 0; _i < 2; ++_i) \
;         __builtin_amdgcn_global_load_lds((const unsigned*)((const char*)(gbase) + (voff)[_i]), (LAS unsigned*)(lds + (bufoff) + ldsw + _i * 8192), 16, 0, 0); } while (0)
; #define PG8_LDA(dst, b, h) do { _Pragma("unroll") for (int m = 0; m < 4; ++m) _Pragma("unroll") for (int k = 0; k < 2; ++k) dst[m][k] = *(const LAS bf16x8*)(lds + PG8_SA(b, h) + aoff + m * 2048 + k * 1024); } while (0)
; #define PG8_WAIT_V(n) asm volatile("s_waitcnt vmcnt(" #n ")" ::: "memory")
; #define PG8_BAR __builtin_amdgcn_s_barrier()
; template <class Epi, class Ptrs>
; __device__ __forceinline__ void gemm_phase(LAS unsigned char* lds, const int K, const StaticOrder& S, const Ptrs& P, const Epi& E) {
;     ...
;         for (int t = 0; t < nt; t += 2) {
;             const bool last = (t == nt - 2);
;             const char* a1 = cA + (size_t)(t + 1) * kstep;
;             const char* a2 = last ? nA : cA + (size_t)(t + 2) * kstep; const char* b2 = last ? nB : cB + (size_t)(t + 2) * kstep;
;             const char* a3 = a2 + kstep; const char* b3 = b2 + kstep;
;             PG8_LDB(B0, 0, 0); PG8_SCHED; PG8_LDA(At, 0, 0); PG8_STAGE(PG8_SA(1, 1), a1 + hstep, voffA);
;             PG8_WAIT_L(8); PG8_BAR; PG8_WAIT_L(0); PG8_MMA(0, 0, At, B0); PG8_BAR; PG8_SCHED;
;             PG8_LDB(B1, 0, 1); PG8_STAGE(PG8_SB(0, 0), b2, voffB);
;             PG8_BAR; PG8_WAIT_L(0); PG8_MMA(0, 1, At, B1); PG8_BAR;
;             PG8_LDA(At, 0, 1); PG8_STAGE(PG8_SA(0, 0), a2, voffA);
;             PG8_BAR; PG8_WAIT_L(0); PG8_MMA(1, 0, At, B0); PG8_BAR; PG8_SCHED;
;             PG8_STAGE(PG8_SB(0, 1), b2 + hstep, voffB);
;             PG8_WAIT_V(6); PG8_BAR; PG8_MMA(1, 1, At, B1); PG8_BAR;
;             PG8_LDB(B0, 1, 0); PG8_SCHED; PG8_LDA(At, 1, 0); PG8_STAGE(PG8_SA(0, 1), a2 + hstep, voffA);
;             PG8_WAIT_L(8); PG8_BAR; PG8_WAIT_L(0); PG8_MMA(0, 0, At, B0); PG8_BAR; PG8_SCHED;
;             PG8_LDB(B1, 1, 1); PG8_STAGE(PG8_SB(1, 0), b3, voffB);
;             PG8_BAR; PG8_WAIT_L(0); PG8_MMA(0, 1, At, B1); PG8_BAR;
;             PG8_LDA(At, 1, 1); PG8_STAGE(PG8_SA(1, 0), a3, voffA);
;             PG8_BAR; PG8_WAIT_L(0); PG8_MMA(1, 0, At, B0); PG8_BAR; PG8_SCHED;
;             PG8_STAGE(PG8_SB(1, 1), b3 + hstep, voffB);
;             PG8_WAIT_V(6); PG8_BAR; PG8_MMA(1, 1, At, B1); PG8_BAR;
	s_waitcnt lgkmcnt(0)
	v_mfma_f32_16x16x32_bf16 v[36:39], v[158:161], v[174:177], v[36:39]
	v_mfma_f32_16x16x32_bf16 v[36:39], v[162:165], v[178:181], v[36:39]
	v_mfma_f32_16x16x32_bf16 v[40:43], v[154:157], v[178:181], v[40:43]
	v_mfma_f32_16x16x32_bf16 v[40:43], v[150:153], v[174:177], v[40:43]
	v_mfma_f32_16x16x32_bf16 v[24:27], v[150:153], v[182:185], v[24:27]
	v_mfma_f32_16x16x32_bf16 v[24:27], v[154:157], v[186:189], v[24:27]
	v_mfma_f32_16x16x32_bf16 v[20:23], v[162:165], v[186:189], v[20:23]
	v_mfma_f32_16x16x32_bf16 v[20:23], v[158:161], v[182:185], v[20:23]
	v_mfma_f32_16x16x32_bf16 v[4:7], v[158:161], v[190:193], v[4:7]
	v_mfma_f32_16x16x32_bf16 v[4:7], v[162:165], v[194:197], v[4:7]
	v_mfma_f32_16x16x32_bf16 v[8:11], v[154:157], v[194:197], v[8:11]
	v_mfma_f32_16x16x32_bf16 v[8:11], v[150:153], v[190:193], v[8:11]
	s_barrier
	s_add_u32 s82, s78, 0x40000
	s_addc_u32 s83, s79, 0
	s_add_i32 s69, s92, s65
	s_mov_b32 m0, s69
	s_nop 0
	global_load_lds_dwordx4 v134, s[82:83]
	s_add_i32 m0, s69, 0x2000
	s_nop 0
	global_load_lds_dwordx4 v138, s[82:83]
	s_waitcnt vmcnt(6)
	v_mfma_f32_16x16x32_bf16 v[60:63], v[198:201], v[166:169], v[60:63]
	v_mfma_f32_16x16x32_bf16 v[60:63], v[210:213], v[170:173], v[60:63]
	v_mfma_f32_16x16x32_bf16 v[48:51], v[218:221], v[170:173], v[48:51]
	v_mfma_f32_16x16x32_bf16 v[48:51], v[214:217], v[166:169], v[48:51]
	s_barrier
	v_mfma_f32_16x16x32_bf16 v[32:35], v[214:217], v[174:177], v[32:35]
	v_mfma_f32_16x16x32_bf16 v[32:35], v[218:221], v[178:181], v[32:35]
	v_mfma_f32_16x16x32_bf16 v[44:47], v[210:213], v[178:181], v[44:47]
	v_mfma_f32_16x16x32_bf16 v[44:47], v[198:201], v[174:177], v[44:47]
	v_mfma_f32_16x16x32_bf16 v[28:31], v[198:201], v[182:185], v[28:31]
	v_mfma_f32_16x16x32_bf16 v[28:31], v[210:213], v[186:189], v[28:31]
	v_mfma_f32_16x16x32_bf16 v[16:19], v[218:221], v[186:189], v[16:19]
	v_mfma_f32_16x16x32_bf16 v[16:19], v[214:217], v[182:185], v[16:19]
	v_mfma_f32_16x16x32_bf16 v[0:3], v[214:217], v[190:193], v[0:3]
	v_mfma_f32_16x16x32_bf16 v[0:3], v[218:221], v[194:197], v[0:3]
	v_mfma_f32_16x16x32_bf16 v[12:15], v[210:213], v[194:197], v[12:15]
	v_mfma_f32_16x16x32_bf16 v[12:15], v[198:201], v[190:193], v[12:15]
	s_barrier
	s_add_i32 s69, 0, 0x18000
	ds_read_b128 v[150:153], v252
	ds_read_b128 v[154:157], v252 offset:1024
	ds_read_b128 v[158:161], v252 offset:2048
	ds_read_b128 v[162:165], v252 offset:3072
	s_add_u32 s80, s80, 0x40000
	s_addc_u32 s81, s81, 0
	s_mov_b32 m0, s77
	ds_read_b128 v[166:169], v206 offset:32768
	ds_read_b128 v[170:173], v206 offset:33792
	ds_read_b128 v[174:177], v206 offset:34816
	ds_read_b128 v[178:181], v206 offset:35840
	ds_read_b128 v[182:185], v206 offset:36864
	ds_read_b128 v[186:189], v206 offset:37888
	ds_read_b128 v[190:193], v206 offset:38912
	ds_read_b128 v[194:197], v206 offset:39936
	global_load_lds_dwordx4 v132, s[80:81]
	s_mov_b32 m0, s85
	s_nop 0
	global_load_lds_dwordx4 v136, s[80:81]
	s_waitcnt lgkmcnt(8)
	s_waitcnt lgkmcnt(6)
	v_mfma_f32_16x16x32_bf16 v[120:123], v[150:153], v[166:169], v[120:123]
	v_mfma_f32_16x16x32_bf16 v[120:123], v[154:157], v[170:173], v[120:123]
	v_mfma_f32_16x16x32_bf16 v[116:119], v[162:165], v[170:173], v[116:119]
	v_mfma_f32_16x16x32_bf16 v[116:119], v[158:161], v[166:169], v[116:119]
	s_barrier
	s_waitcnt lgkmcnt(0)
	v_mfma_f32_16x16x32_bf16 v[100:103], v[158:161], v[174:177], v[100:103]
	v_mfma_f32_16x16x32_bf16 v[100:103], v[162:165], v[178:181], v[100:103]
	v_mfma_f32_16x16x32_bf16 v[104:107], v[154:157], v[178:181], v[104:107]
	v_mfma_f32_16x16x32_bf16 v[104:107], v[150:153], v[174:177], v[104:107]
	v_mfma_f32_16x16x32_bf16 v[88:91], v[150:153], v[182:185], v[88:91]
	v_mfma_f32_16x16x32_bf16 v[88:91], v[154:157], v[186:189], v[88:91]
	v_mfma_f32_16x16x32_bf16 v[84:87], v[162:165], v[186:189], v[84:87]
	v_mfma_f32_16x16x32_bf16 v[84:87], v[158:161], v[182:185], v[84:87]
	v_mfma_f32_16x16x32_bf16 v[68:71], v[158:161], v[190:193], v[68:71]
	v_mfma_f32_16x16x32_bf16 v[68:71], v[162:165], v[194:197], v[68:71]
	v_mfma_f32_16x16x32_bf16 v[72:75], v[154:157], v[194:197], v[72:75]
	v_mfma_f32_16x16x32_bf16 v[72:75], v[150:153], v[190:193], v[72:75]
	s_barrier
	s_add_i32 s71, 0, 0x1c000
	s_add_i32 s69, s69, s65
	s_mov_b32 m0, s69
	ds_read_b128 v[198:201], v253
	ds_read_b128 v[210:213], v253 offset:1024
	ds_read_b128 v[214:217], v253 offset:2048
	ds_read_b128 v[218:221], v253 offset:3072
	global_load_lds_dwordx4 v134, s[100:101]
	s_add_i32 m0, s69, 0x2000
	s_nop 0
	global_load_lds_dwordx4 v138, s[100:101]
	s_waitcnt lgkmcnt(0)
	v_mfma_f32_16x16x32_bf16 v[124:127], v[198:201], v[166:169], v[124:127]
	v_mfma_f32_16x16x32_bf16 v[124:127], v[210:213], v[170:173], v[124:127]
	v_mfma_f32_16x16x32_bf16 v[112:115], v[218:221], v[170:173], v[112:115]
	v_mfma_f32_16x16x32_bf16 v[112:115], v[214:217], v[166:169], v[112:115]
	s_barrier
; template <class Epi, class Ptrs>
; __device__ __forceinline__ void gemm_phase(LAS unsigned char* lds, const int K, const StaticOrder& S, const Ptrs& P, const Epi& E) {
;     ...
;             PG8_LDB(B0, 0, 0); PG8_SCHED; PG8_LDA(At, 0, 0); PG8_STAGE(PG8_SA(1, 1), a1 + hstep, voffA);
;             PG8_WAIT_L(8); PG8_BAR; PG8_WAIT_L(0); PG8_MMA(0, 0, At, B0); PG8_BAR; PG8_SCHED;
;             PG8_LDB(B1, 0, 1); PG8_STAGE(PG8_SB(0, 0), b2, voffB);
;             PG8_BAR; PG8_WAIT_L(0); PG8_MMA(0, 1, At, B1); PG8_BAR;
;             PG8_LDA(At, 0, 1); PG8_STAGE(PG8_SA(0, 0), a2, voffA);
;             PG8_BAR; PG8_WAIT_L(0); PG8_MMA(1, 0, At, B0); PG8_BAR; PG8_SCHED;
;             PG8_STAGE(PG8_SB(0, 1), b2 + hstep, voffB);
;             PG8_WAIT_V(6); PG8_BAR; PG8_MMA(1, 1, At, B1); PG8_BAR;
;             PG8_LDB(B0, 1, 0); PG8_SCHED; PG8_LDA(At, 1, 0); PG8_STAGE(PG8_SA(0, 1), a2 + hstep, voffA);
;             PG8_WAIT_L(8); PG8_BAR; PG8_WAIT_L(0); PG8_MMA(0, 0, At, B0); PG8_BAR; PG8_SCHED;
;             PG8_LDB(B1, 1, 1); PG8_STAGE(PG8_SB(1, 0), b3, voffB);
;             PG8_BAR; PG8_WAIT_L(0); PG8_MMA(0, 1, At, B1); PG8_BAR;
;             PG8_LDA(At, 1, 1); PG8_STAGE(PG8_SA(1, 0), a3, voffA);
;             PG8_BAR; PG8_WAIT_L(0); PG8_MMA(1, 0, At, B0); PG8_BAR; PG8_SCHED;
;             PG8_STAGE(PG8_SB(1, 1), b3 + hstep, voffB);
;             PG8_WAIT_V(6); PG8_BAR; PG8_MMA(1, 1, At, B1); PG8_BAR;
;     __device__ __forceinline__ void operator()(const f32x4 (&acc)[2][2][4][2], const Unit& u, int ui, int wr, int wc, int fr, int fq) const {
;     ...
;         if (pn < 8) {
;             bf16_t* base = (bf16_t*)(ws + WS_U) + (size_t)(u.pm * 256 + wr * 64 + fr) * DM + pn * 128 + wc * 32 + 8 * fq;
; #pragma unroll
;             for (int ai = 0; ai < 2; ++ai)
; #pragma unroll
;                 for (int m = 0; m < 4; ++m) {
;                     const f32x4 g0 = g1_4(acc[ai][0][m][0], acc[ai][1][m][0]), g1 = g1_4(acc[ai][0][m][1], acc[ai][1][m][1]);
;                     *(u32x4*)(base + (size_t)(ai * 128 + m * 16) * DM) = pack8(g0, g1); }
;             return; }
;         if (pn >= 17 && pn < 21) {
;             bf16_t* base = (bf16_t*)(dout + DO_GVT) + (size_t)((pn - 17) * 256 + wr * 64 + fr) * MTOK + u.pm * 256 + wc * 32 + 8 * fq;
;             float* pp = (float*)(ws + WS_PART) + (size_t)(u.pm * 256 + wc * 32 + 8 * fq) * 8 + (pn - 17) * 2 + wr;
; #pragma unroll
	s_waitcnt lgkmcnt(0)
	v_mfma_f32_16x16x32_bf16 v[96:99], v[214:217], v[174:177], v[96:99]
	v_mfma_f32_16x16x32_bf16 v[96:99], v[218:221], v[178:181], v[96:99]
	v_mfma_f32_16x16x32_bf16 v[108:111], v[210:213], v[178:181], v[108:111]
	v_mfma_f32_16x16x32_bf16 v[108:111], v[198:201], v[174:177], v[108:111]
	v_mfma_f32_16x16x32_bf16 v[92:95], v[198:201], v[182:185], v[92:95]
	v_mfma_f32_16x16x32_bf16 v[92:95], v[210:213], v[186:189], v[92:95]
	v_mfma_f32_16x16x32_bf16 v[80:83], v[218:221], v[186:189], v[80:83]
	v_mfma_f32_16x16x32_bf16 v[80:83], v[214:217], v[182:185], v[80:83]
	v_mfma_f32_16x16x32_bf16 v[64:67], v[214:217], v[190:193], v[64:67]
	v_mfma_f32_16x16x32_bf16 v[64:67], v[218:221], v[194:197], v[64:67]
	v_mfma_f32_16x16x32_bf16 v[76:79], v[210:213], v[194:197], v[76:79]
	v_mfma_f32_16x16x32_bf16 v[76:79], v[198:201], v[190:193], v[76:79]
	s_barrier
	s_mov_b32 m0, s89
	s_add_u32 s100, s80, 0xfffc0080
	s_addc_u32 s101, s81, -1
	ds_read_b128 v[166:169], v206 offset:49152
	ds_read_b128 v[170:173], v206 offset:50176
	ds_read_b128 v[174:177], v206 offset:51200
	ds_read_b128 v[178:181], v206 offset:52224
	ds_read_b128 v[182:185], v206 offset:53248
	ds_read_b128 v[186:189], v206 offset:54272
	ds_read_b128 v[190:193], v206 offset:55296
	ds_read_b128 v[194:197], v206 offset:56320
	global_load_lds_dwordx4 v132, s[100:101]
	s_mov_b32 m0, s90
	s_nop 0
	global_load_lds_dwordx4 v136, s[100:101]
	s_waitcnt lgkmcnt(6)
	v_mfma_f32_16x16x32_bf16 v[56:59], v[150:153], v[166:169], v[56:59]
	v_mfma_f32_16x16x32_bf16 v[56:59], v[154:157], v[170:173], v[56:59]
	v_mfma_f32_16x16x32_bf16 v[52:55], v[162:165], v[170:173], v[52:55]
	v_mfma_f32_16x16x32_bf16 v[52:55], v[158:161], v[166:169], v[52:55]
	s_barrier
	s_waitcnt lgkmcnt(0)
	v_mfma_f32_16x16x32_bf16 v[36:39], v[158:161], v[174:177], v[36:39]
	v_mfma_f32_16x16x32_bf16 v[36:39], v[162:165], v[178:181], v[36:39]
	v_mfma_f32_16x16x32_bf16 v[40:43], v[154:157], v[178:181], v[40:43]
	v_mfma_f32_16x16x32_bf16 v[40:43], v[150:153], v[174:177], v[40:43]
	v_mfma_f32_16x16x32_bf16 v[24:27], v[150:153], v[182:185], v[24:27]
	v_mfma_f32_16x16x32_bf16 v[24:27], v[154:157], v[186:189], v[24:27]
	v_mfma_f32_16x16x32_bf16 v[20:23], v[162:165], v[186:189], v[20:23]
	v_mfma_f32_16x16x32_bf16 v[20:23], v[158:161], v[182:185], v[20:23]
	v_mfma_f32_16x16x32_bf16 v[4:7], v[158:161], v[190:193], v[4:7]
	v_mfma_f32_16x16x32_bf16 v[4:7], v[162:165], v[194:197], v[4:7]
	v_mfma_f32_16x16x32_bf16 v[8:11], v[154:157], v[194:197], v[8:11]
	v_mfma_f32_16x16x32_bf16 v[8:11], v[150:153], v[190:193], v[8:11]
	s_barrier
	s_add_u32 s78, s78, 0x40080
	s_addc_u32 s79, s79, 0
	s_add_i32 s69, s71, s65
	s_mov_b32 m0, s69
	s_nop 0
	global_load_lds_dwordx4 v134, s[78:79]
	s_add_i32 m0, s69, 0x2000
	s_nop 0
	global_load_lds_dwordx4 v138, s[78:79]
	s_waitcnt vmcnt(6)
	v_mfma_f32_16x16x32_bf16 v[60:63], v[198:201], v[166:169], v[60:63]
	v_mfma_f32_16x16x32_bf16 v[60:63], v[210:213], v[170:173], v[60:63]
	v_mfma_f32_16x16x32_bf16 v[48:51], v[218:221], v[170:173], v[48:51]
	v_mfma_f32_16x16x32_bf16 v[48:51], v[214:217], v[166:169], v[48:51]
	s_barrier
	v_mfma_f32_16x16x32_bf16 v[32:35], v[214:217], v[174:177], v[32:35]
	v_mfma_f32_16x16x32_bf16 v[32:35], v[218:221], v[178:181], v[32:35]
	v_mfma_f32_16x16x32_bf16 v[44:47], v[210:213], v[178:181], v[44:47]
	v_mfma_f32_16x16x32_bf16 v[44:47], v[198:201], v[174:177], v[44:47]
	v_mfma_f32_16x16x32_bf16 v[28:31], v[198:201], v[182:185], v[28:31]
	v_mfma_f32_16x16x32_bf16 v[28:31], v[210:213], v[186:189], v[28:31]
	v_mfma_f32_16x16x32_bf16 v[16:19], v[218:221], v[186:189], v[16:19]
	v_mfma_f32_16x16x32_bf16 v[16:19], v[214:217], v[182:185], v[16:19]
	v_mfma_f32_16x16x32_bf16 v[0:3], v[214:217], v[190:193], v[0:3]
	v_mfma_f32_16x16x32_bf16 v[0:3], v[218:221], v[194:197], v[0:3]
	v_mfma_f32_16x16x32_bf16 v[12:15], v[210:213], v[194:197], v[12:15]
	v_mfma_f32_16x16x32_bf16 v[12:15], v[198:201], v[190:193], v[12:15]
	s_barrier
	s_add_i32 s63, s63, 2
	s_add_u32 s6, s6, 0x100
	s_addc_u32 s7, s7, 0
	s_add_u32 s20, s20, 0x100
	s_addc_u32 s25, s25, 0
	s_cmp_gt_u32 s63, 13
	s_cbranch_scc0 .LBB0_127
	s_cmp_gt_i32 s74, 7
	s_mov_b64 s[6:7], -1
	s_cbranch_scc0 .LBB0_188
	s_sub_i32 s25, s74, 17
	s_cmp_gt_u32 s25, 3
	s_cbranch_scc0 .LBB0_170
	s_lshl_b32 s69, s76, 8
	s_cmp_gt_u32 s74, 11
	s_cbranch_scc0 .LBB0_135
	s_cmp_eq_u32 s74, 12
	s_mov_b64 s[6:7], 0
	s_cbranch_scc1 .LBB0_134
	s_cmp_gt_u32 s74, 16
	s_cbranch_scc1 .LBB0_191
	s_lshl_b32 s20, s74, 8
	v_readlane_b32 s80, v254, 2
	s_addk_i32 s20, 0xf300
	s_mov_b64 s[78:79], 0x400
	s_mov_b64 s[82:83], -1
	s_mov_b32 s63, s69
	v_readlane_b32 s81, v254, 3
	s_andn2_b64 vcc, exec, s[6:7]
	s_cbranch_vccz .LBB0_136
	s_branch .LBB0_137

; __device__ __forceinline__ unsigned xb_ld(unsigned* p)              { return __hip_atomic_load(p, __ATOMIC_RELAXED, __HIP_MEMORY_SCOPE_AGENT); }
; __device__ __forceinline__ void xcd_barrier_complete(unsigned* bar, unsigned x, unsigned& nloc, unsigned& nx) {
;     const unsigned G = gridDim.x * gridDim.y * gridDim.z;
;     unsigned sum, cnt, mine, sp = 0u;
;     for (;;) {
;         sum = 0u; cnt = 0u; mine = 0u;
; #pragma unroll
;         for (unsigned j = 0; j < 16; ++j) { const unsigned c = xb_ld(&bar[XB_XCNT(j)]); sum += c; cnt += (c > 0u) ? 1u : 0u; mine = (j == x) ? c : mine; }
; __device__ __forceinline__ void xcd_barrier(const XcdBarrier& b) {
;     asm volatile("s_waitcnt vmcnt(0)" ::: "memory");
;     __syncthreads();
;     if (threadIdx.x == 0) {
;         unsigned* bar = b.bar;
;         __builtin_amdgcn_s_waitcnt(0);
;         unsigned nloc = b.st[0], nx = b.st[1];
;         if (nloc == 0u) { xcd_barrier_complete(bar, b.x, nloc, nx); b.st[0] = nloc; b.st[1] = nx; }
.LBB0_195:
	s_nop 0
	s_nop 0
	s_nop 0
	s_nop 0
	s_nop 0
	s_nop 0
	s_nop 0
	s_nop 0
	s_nop 0
	s_nop 0
	s_nop 0
	s_nop 0
	s_nop 0
	s_nop 0
	s_nop 0
	s_nop 0
	s_nop 0
	s_nop 0
	s_nop 0
	s_nop 0
	s_nop 0
	s_nop 0
	s_nop 0
	s_nop 0
	s_nop 0
	s_nop 0
	s_nop 0
	s_nop 0
	s_cmp_gt_i32 s31, 2
	s_cselect_b64 s[0:1], -1, 0
	s_and_b64 s[4:5], s[18:19], s[0:1]
	s_andn2_b64 vcc, exec, s[4:5]
	s_cbranch_vccnz .LBB0_245
	s_waitcnt vmcnt(0)
	s_waitcnt vmcnt(0) lgkmcnt(0)
	s_barrier
	s_and_saveexec_b64 s[4:5], s[8:9]
	s_cbranch_execz .LBB0_244
	s_add_i32 s6, 0, 0x25ff0
	v_mov_b32_e32 v0, s6
	s_waitcnt vmcnt(0) expcnt(0) lgkmcnt(0)
	ds_read_b32 v2, v0
	s_add_i32 s6, 0, 0x25ff4
	v_mov_b32_e32 v0, s6
	ds_read_b32 v0, v0
	s_waitcnt lgkmcnt(1)
	v_cmp_ne_u32_e32 vcc, 0, v2
	s_cbranch_vccnz .LBB0_212
	s_load_dwordx2 s[18:19], s[52:53], 0x4
	s_add_u32 s6, s28, 0x3e800200
	s_addc_u32 s7, s29, 0
	s_add_u32 s10, s28, 0x3e800400
	s_addc_u32 s11, s29, 0
	s_waitcnt lgkmcnt(0)
	s_mul_i32 s76, s18, s3
	s_add_u32 s18, s28, 0x3e800500
	s_mul_i32 s76, s76, s19
	s_addc_u32 s19, s29, 0
	s_add_u32 s20, s28, 0x3e800600
	s_addc_u32 s21, s29, 0
	s_add_u32 s22, s28, 0x3e800700
	s_addc_u32 s23, s29, 0
	s_add_u32 s24, s28, 0x3e800800
	s_addc_u32 s25, s29, 0
	s_add_u32 s42, s28, 0x3e800900
	s_addc_u32 s43, s29, 0
	s_add_u32 s44, s28, 0x3e800a00
	s_addc_u32 s45, s29, 0
	s_add_u32 s48, s28, 0x3e800b00
	s_addc_u32 s49, s29, 0
	s_add_u32 s54, s28, 0x3e800c00
	s_addc_u32 s55, s29, 0
	s_add_u32 s56, s28, 0x3e800d00
	s_addc_u32 s57, s29, 0
	s_add_u32 s58, s28, 0x3e800e00
	s_addc_u32 s59, s29, 0
	s_add_u32 s60, s28, 0x3e800f00
	s_addc_u32 s61, s29, 0
	s_add_u32 s62, s28, 0x3e801000
	s_addc_u32 s63, s29, 0
	s_add_u32 s64, s28, 0x3e801100
	s_addc_u32 s65, s29, 0
	s_add_u32 s66, s28, 0x3e801200
	s_addc_u32 s67, s29, 0
	s_add_u32 s68, s28, 0x3e801300
	s_addc_u32 s69, s29, 0
	s_mov_b32 s77, 1
	v_mov_b32_e32 v16, 0
	s_branch .LBB0_200

; #define PG8_STAGE(bufoff, gbase, voff) do { _Pragma("unroll") for (int _i = 0; _i < 2; ++_i) \
;         __builtin_amdgcn_global_load_lds((const unsigned*)((const char*)(gbase) + (voff)[_i]), (LAS unsigned*)(lds + (bufoff) + ldsw + _i * 8192), 16, 0, 0); } while (0)
; #define PG8_WAIT_V(n) asm volatile("s_waitcnt vmcnt(" #n ")" ::: "memory")
; #define PG8_BAR __builtin_amdgcn_s_barrier()
; template <class Epi, class Ptrs>
; __device__ __forceinline__ void gemm_phase(LAS unsigned char* lds, const int K, const StaticOrder& S, const Ptrs& P, const Epi& E) {
;     ...
;     for (int i = 0; i < 2; ++i) { int R, C; stage_rc(tid * 16 + i * 8192, R, C); const int Rb = (R & ~31) + perm32(R & 31);
;         voffA[i] = (unsigned)(R * K + C) * 2u; voffB[i] = (unsigned)(Rb * K + C) * 2u; }
;     const size_t kstep = (size_t)(BK * 2);
;     const size_t hstep = (size_t)HALF * K * 2;
;     const unsigned ldsw = (unsigned)wid * 1024u;
;     const int aoff = lds_byte(wr * 64 + fr, fq * 8), boff = lds_byte(wc * 32 + fr, fq * 8);
;     ...
;     Unit cur, nxt; int ui = 0;
;     if (!S.next(0, cur)) return;
;     f32x4 acc[2][2][4][2];
; #pragma unroll
;     for (int a = 0; a < 2; ++a)
; #pragma unroll
;         for (int b = 0; b < 2; ++b)
; #pragma unroll
;             for (int m = 0; m < 4; ++m)
; #pragma unroll
;                 for (int n = 0; n < 2; ++n) acc[a][b][m][n] = (f32x4){0.f, 0.f, 0.f, 0.f};
;     bf16x8 At[4][2], B0[2][2], B1[2][2];
;     const char* cA; const char* cB; P.get(cur, cA, cB);
;     PG8_STAGE(PG8_SB(0, 0), cB, voffB); PG8_STAGE(PG8_SA(0, 0), cA, voffA); PG8_STAGE(PG8_SB(0, 1), cB + hstep, voffB); PG8_STAGE(PG8_SA(0, 1), cA + hstep, voffA);
;     if (wr == 1) PG8_BAR;
;     PG8_WAIT_V(4); PG8_BAR;
;     PG8_STAGE(PG8_SB(1, 0), cB + kstep, voffB); PG8_STAGE(PG8_SA(1, 0), cA + kstep, voffA); PG8_STAGE(PG8_SB(1, 1), cB + hstep + kstep, voffB);
;     PG8_WAIT_V(6); PG8_BAR;
.LBB0_346:
	s_add_u32 s14, s28, 0x2000000
	s_addc_u32 s15, s29, 0
	s_add_u32 s16, s28, 0x3e000000
	s_addc_u32 s17, s29, 0
	s_ashr_i32 s58, s3, 31
	s_ashr_i32 s59, s2, 31
	s_add_u32 s60, s38, 0xf8000000
	s_mov_b64 s[18:19], 0x80
	s_addc_u32 s61, s39, -1
	s_and_b32 s62, s1, 3
	s_add_i32 m0, s54, 0x18000
	v_lshl_add_u64 v[6:7], v[6:7], 0, s[18:19]
	s_lshl_b32 s1, s0, 13
	s_lshl_b32 s20, s62, 12
	s_waitcnt vmcnt(4)
	s_barrier
	global_load_lds_dwordx4 v[6:7], off
	v_lshl_add_u64 v[4:5], v[4:5], 0, s[18:19]
	s_add_i32 m0, s54, 0x1a000
	s_add_i32 s63, s54, 0x8000
	s_add_i32 s64, s54, 0xa000
	global_load_lds_dwordx4 v[4:5], off
	v_lshl_add_u64 v[2:3], v[2:3], 0, s[18:19]
	s_mov_b32 m0, s63
	s_add_u32 s4, s42, 0x40080
	global_load_lds_dwordx4 v[2:3], off
	v_lshl_add_u64 v[0:1], v[0:1], 0, s[18:19]
	s_mov_b32 m0, s64
	s_addc_u32 s5, s43, 0
	global_load_lds_dwordx4 v[0:1], off
	s_add_i32 m0, s54, 0x1c000
	v_lshl_add_u64 v[0:1], s[4:5], 0, v[178:179]
	global_load_lds_dwordx4 v[0:1], off
	v_lshl_add_u64 v[0:1], s[4:5], 0, v[182:183]
	s_add_i32 m0, s54, 0x1e000
	v_lshlrev_b32_e32 v4, 6, v208
	global_load_lds_dwordx4 v[0:1], off
	v_bfe_u32 v1, v208, 4, 2
	v_lshlrev_b32_e32 v2, 3, v1
	v_lshlrev_b32_e32 v3, 4, v1
	v_cmp_eq_u32_e64 s[6:7], 0, v1
	v_lshlrev_b32_e32 v1, 8, v208
	v_lshl_or_b32 v206, s62, 5, v2
	v_and_b32_e32 v1, 0x38000, v1
	v_lshlrev_b32_e32 v2, 11, v10
	v_or3_b32 v1, v8, v1, v2
	v_and_b32_e32 v0, 15, v208
	s_movk_i32 s4, 0x3c0
	v_lshlrev_b32_e32 v5, 2, v208
	v_add_u32_e32 v184, v1, v9
	v_lshlrev_b32_e32 v1, 4, v11
	v_and_or_b32 v4, v4, s4, v3
	v_and_b32_e32 v5, 32, v5
	v_lshl_or_b32 v204, s0, 6, v0
	v_lshl_or_b32 v0, v0, 6, v3
	s_waitcnt vmcnt(6)
	v_and_b32_e32 v1, 0x78000, v1
	v_bitop3_b32 v0, v0, s1, v5 bitop3:0xde
	v_bitop3_b32 v205, s20, v4, v5 bitop3:0xf6
	v_or3_b32 v1, v8, v1, v2
	s_add_i32 s66, 0, 0x10000
	s_add_i32 s67, 0, 0x14000
	v_mov_b32_e32 v185, v179
	v_add_u32_e32 v186, v1, v9
	v_mov_b32_e32 v187, v179
	v_mov_b64_e32 v[188:189], 0x600
	v_mov_b64_e32 v[190:191], 0x5ff
	s_movk_i32 s65, 0xc1
	v_add_u32_e32 v207, s66, v205
	v_add_u32_e32 v209, 0, v0
	v_add_u32_e32 v210, s67, v205
	s_nop 0
	s_nop 0
	s_nop 0
	s_nop 0
	s_nop 0
	s_nop 0
	s_nop 0
	s_nop 0
	s_nop 0
	s_nop 0
	s_nop 0
	s_nop 0
	s_nop 0
	s_nop 0
	s_nop 0
	s_nop 0
	s_nop 0
	s_nop 0
	s_nop 0
	s_nop 0
	s_nop 0
	s_nop 0
	s_nop 0
	s_nop 0
	s_nop 0
	s_nop 0
	s_nop 0
	s_nop 0
	s_nop 0
	s_nop 0
	s_nop 0
	s_nop 0
	s_nop 0
	s_nop 0
	s_nop 0
	s_nop 0
	s_nop 0
	s_nop 0
	s_nop 0
	s_nop 0
	s_nop 0
	s_nop 0
	s_nop 0
	s_nop 0
	s_nop 0
	s_nop 0
	s_nop 0
	s_nop 0
	s_nop 0
	s_mov_b32 s68, 0
	s_cmpk_lt_u32 s46, 0x100
	s_cbranch_scc1 .Lsprio_1
	s_setprio 1

; #define PG8_STAGE(bufoff, gbase, voff) do { _Pragma("unroll") for (int _i = 0; _i < 2; ++_i) \
;         __builtin_amdgcn_global_load_lds((const unsigned*)((const char*)(gbase) + (voff)[_i]), (LAS unsigned*)(lds + (bufoff) + ldsw + _i * 8192), 16, 0, 0); } while (0)
; #define PG8_LDA(dst, b, h) do { _Pragma("unroll") for (int m = 0; m < 4; ++m) _Pragma("unroll") for (int k = 0; k < 2; ++k) dst[m][k] = *(const LAS bf16x8*)(lds + PG8_SA(b, h) + aoff + m * 2048 + k * 1024); } while (0)
; #define PG8_WAIT_V(n) asm volatile("s_waitcnt vmcnt(" #n ")" ::: "memory")
; #define PG8_BAR __builtin_amdgcn_s_barrier()
; template <class Epi, class Ptrs>
; __device__ __forceinline__ void gemm_phase(LAS unsigned char* lds, const int K, const StaticOrder& S, const Ptrs& P, const Epi& E) {
;     ...
;         for (int t = 0; t < nt; t += 2) {
;             const bool last = (t == nt - 2);
;             const char* a1 = cA + (size_t)(t + 1) * kstep;
;             const char* a2 = last ? nA : cA + (size_t)(t + 2) * kstep; const char* b2 = last ? nB : cB + (size_t)(t + 2) * kstep;
;             const char* a3 = a2 + kstep; const char* b3 = b2 + kstep;
;             PG8_LDB(B0, 0, 0); PG8_SCHED; PG8_LDA(At, 0, 0); PG8_STAGE(PG8_SA(1, 1), a1 + hstep, voffA);
;             PG8_WAIT_L(8); PG8_BAR; PG8_WAIT_L(0); PG8_MMA(0, 0, At, B0); PG8_BAR; PG8_SCHED;
;             PG8_LDB(B1, 0, 1); PG8_STAGE(PG8_SB(0, 0), b2, voffB);
;             PG8_BAR; PG8_WAIT_L(0); PG8_MMA(0, 1, At, B1); PG8_BAR;
;             PG8_LDA(At, 0, 1); PG8_STAGE(PG8_SA(0, 0), a2, voffA);
;             PG8_BAR; PG8_WAIT_L(0); PG8_MMA(1, 0, At, B0); PG8_BAR; PG8_SCHED;
;             PG8_STAGE(PG8_SB(0, 1), b2 + hstep, voffB);
;             PG8_WAIT_V(6); PG8_BAR; PG8_MMA(1, 1, At, B1); PG8_BAR;
;             PG8_LDB(B0, 1, 0); PG8_SCHED; PG8_LDA(At, 1, 0); PG8_STAGE(PG8_SA(0, 1), a2 + hstep, voffA);
;             PG8_WAIT_L(8); PG8_BAR; PG8_WAIT_L(0); PG8_MMA(0, 0, At, B0); PG8_BAR; PG8_SCHED;
;             PG8_LDB(B1, 1, 1); PG8_STAGE(PG8_SB(1, 0), b3, voffB);
;             PG8_BAR; PG8_WAIT_L(0); PG8_MMA(0, 1, At, B1); PG8_BAR;
;             PG8_LDA(At, 1, 1); PG8_STAGE(PG8_SA(1, 0), a3, voffA);
;             PG8_BAR; PG8_WAIT_L(0); PG8_MMA(1, 0, At, B0); PG8_BAR; PG8_SCHED;
;             PG8_STAGE(PG8_SB(1, 1), b3 + hstep, voffB);
;             PG8_WAIT_V(6); PG8_BAR; PG8_MMA(1, 1, At, B1); PG8_BAR;
.LBB0_352:
	s_add_u32 s38, s44, 0x40080
	s_addc_u32 s39, s45, 0
	s_add_u32 s21, s42, 0x100
	s_addc_u32 s23, s43, 0
	s_mov_b32 s41, -2
	v_add_u32_e32 v252, 0x18000, v205
	v_add_u32_e32 v253, 0x1c000, v205
	ds_read_b128 v[128:131], v207
	ds_read_b128 v[132:135], v207 offset:1024
	ds_read_b128 v[136:139], v207 offset:2048
	ds_read_b128 v[140:143], v207 offset:3072
	s_add_u32 s42, s38, 0xfffc0080
	s_addc_u32 s43, s39, -1
	s_cmp_eq_u32 s41, 12
	s_cselect_b32 s45, s1, s43
	s_cselect_b32 s44, s0, s42
	s_cselect_b32 s43, s25, s23
	s_cselect_b32 s42, s24, s21
	s_add_i32 m0, s54, 0xc000
	ds_read_b128 v[144:147], v209
	ds_read_b128 v[148:151], v209 offset:1024
	ds_read_b128 v[152:155], v209 offset:2048
	ds_read_b128 v[156:159], v209 offset:3072
	ds_read_b128 v[160:163], v209 offset:4096
	ds_read_b128 v[164:167], v209 offset:5120
	ds_read_b128 v[168:171], v209 offset:6144
	ds_read_b128 v[172:175], v209 offset:7168
	global_load_lds_dwordx4 v184, s[38:39]
	s_add_i32 m0, s54, 0xe000
	s_nop 0
	global_load_lds_dwordx4 v186, s[38:39]
	s_waitcnt lgkmcnt(8)
	s_waitcnt lgkmcnt(6)
	v_mfma_f32_16x16x32_bf16 v[124:127], v[128:131], v[144:147], 0
	v_mfma_f32_16x16x32_bf16 v[124:127], v[132:135], v[148:151], v[124:127]
	v_mfma_f32_16x16x32_bf16 v[120:123], v[140:143], v[148:151], 0
	v_mfma_f32_16x16x32_bf16 v[120:123], v[136:139], v[144:147], v[120:123]
	s_barrier
	s_waitcnt lgkmcnt(0)
	v_mfma_f32_16x16x32_bf16 v[104:107], v[136:139], v[152:155], 0
	v_mfma_f32_16x16x32_bf16 v[104:107], v[140:143], v[156:159], v[104:107]
	v_mfma_f32_16x16x32_bf16 v[108:111], v[132:135], v[156:159], 0
	v_mfma_f32_16x16x32_bf16 v[108:111], v[128:131], v[152:155], v[108:111]
	v_mfma_f32_16x16x32_bf16 v[92:95], v[128:131], v[160:163], 0
	v_mfma_f32_16x16x32_bf16 v[92:95], v[132:135], v[164:167], v[92:95]
	v_mfma_f32_16x16x32_bf16 v[88:91], v[140:143], v[164:167], 0
	v_mfma_f32_16x16x32_bf16 v[88:91], v[136:139], v[160:163], v[88:91]
	v_mfma_f32_16x16x32_bf16 v[72:75], v[136:139], v[168:171], 0
	v_mfma_f32_16x16x32_bf16 v[72:75], v[140:143], v[172:175], v[72:75]
	v_mfma_f32_16x16x32_bf16 v[76:79], v[132:135], v[172:175], 0
	v_mfma_f32_16x16x32_bf16 v[76:79], v[128:131], v[168:171], v[76:79]
	s_barrier
	s_add_i32 s69, s66, s51
	s_add_u32 s90, s42, 0x80
	s_addc_u32 s91, s43, 0
	s_mov_b32 m0, s69
	ds_read_b128 v[192:195], v210
	ds_read_b128 v[196:199], v210 offset:1024
	ds_read_b128 v[200:203], v210 offset:2048
	ds_read_b128 v[212:215], v210 offset:3072
	global_load_lds_dwordx4 v178, s[42:43]
	s_add_i32 m0, s69, 0x2000
	s_nop 0
	global_load_lds_dwordx4 v182, s[42:43]
	s_waitcnt lgkmcnt(0)
	v_mfma_f32_16x16x32_bf16 v[116:119], v[192:195], v[144:147], 0
	v_mfma_f32_16x16x32_bf16 v[116:119], v[196:199], v[148:151], v[116:119]
	v_mfma_f32_16x16x32_bf16 v[112:115], v[212:215], v[148:151], 0
	v_mfma_f32_16x16x32_bf16 v[112:115], v[200:203], v[144:147], v[112:115]
	s_barrier
	s_waitcnt lgkmcnt(0)
	v_mfma_f32_16x16x32_bf16 v[96:99], v[200:203], v[152:155], 0
	v_mfma_f32_16x16x32_bf16 v[96:99], v[212:215], v[156:159], v[96:99]
	v_mfma_f32_16x16x32_bf16 v[100:103], v[196:199], v[156:159], 0
	v_mfma_f32_16x16x32_bf16 v[100:103], v[192:195], v[152:155], v[100:103]
	v_mfma_f32_16x16x32_bf16 v[84:87], v[192:195], v[160:163], 0
	v_mfma_f32_16x16x32_bf16 v[84:87], v[196:199], v[164:167], v[84:87]
	v_mfma_f32_16x16x32_bf16 v[80:83], v[212:215], v[164:167], 0
	v_mfma_f32_16x16x32_bf16 v[80:83], v[200:203], v[160:163], v[80:83]
	v_mfma_f32_16x16x32_bf16 v[64:67], v[200:203], v[168:171], 0
	v_mfma_f32_16x16x32_bf16 v[64:67], v[212:215], v[172:175], v[64:67]
	v_mfma_f32_16x16x32_bf16 v[68:71], v[196:199], v[172:175], 0
	v_mfma_f32_16x16x32_bf16 v[68:71], v[192:195], v[168:171], v[68:71]
	s_barrier
	s_mov_b32 m0, s54
	s_add_u32 s92, s44, 0x80
	s_addc_u32 s93, s45, 0
	ds_read_b128 v[144:147], v209 offset:16384
	ds_read_b128 v[148:151], v209 offset:17408
	ds_read_b128 v[152:155], v209 offset:18432
	ds_read_b128 v[156:159], v209 offset:19456
	ds_read_b128 v[160:163], v209 offset:20480
	ds_read_b128 v[164:167], v209 offset:21504
	ds_read_b128 v[168:171], v209 offset:22528
	ds_read_b128 v[172:175], v209 offset:23552
	global_load_lds_dwordx4 v176, s[44:45]
	s_mov_b32 m0, s55
	s_nop 0
	global_load_lds_dwordx4 v180, s[44:45]
	s_waitcnt lgkmcnt(6)
	v_mfma_f32_16x16x32_bf16 v[60:63], v[128:131], v[144:147], 0
	v_mfma_f32_16x16x32_bf16 v[60:63], v[132:135], v[148:151], v[60:63]
	v_mfma_f32_16x16x32_bf16 v[56:59], v[140:143], v[148:151], 0
	v_mfma_f32_16x16x32_bf16 v[56:59], v[136:139], v[144:147], v[56:59]
	s_barrier
	s_waitcnt lgkmcnt(0)
	v_mfma_f32_16x16x32_bf16 v[40:43], v[136:139], v[152:155], 0
	v_mfma_f32_16x16x32_bf16 v[40:43], v[140:143], v[156:159], v[40:43]
	v_mfma_f32_16x16x32_bf16 v[44:47], v[132:135], v[156:159], 0
	v_mfma_f32_16x16x32_bf16 v[44:47], v[128:131], v[152:155], v[44:47]
	v_mfma_f32_16x16x32_bf16 v[28:31], v[128:131], v[160:163], 0
	v_mfma_f32_16x16x32_bf16 v[28:31], v[132:135], v[164:167], v[28:31]
	v_mfma_f32_16x16x32_bf16 v[24:27], v[140:143], v[164:167], 0
	v_mfma_f32_16x16x32_bf16 v[24:27], v[136:139], v[160:163], v[24:27]
	v_mfma_f32_16x16x32_bf16 v[8:11], v[136:139], v[168:171], 0
	v_mfma_f32_16x16x32_bf16 v[8:11], v[140:143], v[172:175], v[8:11]
	v_mfma_f32_16x16x32_bf16 v[12:15], v[132:135], v[172:175], 0
	v_mfma_f32_16x16x32_bf16 v[12:15], v[128:131], v[168:171], v[12:15]
	s_barrier
	s_add_u32 s70, s42, 0x40000
	s_addc_u32 s71, s43, 0
	s_add_i32 s69, s67, s51
	s_mov_b32 m0, s69
	s_nop 0
	global_load_lds_dwordx4 v178, s[70:71]
	s_add_i32 m0, s69, 0x2000
	s_nop 0
	global_load_lds_dwordx4 v182, s[70:71]
	s_waitcnt vmcnt(6)
	v_mfma_f32_16x16x32_bf16 v[52:55], v[192:195], v[144:147], 0
	v_mfma_f32_16x16x32_bf16 v[52:55], v[196:199], v[148:151], v[52:55]
	v_mfma_f32_16x16x32_bf16 v[48:51], v[212:215], v[148:151], 0
	v_mfma_f32_16x16x32_bf16 v[48:51], v[200:203], v[144:147], v[48:51]
	s_barrier
; #define PG8_STAGE(bufoff, gbase, voff) do { _Pragma("unroll") for (int _i = 0; _i < 2; ++_i) \
;         __builtin_amdgcn_global_load_lds((const unsigned*)((const char*)(gbase) + (voff)[_i]), (LAS unsigned*)(lds + (bufoff) + ldsw + _i * 8192), 16, 0, 0); } while (0)
; #define PG8_LDA(dst, b, h) do { _Pragma("unroll") for (int m = 0; m < 4; ++m) _Pragma("unroll") for (int k = 0; k < 2; ++k) dst[m][k] = *(const LAS bf16x8*)(lds + PG8_SA(b, h) + aoff + m * 2048 + k * 1024); } while (0)
; #define PG8_WAIT_V(n) asm volatile("s_waitcnt vmcnt(" #n ")" ::: "memory")
; #define PG8_BAR __builtin_amdgcn_s_barrier()
; template <class Epi, class Ptrs>
; __device__ __forceinline__ void gemm_phase(LAS unsigned char* lds, const int K, const StaticOrder& S, const Ptrs& P, const Epi& E) {
;     ...
;         for (int t = 0; t < nt; t += 2) {
;             const bool last = (t == nt - 2);
;             const char* a1 = cA + (size_t)(t + 1) * kstep;
;             const char* a2 = last ? nA : cA + (size_t)(t + 2) * kstep; const char* b2 = last ? nB : cB + (size_t)(t + 2) * kstep;
;             const char* a3 = a2 + kstep; const char* b3 = b2 + kstep;
;             PG8_LDB(B0, 0, 0); PG8_SCHED; PG8_LDA(At, 0, 0); PG8_STAGE(PG8_SA(1, 1), a1 + hstep, voffA);
;             PG8_WAIT_L(8); PG8_BAR; PG8_WAIT_L(0); PG8_MMA(0, 0, At, B0); PG8_BAR; PG8_SCHED;
;             PG8_LDB(B1, 0, 1); PG8_STAGE(PG8_SB(0, 0), b2, voffB);
;             PG8_BAR; PG8_WAIT_L(0); PG8_MMA(0, 1, At, B1); PG8_BAR;
;             PG8_LDA(At, 0, 1); PG8_STAGE(PG8_SA(0, 0), a2, voffA);
;             PG8_BAR; PG8_WAIT_L(0); PG8_MMA(1, 0, At, B0); PG8_BAR; PG8_SCHED;
;             PG8_STAGE(PG8_SB(0, 1), b2 + hstep, voffB);
;             PG8_WAIT_V(6); PG8_BAR; PG8_MMA(1, 1, At, B1); PG8_BAR;
;             PG8_LDB(B0, 1, 0); PG8_SCHED; PG8_LDA(At, 1, 0); PG8_STAGE(PG8_SA(0, 1), a2 + hstep, voffA);
;             PG8_WAIT_L(8); PG8_BAR; PG8_WAIT_L(0); PG8_MMA(0, 0, At, B0); PG8_BAR; PG8_SCHED;
;             PG8_LDB(B1, 1, 1); PG8_STAGE(PG8_SB(1, 0), b3, voffB);
;             PG8_BAR; PG8_WAIT_L(0); PG8_MMA(0, 1, At, B1); PG8_BAR;
;             PG8_LDA(At, 1, 1); PG8_STAGE(PG8_SA(1, 0), a3, voffA);
;             PG8_BAR; PG8_WAIT_L(0); PG8_MMA(1, 0, At, B0); PG8_BAR; PG8_SCHED;
;             PG8_STAGE(PG8_SB(1, 1), b3 + hstep, voffB);
;             PG8_WAIT_V(6); PG8_BAR; PG8_MMA(1, 1, At, B1); PG8_BAR;
	v_mfma_f32_16x16x32_bf16 v[32:35], v[200:203], v[152:155], 0
	v_mfma_f32_16x16x32_bf16 v[32:35], v[212:215], v[156:159], v[32:35]
	v_mfma_f32_16x16x32_bf16 v[36:39], v[196:199], v[156:159], 0
	v_mfma_f32_16x16x32_bf16 v[36:39], v[192:195], v[152:155], v[36:39]
	v_mfma_f32_16x16x32_bf16 v[20:23], v[192:195], v[160:163], 0
	v_mfma_f32_16x16x32_bf16 v[20:23], v[196:199], v[164:167], v[20:23]
	v_mfma_f32_16x16x32_bf16 v[16:19], v[212:215], v[164:167], 0
	v_mfma_f32_16x16x32_bf16 v[16:19], v[200:203], v[160:163], v[16:19]
	v_mfma_f32_16x16x32_bf16 v[0:3], v[200:203], v[168:171], 0
	v_mfma_f32_16x16x32_bf16 v[0:3], v[212:215], v[172:175], v[0:3]
	v_mfma_f32_16x16x32_bf16 v[4:7], v[196:199], v[172:175], 0
	v_mfma_f32_16x16x32_bf16 v[4:7], v[192:195], v[168:171], v[4:7]
	s_barrier
	s_add_i32 s69, 0, 0x18000
	ds_read_b128 v[128:131], v252
	ds_read_b128 v[132:135], v252 offset:1024
	ds_read_b128 v[136:139], v252 offset:2048
	ds_read_b128 v[140:143], v252 offset:3072
	s_add_u32 s44, s44, 0x40000
	s_addc_u32 s45, s45, 0
	s_mov_b32 m0, s56
	ds_read_b128 v[144:147], v209 offset:32768
	ds_read_b128 v[148:151], v209 offset:33792
	ds_read_b128 v[152:155], v209 offset:34816
	ds_read_b128 v[156:159], v209 offset:35840
	ds_read_b128 v[160:163], v209 offset:36864
	ds_read_b128 v[164:167], v209 offset:37888
	ds_read_b128 v[168:171], v209 offset:38912
	ds_read_b128 v[172:175], v209 offset:39936
	global_load_lds_dwordx4 v176, s[44:45]
	s_mov_b32 m0, s57
	s_nop 0
	global_load_lds_dwordx4 v180, s[44:45]
	s_waitcnt lgkmcnt(8)
	s_waitcnt lgkmcnt(6)
	v_mfma_f32_16x16x32_bf16 v[124:127], v[128:131], v[144:147], v[124:127]
	v_mfma_f32_16x16x32_bf16 v[124:127], v[132:135], v[148:151], v[124:127]
	v_mfma_f32_16x16x32_bf16 v[120:123], v[140:143], v[148:151], v[120:123]
	v_mfma_f32_16x16x32_bf16 v[120:123], v[136:139], v[144:147], v[120:123]
	s_barrier
	s_waitcnt lgkmcnt(0)
	v_mfma_f32_16x16x32_bf16 v[104:107], v[136:139], v[152:155], v[104:107]
	v_mfma_f32_16x16x32_bf16 v[104:107], v[140:143], v[156:159], v[104:107]
	v_mfma_f32_16x16x32_bf16 v[108:111], v[132:135], v[156:159], v[108:111]
	v_mfma_f32_16x16x32_bf16 v[108:111], v[128:131], v[152:155], v[108:111]
	v_mfma_f32_16x16x32_bf16 v[92:95], v[128:131], v[160:163], v[92:95]
	v_mfma_f32_16x16x32_bf16 v[92:95], v[132:135], v[164:167], v[92:95]
	v_mfma_f32_16x16x32_bf16 v[88:91], v[140:143], v[164:167], v[88:91]
	v_mfma_f32_16x16x32_bf16 v[88:91], v[136:139], v[160:163], v[88:91]
	v_mfma_f32_16x16x32_bf16 v[72:75], v[136:139], v[168:171], v[72:75]
	v_mfma_f32_16x16x32_bf16 v[72:75], v[140:143], v[172:175], v[72:75]
	v_mfma_f32_16x16x32_bf16 v[76:79], v[132:135], v[172:175], v[76:79]
	v_mfma_f32_16x16x32_bf16 v[76:79], v[128:131], v[168:171], v[76:79]
	s_barrier
	s_add_i32 s44, 0, 0x1c000
	s_add_i32 s45, s69, s51
	s_mov_b32 m0, s45
	ds_read_b128 v[192:195], v253
	ds_read_b128 v[196:199], v253 offset:1024
	ds_read_b128 v[200:203], v253 offset:2048
	ds_read_b128 v[212:215], v253 offset:3072
	global_load_lds_dwordx4 v178, s[90:91]
	s_add_i32 m0, s45, 0x2000
	s_nop 0
	global_load_lds_dwordx4 v182, s[90:91]
	s_waitcnt lgkmcnt(0)
	v_mfma_f32_16x16x32_bf16 v[116:119], v[192:195], v[144:147], v[116:119]
	v_mfma_f32_16x16x32_bf16 v[116:119], v[196:199], v[148:151], v[116:119]
	v_mfma_f32_16x16x32_bf16 v[112:115], v[212:215], v[148:151], v[112:115]
	v_mfma_f32_16x16x32_bf16 v[112:115], v[200:203], v[144:147], v[112:115]
	s_barrier
	s_waitcnt lgkmcnt(0)
	v_mfma_f32_16x16x32_bf16 v[96:99], v[200:203], v[152:155], v[96:99]
	v_mfma_f32_16x16x32_bf16 v[96:99], v[212:215], v[156:159], v[96:99]
	v_mfma_f32_16x16x32_bf16 v[100:103], v[196:199], v[156:159], v[100:103]
	v_mfma_f32_16x16x32_bf16 v[100:103], v[192:195], v[152:155], v[100:103]
	v_mfma_f32_16x16x32_bf16 v[84:87], v[192:195], v[160:163], v[84:87]
	v_mfma_f32_16x16x32_bf16 v[84:87], v[196:199], v[164:167], v[84:87]
	v_mfma_f32_16x16x32_bf16 v[80:83], v[212:215], v[164:167], v[80:83]
	v_mfma_f32_16x16x32_bf16 v[80:83], v[200:203], v[160:163], v[80:83]
	v_mfma_f32_16x16x32_bf16 v[64:67], v[200:203], v[168:171], v[64:67]
	v_mfma_f32_16x16x32_bf16 v[64:67], v[212:215], v[172:175], v[64:67]
	v_mfma_f32_16x16x32_bf16 v[68:71], v[196:199], v[172:175], v[68:71]
	v_mfma_f32_16x16x32_bf16 v[68:71], v[192:195], v[168:171], v[68:71]
	s_barrier
	s_mov_b32 m0, s63
	ds_read_b128 v[144:147], v209 offset:49152
	ds_read_b128 v[148:151], v209 offset:50176
	ds_read_b128 v[152:155], v209 offset:51200
	ds_read_b128 v[156:159], v209 offset:52224
	ds_read_b128 v[160:163], v209 offset:53248
	ds_read_b128 v[164:167], v209 offset:54272
	ds_read_b128 v[168:171], v209 offset:55296
	ds_read_b128 v[172:175], v209 offset:56320
	global_load_lds_dwordx4 v176, s[92:93]
	s_mov_b32 m0, s64
	s_nop 0
	global_load_lds_dwordx4 v180, s[92:93]
	s_waitcnt lgkmcnt(6)
	v_mfma_f32_16x16x32_bf16 v[60:63], v[128:131], v[144:147], v[60:63]
	v_mfma_f32_16x16x32_bf16 v[60:63], v[132:135], v[148:151], v[60:63]
	v_mfma_f32_16x16x32_bf16 v[56:59], v[140:143], v[148:151], v[56:59]
	v_mfma_f32_16x16x32_bf16 v[56:59], v[136:139], v[144:147], v[56:59]
	s_barrier
	s_waitcnt lgkmcnt(0)
	v_mfma_f32_16x16x32_bf16 v[40:43], v[136:139], v[152:155], v[40:43]
	v_mfma_f32_16x16x32_bf16 v[40:43], v[140:143], v[156:159], v[40:43]
	v_mfma_f32_16x16x32_bf16 v[44:47], v[132:135], v[156:159], v[44:47]
	v_mfma_f32_16x16x32_bf16 v[44:47], v[128:131], v[152:155], v[44:47]
	v_mfma_f32_16x16x32_bf16 v[28:31], v[128:131], v[160:163], v[28:31]
	v_mfma_f32_16x16x32_bf16 v[28:31], v[132:135], v[164:167], v[28:31]
	v_mfma_f32_16x16x32_bf16 v[24:27], v[140:143], v[164:167], v[24:27]
	v_mfma_f32_16x16x32_bf16 v[24:27], v[136:139], v[160:163], v[24:27]
	v_mfma_f32_16x16x32_bf16 v[8:11], v[136:139], v[168:171], v[8:11]
	v_mfma_f32_16x16x32_bf16 v[8:11], v[140:143], v[172:175], v[8:11]
	v_mfma_f32_16x16x32_bf16 v[12:15], v[132:135], v[172:175], v[12:15]
	v_mfma_f32_16x16x32_bf16 v[12:15], v[128:131], v[168:171], v[12:15]
	s_barrier
; #define PG8_STAGE(bufoff, gbase, voff) do { _Pragma("unroll") for (int _i = 0; _i < 2; ++_i) \
;         __builtin_amdgcn_global_load_lds((const unsigned*)((const char*)(gbase) + (voff)[_i]), (LAS unsigned*)(lds + (bufoff) + ldsw + _i * 8192), 16, 0, 0); } while (0)
; #define PG8_LDA(dst, b, h) do { _Pragma("unroll") for (int m = 0; m < 4; ++m) _Pragma("unroll") for (int k = 0; k < 2; ++k) dst[m][k] = *(const LAS bf16x8*)(lds + PG8_SA(b, h) + aoff + m * 2048 + k * 1024); } while (0)
; #define PG8_WAIT_V(n) asm volatile("s_waitcnt vmcnt(" #n ")" ::: "memory")
; #define PG8_BAR __builtin_amdgcn_s_barrier()
; template <class Epi, class Ptrs>
; __device__ __forceinline__ void gemm_phase(LAS unsigned char* lds, const int K, const StaticOrder& S, const Ptrs& P, const Epi& E) {
;     ...
;         for (int t = 0; t < nt; t += 2) {
;             const bool last = (t == nt - 2);
;             const char* a1 = cA + (size_t)(t + 1) * kstep;
;             const char* a2 = last ? nA : cA + (size_t)(t + 2) * kstep; const char* b2 = last ? nB : cB + (size_t)(t + 2) * kstep;
;             const char* a3 = a2 + kstep; const char* b3 = b2 + kstep;
;             PG8_LDB(B0, 0, 0); PG8_SCHED; PG8_LDA(At, 0, 0); PG8_STAGE(PG8_SA(1, 1), a1 + hstep, voffA);
;             PG8_WAIT_L(8); PG8_BAR; PG8_WAIT_L(0); PG8_MMA(0, 0, At, B0); PG8_BAR; PG8_SCHED;
;             PG8_LDB(B1, 0, 1); PG8_STAGE(PG8_SB(0, 0), b2, voffB);
;             PG8_BAR; PG8_WAIT_L(0); PG8_MMA(0, 1, At, B1); PG8_BAR;
;             PG8_LDA(At, 0, 1); PG8_STAGE(PG8_SA(0, 0), a2, voffA);
;             PG8_BAR; PG8_WAIT_L(0); PG8_MMA(1, 0, At, B0); PG8_BAR; PG8_SCHED;
;             PG8_STAGE(PG8_SB(0, 1), b2 + hstep, voffB);
;             PG8_WAIT_V(6); PG8_BAR; PG8_MMA(1, 1, At, B1); PG8_BAR;
;             PG8_LDB(B0, 1, 0); PG8_SCHED; PG8_LDA(At, 1, 0); PG8_STAGE(PG8_SA(0, 1), a2 + hstep, voffA);
;             PG8_WAIT_L(8); PG8_BAR; PG8_WAIT_L(0); PG8_MMA(0, 0, At, B0); PG8_BAR; PG8_SCHED;
;             PG8_LDB(B1, 1, 1); PG8_STAGE(PG8_SB(1, 0), b3, voffB);
;             PG8_BAR; PG8_WAIT_L(0); PG8_MMA(0, 1, At, B1); PG8_BAR;
;             PG8_LDA(At, 1, 1); PG8_STAGE(PG8_SA(1, 0), a3, voffA);
;             PG8_BAR; PG8_WAIT_L(0); PG8_MMA(1, 0, At, B0); PG8_BAR; PG8_SCHED;
;             PG8_STAGE(PG8_SB(1, 1), b3 + hstep, voffB);
;             PG8_WAIT_V(6); PG8_BAR; PG8_MMA(1, 1, At, B1); PG8_BAR;
	s_add_u32 s42, s42, 0x40080
	s_addc_u32 s43, s43, 0
	s_add_i32 s44, s44, s51
	s_mov_b32 m0, s44
	s_nop 0
	global_load_lds_dwordx4 v178, s[42:43]
	s_add_i32 m0, s44, 0x2000
	s_nop 0
	global_load_lds_dwordx4 v182, s[42:43]
	s_waitcnt vmcnt(6)
	v_mfma_f32_16x16x32_bf16 v[52:55], v[192:195], v[144:147], v[52:55]
	v_mfma_f32_16x16x32_bf16 v[52:55], v[196:199], v[148:151], v[52:55]
	v_mfma_f32_16x16x32_bf16 v[48:51], v[212:215], v[148:151], v[48:51]
	v_mfma_f32_16x16x32_bf16 v[48:51], v[200:203], v[144:147], v[48:51]
	s_barrier
	v_mfma_f32_16x16x32_bf16 v[32:35], v[200:203], v[152:155], v[32:35]
	v_mfma_f32_16x16x32_bf16 v[32:35], v[212:215], v[156:159], v[32:35]
	v_mfma_f32_16x16x32_bf16 v[36:39], v[196:199], v[156:159], v[36:39]
	v_mfma_f32_16x16x32_bf16 v[36:39], v[192:195], v[152:155], v[36:39]
	v_mfma_f32_16x16x32_bf16 v[20:23], v[192:195], v[160:163], v[20:23]
	v_mfma_f32_16x16x32_bf16 v[20:23], v[196:199], v[164:167], v[20:23]
	v_mfma_f32_16x16x32_bf16 v[16:19], v[212:215], v[164:167], v[16:19]
	v_mfma_f32_16x16x32_bf16 v[16:19], v[200:203], v[160:163], v[16:19]
	v_mfma_f32_16x16x32_bf16 v[0:3], v[200:203], v[168:171], v[0:3]
	v_mfma_f32_16x16x32_bf16 v[0:3], v[212:215], v[172:175], v[0:3]
	v_mfma_f32_16x16x32_bf16 v[4:7], v[196:199], v[172:175], v[4:7]
	v_mfma_f32_16x16x32_bf16 v[4:7], v[192:195], v[168:171], v[4:7]
	s_barrier
	s_add_i32 s41, s41, 2
	s_add_u32 s38, s38, 0x100
	s_addc_u32 s39, s39, 0
	s_add_u32 s21, s21, 0x100
	s_addc_u32 s23, s23, 0
	s_cmp_gt_u32 s41, 13
.LBB0_353:
	ds_read_b128 v[128:131], v207
	ds_read_b128 v[132:135], v207 offset:1024
	ds_read_b128 v[136:139], v207 offset:2048
	ds_read_b128 v[140:143], v207 offset:3072
	s_add_u32 s42, s38, 0xfffc0080
	s_addc_u32 s43, s39, -1
	s_cmp_eq_u32 s41, 12
	s_cselect_b32 s45, s1, s43
	s_cselect_b32 s44, s0, s42
	s_cselect_b32 s43, s25, s23
	s_cselect_b32 s42, s24, s21
	s_add_i32 m0, s54, 0xc000
	ds_read_b128 v[144:147], v209
	ds_read_b128 v[148:151], v209 offset:1024
	ds_read_b128 v[152:155], v209 offset:2048
	ds_read_b128 v[156:159], v209 offset:3072
	ds_read_b128 v[160:163], v209 offset:4096
	ds_read_b128 v[164:167], v209 offset:5120
	ds_read_b128 v[168:171], v209 offset:6144
	ds_read_b128 v[172:175], v209 offset:7168
	global_load_lds_dwordx4 v184, s[38:39]
	s_add_i32 m0, s54, 0xe000
	s_nop 0
	global_load_lds_dwordx4 v186, s[38:39]
	s_waitcnt lgkmcnt(8)
	s_waitcnt lgkmcnt(6)
	v_mfma_f32_16x16x32_bf16 v[124:127], v[128:131], v[144:147], v[124:127]
	v_mfma_f32_16x16x32_bf16 v[124:127], v[132:135], v[148:151], v[124:127]
	v_mfma_f32_16x16x32_bf16 v[120:123], v[140:143], v[148:151], v[120:123]
	v_mfma_f32_16x16x32_bf16 v[120:123], v[136:139], v[144:147], v[120:123]
	s_barrier
	s_waitcnt lgkmcnt(0)
	v_mfma_f32_16x16x32_bf16 v[104:107], v[136:139], v[152:155], v[104:107]
	v_mfma_f32_16x16x32_bf16 v[104:107], v[140:143], v[156:159], v[104:107]
	v_mfma_f32_16x16x32_bf16 v[108:111], v[132:135], v[156:159], v[108:111]
	v_mfma_f32_16x16x32_bf16 v[108:111], v[128:131], v[152:155], v[108:111]
	v_mfma_f32_16x16x32_bf16 v[92:95], v[128:131], v[160:163], v[92:95]
	v_mfma_f32_16x16x32_bf16 v[92:95], v[132:135], v[164:167], v[92:95]
	v_mfma_f32_16x16x32_bf16 v[88:91], v[140:143], v[164:167], v[88:91]
	v_mfma_f32_16x16x32_bf16 v[88:91], v[136:139], v[160:163], v[88:91]
	v_mfma_f32_16x16x32_bf16 v[72:75], v[136:139], v[168:171], v[72:75]
	v_mfma_f32_16x16x32_bf16 v[72:75], v[140:143], v[172:175], v[72:75]
	v_mfma_f32_16x16x32_bf16 v[76:79], v[132:135], v[172:175], v[76:79]
	v_mfma_f32_16x16x32_bf16 v[76:79], v[128:131], v[168:171], v[76:79]
	s_barrier
	s_add_i32 s69, s66, s51
	s_add_u32 s90, s42, 0x80
	s_addc_u32 s91, s43, 0
	s_mov_b32 m0, s69
	ds_read_b128 v[192:195], v210
	ds_read_b128 v[196:199], v210 offset:1024
	ds_read_b128 v[200:203], v210 offset:2048
	ds_read_b128 v[212:215], v210 offset:3072
	global_load_lds_dwordx4 v178, s[42:43]
	s_add_i32 m0, s69, 0x2000
	s_nop 0
	global_load_lds_dwordx4 v182, s[42:43]
	s_waitcnt lgkmcnt(0)
	v_mfma_f32_16x16x32_bf16 v[116:119], v[192:195], v[144:147], v[116:119]
	v_mfma_f32_16x16x32_bf16 v[116:119], v[196:199], v[148:151], v[116:119]
	v_mfma_f32_16x16x32_bf16 v[112:115], v[212:215], v[148:151], v[112:115]
	v_mfma_f32_16x16x32_bf16 v[112:115], v[200:203], v[144:147], v[112:115]
	s_barrier
	s_waitcnt lgkmcnt(0)
	v_mfma_f32_16x16x32_bf16 v[96:99], v[200:203], v[152:155], v[96:99]
	v_mfma_f32_16x16x32_bf16 v[96:99], v[212:215], v[156:159], v[96:99]
	v_mfma_f32_16x16x32_bf16 v[100:103], v[196:199], v[156:159], v[100:103]
	v_mfma_f32_16x16x32_bf16 v[100:103], v[192:195], v[152:155], v[100:103]
	v_mfma_f32_16x16x32_bf16 v[84:87], v[192:195], v[160:163], v[84:87]
	v_mfma_f32_16x16x32_bf16 v[84:87], v[196:199], v[164:167], v[84:87]
	v_mfma_f32_16x16x32_bf16 v[80:83], v[212:215], v[164:167], v[80:83]
	v_mfma_f32_16x16x32_bf16 v[80:83], v[200:203], v[160:163], v[80:83]
	v_mfma_f32_16x16x32_bf16 v[64:67], v[200:203], v[168:171], v[64:67]
	v_mfma_f32_16x16x32_bf16 v[64:67], v[212:215], v[172:175], v[64:67]
	v_mfma_f32_16x16x32_bf16 v[68:71], v[196:199], v[172:175], v[68:71]
	v_mfma_f32_16x16x32_bf16 v[68:71], v[192:195], v[168:171], v[68:71]
	s_barrier
	s_mov_b32 m0, s54
	s_add_u32 s92, s44, 0x80
	s_addc_u32 s93, s45, 0
	ds_read_b128 v[144:147], v209 offset:16384
	ds_read_b128 v[148:151], v209 offset:17408
	ds_read_b128 v[152:155], v209 offset:18432
	ds_read_b128 v[156:159], v209 offset:19456
	ds_read_b128 v[160:163], v209 offset:20480
	ds_read_b128 v[164:167], v209 offset:21504
	ds_read_b128 v[168:171], v209 offset:22528
	ds_read_b128 v[172:175], v209 offset:23552
	global_load_lds_dwordx4 v176, s[44:45]
	s_mov_b32 m0, s55
	s_nop 0
	global_load_lds_dwordx4 v180, s[44:45]
	s_waitcnt lgkmcnt(6)
	v_mfma_f32_16x16x32_bf16 v[60:63], v[128:131], v[144:147], v[60:63]
	v_mfma_f32_16x16x32_bf16 v[60:63], v[132:135], v[148:151], v[60:63]
	v_mfma_f32_16x16x32_bf16 v[56:59], v[140:143], v[148:151], v[56:59]
	v_mfma_f32_16x16x32_bf16 v[56:59], v[136:139], v[144:147], v[56:59]
	s_barrier
; #define PG8_STAGE(bufoff, gbase, voff) do { _Pragma("unroll") for (int _i = 0; _i < 2; ++_i) \
;         __builtin_amdgcn_global_load_lds((const unsigned*)((const char*)(gbase) + (voff)[_i]), (LAS unsigned*)(lds + (bufoff) + ldsw + _i * 8192), 16, 0, 0); } while (0)
; #define PG8_LDA(dst, b, h) do { _Pragma("unroll") for (int m = 0; m < 4; ++m) _Pragma("unroll") for (int k = 0; k < 2; ++k) dst[m][k] = *(const LAS bf16x8*)(lds + PG8_SA(b, h) + aoff + m * 2048 + k * 1024); } while (0)
; #define PG8_WAIT_V(n) asm volatile("s_waitcnt vmcnt(" #n ")" ::: "memory")
; #define PG8_BAR __builtin_amdgcn_s_barrier()
; template <class Epi, class Ptrs>
; __device__ __forceinline__ void gemm_phase(LAS unsigned char* lds, const int K, const StaticOrder& S, const Ptrs& P, const Epi& E) {
;     ...
;         for (int t = 0; t < nt; t += 2) {
;             const bool last = (t == nt - 2);
;             const char* a1 = cA + (size_t)(t + 1) * kstep;
;             const char* a2 = last ? nA : cA + (size_t)(t + 2) * kstep; const char* b2 = last ? nB : cB + (size_t)(t + 2) * kstep;
;             const char* a3 = a2 + kstep; const char* b3 = b2 + kstep;
;             PG8_LDB(B0, 0, 0); PG8_SCHED; PG8_LDA(At, 0, 0); PG8_STAGE(PG8_SA(1, 1), a1 + hstep, voffA);
;             PG8_WAIT_L(8); PG8_BAR; PG8_WAIT_L(0); PG8_MMA(0, 0, At, B0); PG8_BAR; PG8_SCHED;
;             PG8_LDB(B1, 0, 1); PG8_STAGE(PG8_SB(0, 0), b2, voffB);
;             PG8_BAR; PG8_WAIT_L(0); PG8_MMA(0, 1, At, B1); PG8_BAR;
;             PG8_LDA(At, 0, 1); PG8_STAGE(PG8_SA(0, 0), a2, voffA);
;             PG8_BAR; PG8_WAIT_L(0); PG8_MMA(1, 0, At, B0); PG8_BAR; PG8_SCHED;
;             PG8_STAGE(PG8_SB(0, 1), b2 + hstep, voffB);
;             PG8_WAIT_V(6); PG8_BAR; PG8_MMA(1, 1, At, B1); PG8_BAR;
;             PG8_LDB(B0, 1, 0); PG8_SCHED; PG8_LDA(At, 1, 0); PG8_STAGE(PG8_SA(0, 1), a2 + hstep, voffA);
;             PG8_WAIT_L(8); PG8_BAR; PG8_WAIT_L(0); PG8_MMA(0, 0, At, B0); PG8_BAR; PG8_SCHED;
;             PG8_LDB(B1, 1, 1); PG8_STAGE(PG8_SB(1, 0), b3, voffB);
;             PG8_BAR; PG8_WAIT_L(0); PG8_MMA(0, 1, At, B1); PG8_BAR;
;             PG8_LDA(At, 1, 1); PG8_STAGE(PG8_SA(1, 0), a3, voffA);
;             PG8_BAR; PG8_WAIT_L(0); PG8_MMA(1, 0, At, B0); PG8_BAR; PG8_SCHED;
;             PG8_STAGE(PG8_SB(1, 1), b3 + hstep, voffB);
;             PG8_WAIT_V(6); PG8_BAR; PG8_MMA(1, 1, At, B1); PG8_BAR;
	s_waitcnt lgkmcnt(0)
	v_mfma_f32_16x16x32_bf16 v[40:43], v[136:139], v[152:155], v[40:43]
	v_mfma_f32_16x16x32_bf16 v[40:43], v[140:143], v[156:159], v[40:43]
	v_mfma_f32_16x16x32_bf16 v[44:47], v[132:135], v[156:159], v[44:47]
	v_mfma_f32_16x16x32_bf16 v[44:47], v[128:131], v[152:155], v[44:47]
	v_mfma_f32_16x16x32_bf16 v[28:31], v[128:131], v[160:163], v[28:31]
	v_mfma_f32_16x16x32_bf16 v[28:31], v[132:135], v[164:167], v[28:31]
	v_mfma_f32_16x16x32_bf16 v[24:27], v[140:143], v[164:167], v[24:27]
	v_mfma_f32_16x16x32_bf16 v[24:27], v[136:139], v[160:163], v[24:27]
	v_mfma_f32_16x16x32_bf16 v[8:11], v[136:139], v[168:171], v[8:11]
	v_mfma_f32_16x16x32_bf16 v[8:11], v[140:143], v[172:175], v[8:11]
	v_mfma_f32_16x16x32_bf16 v[12:15], v[132:135], v[172:175], v[12:15]
	v_mfma_f32_16x16x32_bf16 v[12:15], v[128:131], v[168:171], v[12:15]
	s_barrier
	s_add_u32 s70, s42, 0x40000
	s_addc_u32 s71, s43, 0
	s_add_i32 s69, s67, s51
	s_mov_b32 m0, s69
	s_nop 0
	global_load_lds_dwordx4 v178, s[70:71]
	s_add_i32 m0, s69, 0x2000
	s_nop 0
	global_load_lds_dwordx4 v182, s[70:71]
	s_waitcnt vmcnt(6)
	v_mfma_f32_16x16x32_bf16 v[52:55], v[192:195], v[144:147], v[52:55]
	v_mfma_f32_16x16x32_bf16 v[52:55], v[196:199], v[148:151], v[52:55]
	v_mfma_f32_16x16x32_bf16 v[48:51], v[212:215], v[148:151], v[48:51]
	v_mfma_f32_16x16x32_bf16 v[48:51], v[200:203], v[144:147], v[48:51]
	s_barrier
	v_mfma_f32_16x16x32_bf16 v[32:35], v[200:203], v[152:155], v[32:35]
	v_mfma_f32_16x16x32_bf16 v[32:35], v[212:215], v[156:159], v[32:35]
	v_mfma_f32_16x16x32_bf16 v[36:39], v[196:199], v[156:159], v[36:39]
	v_mfma_f32_16x16x32_bf16 v[36:39], v[192:195], v[152:155], v[36:39]
	v_mfma_f32_16x16x32_bf16 v[20:23], v[192:195], v[160:163], v[20:23]
	v_mfma_f32_16x16x32_bf16 v[20:23], v[196:199], v[164:167], v[20:23]
	v_mfma_f32_16x16x32_bf16 v[16:19], v[212:215], v[164:167], v[16:19]
	v_mfma_f32_16x16x32_bf16 v[16:19], v[200:203], v[160:163], v[16:19]
	v_mfma_f32_16x16x32_bf16 v[0:3], v[200:203], v[168:171], v[0:3]
	v_mfma_f32_16x16x32_bf16 v[0:3], v[212:215], v[172:175], v[0:3]
	v_mfma_f32_16x16x32_bf16 v[4:7], v[196:199], v[172:175], v[4:7]
	v_mfma_f32_16x16x32_bf16 v[4:7], v[192:195], v[168:171], v[4:7]
	s_barrier
	s_add_i32 s69, 0, 0x18000
	ds_read_b128 v[128:131], v252
	ds_read_b128 v[132:135], v252 offset:1024
	ds_read_b128 v[136:139], v252 offset:2048
	ds_read_b128 v[140:143], v252 offset:3072
	s_add_u32 s44, s44, 0x40000
	s_addc_u32 s45, s45, 0
	s_mov_b32 m0, s56
	ds_read_b128 v[144:147], v209 offset:32768
	ds_read_b128 v[148:151], v209 offset:33792
	ds_read_b128 v[152:155], v209 offset:34816
	ds_read_b128 v[156:159], v209 offset:35840
	ds_read_b128 v[160:163], v209 offset:36864
	ds_read_b128 v[164:167], v209 offset:37888
	ds_read_b128 v[168:171], v209 offset:38912
	ds_read_b128 v[172:175], v209 offset:39936
	global_load_lds_dwordx4 v176, s[44:45]
	s_mov_b32 m0, s57
	s_nop 0
	global_load_lds_dwordx4 v180, s[44:45]
	s_waitcnt lgkmcnt(8)
	s_waitcnt lgkmcnt(6)
	v_mfma_f32_16x16x32_bf16 v[124:127], v[128:131], v[144:147], v[124:127]
	v_mfma_f32_16x16x32_bf16 v[124:127], v[132:135], v[148:151], v[124:127]
	v_mfma_f32_16x16x32_bf16 v[120:123], v[140:143], v[148:151], v[120:123]
	v_mfma_f32_16x16x32_bf16 v[120:123], v[136:139], v[144:147], v[120:123]
	s_barrier
	s_waitcnt lgkmcnt(0)
	v_mfma_f32_16x16x32_bf16 v[104:107], v[136:139], v[152:155], v[104:107]
	v_mfma_f32_16x16x32_bf16 v[104:107], v[140:143], v[156:159], v[104:107]
	v_mfma_f32_16x16x32_bf16 v[108:111], v[132:135], v[156:159], v[108:111]
	v_mfma_f32_16x16x32_bf16 v[108:111], v[128:131], v[152:155], v[108:111]
	v_mfma_f32_16x16x32_bf16 v[92:95], v[128:131], v[160:163], v[92:95]
	v_mfma_f32_16x16x32_bf16 v[92:95], v[132:135], v[164:167], v[92:95]
	v_mfma_f32_16x16x32_bf16 v[88:91], v[140:143], v[164:167], v[88:91]
	v_mfma_f32_16x16x32_bf16 v[88:91], v[136:139], v[160:163], v[88:91]
	v_mfma_f32_16x16x32_bf16 v[72:75], v[136:139], v[168:171], v[72:75]
	v_mfma_f32_16x16x32_bf16 v[72:75], v[140:143], v[172:175], v[72:75]
	v_mfma_f32_16x16x32_bf16 v[76:79], v[132:135], v[172:175], v[76:79]
	v_mfma_f32_16x16x32_bf16 v[76:79], v[128:131], v[168:171], v[76:79]
	s_barrier
	s_add_i32 s44, 0, 0x1c000
	s_add_i32 s45, s69, s51
	s_mov_b32 m0, s45
	ds_read_b128 v[192:195], v253
	ds_read_b128 v[196:199], v253 offset:1024
	ds_read_b128 v[200:203], v253 offset:2048
	ds_read_b128 v[212:215], v253 offset:3072
	global_load_lds_dwordx4 v178, s[90:91]
	s_add_i32 m0, s45, 0x2000
	s_nop 0
	global_load_lds_dwordx4 v182, s[90:91]
	s_waitcnt lgkmcnt(0)
	v_mfma_f32_16x16x32_bf16 v[116:119], v[192:195], v[144:147], v[116:119]
	v_mfma_f32_16x16x32_bf16 v[116:119], v[196:199], v[148:151], v[116:119]
	v_mfma_f32_16x16x32_bf16 v[112:115], v[212:215], v[148:151], v[112:115]
	v_mfma_f32_16x16x32_bf16 v[112:115], v[200:203], v[144:147], v[112:115]
	s_barrier
	s_waitcnt lgkmcnt(0)
	v_mfma_f32_16x16x32_bf16 v[96:99], v[200:203], v[152:155], v[96:99]
	v_mfma_f32_16x16x32_bf16 v[96:99], v[212:215], v[156:159], v[96:99]
	v_mfma_f32_16x16x32_bf16 v[100:103], v[196:199], v[156:159], v[100:103]
	v_mfma_f32_16x16x32_bf16 v[100:103], v[192:195], v[152:155], v[100:103]
	v_mfma_f32_16x16x32_bf16 v[84:87], v[192:195], v[160:163], v[84:87]
	v_mfma_f32_16x16x32_bf16 v[84:87], v[196:199], v[164:167], v[84:87]
	v_mfma_f32_16x16x32_bf16 v[80:83], v[212:215], v[164:167], v[80:83]
	v_mfma_f32_16x16x32_bf16 v[80:83], v[200:203], v[160:163], v[80:83]
	v_mfma_f32_16x16x32_bf16 v[64:67], v[200:203], v[168:171], v[64:67]
	v_mfma_f32_16x16x32_bf16 v[64:67], v[212:215], v[172:175], v[64:67]
	v_mfma_f32_16x16x32_bf16 v[68:71], v[196:199], v[172:175], v[68:71]
	v_mfma_f32_16x16x32_bf16 v[68:71], v[192:195], v[168:171], v[68:71]
	s_barrier
; #define PG8_STAGE(bufoff, gbase, voff) do { _Pragma("unroll") for (int _i = 0; _i < 2; ++_i) \
;         __builtin_amdgcn_global_load_lds((const unsigned*)((const char*)(gbase) + (voff)[_i]), (LAS unsigned*)(lds + (bufoff) + ldsw + _i * 8192), 16, 0, 0); } while (0)
; #define PG8_LDA(dst, b, h) do { _Pragma("unroll") for (int m = 0; m < 4; ++m) _Pragma("unroll") for (int k = 0; k < 2; ++k) dst[m][k] = *(const LAS bf16x8*)(lds + PG8_SA(b, h) + aoff + m * 2048 + k * 1024); } while (0)
; #define PG8_WAIT_V(n) asm volatile("s_waitcnt vmcnt(" #n ")" ::: "memory")
; #define PG8_BAR __builtin_amdgcn_s_barrier()
; template <class Epi, class Ptrs>
; __device__ __forceinline__ void gemm_phase(LAS unsigned char* lds, const int K, const StaticOrder& S, const Ptrs& P, const Epi& E) {
;     ...
;         for (int t = 0; t < nt; t += 2) {
;             const bool last = (t == nt - 2);
;             const char* a1 = cA + (size_t)(t + 1) * kstep;
;             const char* a2 = last ? nA : cA + (size_t)(t + 2) * kstep; const char* b2 = last ? nB : cB + (size_t)(t + 2) * kstep;
;             const char* a3 = a2 + kstep; const char* b3 = b2 + kstep;
;             PG8_LDB(B0, 0, 0); PG8_SCHED; PG8_LDA(At, 0, 0); PG8_STAGE(PG8_SA(1, 1), a1 + hstep, voffA);
;             PG8_WAIT_L(8); PG8_BAR; PG8_WAIT_L(0); PG8_MMA(0, 0, At, B0); PG8_BAR; PG8_SCHED;
;             PG8_LDB(B1, 0, 1); PG8_STAGE(PG8_SB(0, 0), b2, voffB);
;             PG8_BAR; PG8_WAIT_L(0); PG8_MMA(0, 1, At, B1); PG8_BAR;
;             PG8_LDA(At, 0, 1); PG8_STAGE(PG8_SA(0, 0), a2, voffA);
;             PG8_BAR; PG8_WAIT_L(0); PG8_MMA(1, 0, At, B0); PG8_BAR; PG8_SCHED;
;             PG8_STAGE(PG8_SB(0, 1), b2 + hstep, voffB);
;             PG8_WAIT_V(6); PG8_BAR; PG8_MMA(1, 1, At, B1); PG8_BAR;
;             PG8_LDB(B0, 1, 0); PG8_SCHED; PG8_LDA(At, 1, 0); PG8_STAGE(PG8_SA(0, 1), a2 + hstep, voffA);
;             PG8_WAIT_L(8); PG8_BAR; PG8_WAIT_L(0); PG8_MMA(0, 0, At, B0); PG8_BAR; PG8_SCHED;
;             PG8_LDB(B1, 1, 1); PG8_STAGE(PG8_SB(1, 0), b3, voffB);
;             PG8_BAR; PG8_WAIT_L(0); PG8_MMA(0, 1, At, B1); PG8_BAR;
;             PG8_LDA(At, 1, 1); PG8_STAGE(PG8_SA(1, 0), a3, voffA);
;             PG8_BAR; PG8_WAIT_L(0); PG8_MMA(1, 0, At, B0); PG8_BAR; PG8_SCHED;
;             PG8_STAGE(PG8_SB(1, 1), b3 + hstep, voffB);
;             PG8_WAIT_V(6); PG8_BAR; PG8_MMA(1, 1, At, B1); PG8_BAR;
	s_mov_b32 m0, s63
	ds_read_b128 v[144:147], v209 offset:49152
	ds_read_b128 v[148:151], v209 offset:50176
	ds_read_b128 v[152:155], v209 offset:51200
	ds_read_b128 v[156:159], v209 offset:52224
	ds_read_b128 v[160:163], v209 offset:53248
	ds_read_b128 v[164:167], v209 offset:54272
	ds_read_b128 v[168:171], v209 offset:55296
	ds_read_b128 v[172:175], v209 offset:56320
	global_load_lds_dwordx4 v176, s[92:93]
	s_mov_b32 m0, s64
	s_nop 0
	global_load_lds_dwordx4 v180, s[92:93]
	s_waitcnt lgkmcnt(6)
	v_mfma_f32_16x16x32_bf16 v[60:63], v[128:131], v[144:147], v[60:63]
	v_mfma_f32_16x16x32_bf16 v[60:63], v[132:135], v[148:151], v[60:63]
	v_mfma_f32_16x16x32_bf16 v[56:59], v[140:143], v[148:151], v[56:59]
	v_mfma_f32_16x16x32_bf16 v[56:59], v[136:139], v[144:147], v[56:59]
	s_barrier
	s_waitcnt lgkmcnt(0)
	v_mfma_f32_16x16x32_bf16 v[40:43], v[136:139], v[152:155], v[40:43]
	v_mfma_f32_16x16x32_bf16 v[40:43], v[140:143], v[156:159], v[40:43]
	v_mfma_f32_16x16x32_bf16 v[44:47], v[132:135], v[156:159], v[44:47]
	v_mfma_f32_16x16x32_bf16 v[44:47], v[128:131], v[152:155], v[44:47]
	v_mfma_f32_16x16x32_bf16 v[28:31], v[128:131], v[160:163], v[28:31]
	v_mfma_f32_16x16x32_bf16 v[28:31], v[132:135], v[164:167], v[28:31]
	v_mfma_f32_16x16x32_bf16 v[24:27], v[140:143], v[164:167], v[24:27]
	v_mfma_f32_16x16x32_bf16 v[24:27], v[136:139], v[160:163], v[24:27]
	v_mfma_f32_16x16x32_bf16 v[8:11], v[136:139], v[168:171], v[8:11]
	v_mfma_f32_16x16x32_bf16 v[8:11], v[140:143], v[172:175], v[8:11]
	v_mfma_f32_16x16x32_bf16 v[12:15], v[132:135], v[172:175], v[12:15]
	v_mfma_f32_16x16x32_bf16 v[12:15], v[128:131], v[168:171], v[12:15]
	s_barrier
	s_add_u32 s42, s42, 0x40080
	s_addc_u32 s43, s43, 0
	s_add_i32 s44, s44, s51
	s_mov_b32 m0, s44
	s_nop 0
	global_load_lds_dwordx4 v178, s[42:43]
	s_add_i32 m0, s44, 0x2000
	s_nop 0
	global_load_lds_dwordx4 v182, s[42:43]
	s_waitcnt vmcnt(6)
	v_mfma_f32_16x16x32_bf16 v[52:55], v[192:195], v[144:147], v[52:55]
	v_mfma_f32_16x16x32_bf16 v[52:55], v[196:199], v[148:151], v[52:55]
	v_mfma_f32_16x16x32_bf16 v[48:51], v[212:215], v[148:151], v[48:51]
	v_mfma_f32_16x16x32_bf16 v[48:51], v[200:203], v[144:147], v[48:51]
	s_barrier
	v_mfma_f32_16x16x32_bf16 v[32:35], v[200:203], v[152:155], v[32:35]
	v_mfma_f32_16x16x32_bf16 v[32:35], v[212:215], v[156:159], v[32:35]
	v_mfma_f32_16x16x32_bf16 v[36:39], v[196:199], v[156:159], v[36:39]
	v_mfma_f32_16x16x32_bf16 v[36:39], v[192:195], v[152:155], v[36:39]
	v_mfma_f32_16x16x32_bf16 v[20:23], v[192:195], v[160:163], v[20:23]
	v_mfma_f32_16x16x32_bf16 v[20:23], v[196:199], v[164:167], v[20:23]
	v_mfma_f32_16x16x32_bf16 v[16:19], v[212:215], v[164:167], v[16:19]
	v_mfma_f32_16x16x32_bf16 v[16:19], v[200:203], v[160:163], v[16:19]
	v_mfma_f32_16x16x32_bf16 v[0:3], v[200:203], v[168:171], v[0:3]
	v_mfma_f32_16x16x32_bf16 v[0:3], v[212:215], v[172:175], v[0:3]
	v_mfma_f32_16x16x32_bf16 v[4:7], v[196:199], v[172:175], v[4:7]
	v_mfma_f32_16x16x32_bf16 v[4:7], v[192:195], v[168:171], v[4:7]
	s_barrier
	s_add_i32 s41, s41, 2
	s_add_u32 s38, s38, 0x100
	s_addc_u32 s39, s39, 0
	s_add_u32 s21, s21, 0x100
	s_addc_u32 s23, s23, 0
	s_cmp_gt_u32 s41, 13
	s_cbranch_scc0 .LBB0_353
; __device__ __forceinline__ unsigned cvt_pk_bf16(float lo, float hi) { unsigned r; asm volatile("v_cvt_pk_bf16_f32 %0, %1, %2" : "=v"(r) : "v"(lo), "v"(hi)); return r; }
; __device__ __forceinline__ float x16_sum(float x) { auto s = __builtin_amdgcn_permlane16_swap(__float_as_uint(x), __float_as_uint(x), false, false); return __uint_as_float(s[0]) + __uint_as_float(s[1]); }
; __device__ __forceinline__ float x32_sum(float x) { auto s = __builtin_amdgcn_permlane32_swap(__float_as_uint(x), __float_as_uint(x), false, false); return __uint_as_float(s[0]) + __uint_as_float(s[1]); }
;     __device__ __forceinline__ void operator()(const f32x4 (&acc)[2][2][4][2], const Unit& u, int ui, int wr, int wc, int fr, int fq) const {
;         const int row0 = u.pm * 256 + wr * 64 + fr, col0 = u.pn * 256 + wc * 32 + 8 * fq;
;         const float* xb0 = (u.pm * 256 < MP) ? xp : xs - (size_t)MP * DM;
; #pragma unroll
;         for (int ai = 0; ai < 2; ++ai) {
;             f32x4 xv[4][2][2];
; #pragma unroll
;             for (int m = 0; m < 4; ++m)
; #pragma unroll
;                 for (int bj = 0; bj < 2; ++bj) { const float* p = xb0 + (size_t)(row0 + ai * 128 + m * 16) * DM + col0 + bj * 128; xv[m][bj][0] = *(const f32x4*)p; xv[m][bj][1] = *(const f32x4*)(p + 4); }
; #pragma unroll
;             for (int m = 0; m < 4; ++m) { const int row = row0 + ai * 128 + m * 16; const size_t off = (size_t)row * DM + col0; float ss = 0.f;
; #pragma unroll
;                 for (int bj = 0; bj < 2; ++bj) {
;                     const f32x4 v0 = acc[ai][bj][m][0] + xv[m][bj][0], v1 = acc[ai][bj][m][1] + xv[m][bj][1];
;                     u32x4 w; w.x = cvt_pk_bf16(v0[0], v0[1]); w.y = cvt_pk_bf16(v0[2], v0[3]); w.z = cvt_pk_bf16(v1[0], v1[1]); w.w = cvt_pk_bf16(v1[2], v1[3]);
;                     *(u32x4*)(xb + off + bj * 128) = w;
;                     ss += (v0[0] * v0[0] + v0[1] * v0[1]) + (v0[2] * v0[2] + v0[3] * v0[3]) + (v1[0] * v1[0] + v1[1] * v1[1]) + (v1[2] * v1[2] + v1[3] * v1[3]); }
;                 ss = x32_sum(x16_sum(ss));
;                 if (fq == 0) part[(size_t)row * 16 + u.pn * 4 + wc] = ss; }
	s_cmpk_lt_i32 s40, 0x80
	v_lshl_add_u32 v194, s40, 8, v204
	v_lshl_or_b32 v192, s12, 8, v206
	s_cselect_b32 s21, s37, s61
	s_cselect_b32 s23, s36, s60
	v_mov_b32_e32 v128, s23
	v_mov_b32_e32 v129, s21
	v_ashrrev_i32_e32 v193, 31, v192
	v_ashrrev_i32_e32 v195, 31, v194
	v_lshl_add_u64 v[196:197], v[192:193], 2, v[128:129]
	v_lshlrev_b64 v[128:129], 12, v[194:195]
	v_or_b32_e32 v202, 16, v194
	v_or_b32_e32 v200, 32, v194
	v_or_b32_e32 v198, 48, v194
	v_lshl_add_u64 v[128:129], v[196:197], 0, v[128:129]
	v_ashrrev_i32_e32 v203, 31, v202
	v_ashrrev_i32_e32 v201, 31, v200
	v_ashrrev_i32_e32 v199, 31, v198
	global_load_dwordx4 v[212:215], v[128:129], off
	global_load_dwordx4 v[216:219], v[128:129], off offset:16
	global_load_dwordx4 v[220:223], v[128:129], off offset:512
	global_load_dwordx4 v[224:227], v[128:129], off offset:528
	v_lshlrev_b64 v[128:129], 12, v[202:203]
	v_lshlrev_b64 v[130:131], 12, v[200:201]
	v_lshlrev_b64 v[132:133], 12, v[198:199]
	v_lshl_add_u64 v[128:129], v[196:197], 0, v[128:129]
	v_lshl_add_u64 v[130:131], v[196:197], 0, v[130:131]
	v_lshl_add_u64 v[132:133], v[196:197], 0, v[132:133]
	global_load_dwordx4 v[168:171], v[128:129], off offset:16
	global_load_dwordx4 v[172:175], v[128:129], off
	global_load_dwordx4 v[160:163], v[128:129], off offset:528
	global_load_dwordx4 v[164:167], v[128:129], off offset:512
	global_load_dwordx4 v[152:155], v[130:131], off offset:16
	global_load_dwordx4 v[156:159], v[130:131], off
	global_load_dwordx4 v[144:147], v[130:131], off offset:528
	global_load_dwordx4 v[148:151], v[130:131], off offset:512
	global_load_dwordx4 v[136:139], v[132:133], off offset:16
	global_load_dwordx4 v[140:143], v[132:133], off
	s_nop 0
	global_load_dwordx4 v[128:131], v[132:133], off offset:528
	s_nop 0
	global_load_dwordx4 v[132:135], v[132:133], off offset:512
	v_lshlrev_b64 v[228:229], 11, v[194:195]
	v_lshl_add_u64 v[228:229], s[14:15], 0, v[228:229]
	v_lshl_add_u64 v[228:229], v[192:193], 1, v[228:229]
	s_lshl_b32 s38, s12, 2
	s_ashr_i32 s39, s38, 31
	s_waitcnt vmcnt(0)
	v_pk_add_f32 v[126:127], v[126:127], v[214:215]
	v_pk_add_f32 v[124:125], v[124:125], v[212:213]
	v_pk_add_f32 v[118:119], v[118:119], v[222:223]
	v_pk_add_f32 v[116:117], v[116:117], v[220:221]
	v_pk_add_f32 v[120:121], v[120:121], v[216:217]
	v_pk_add_f32 v[214:215], v[112:113], v[224:225]
	v_cvt_pk_bf16_f32 v112, v124, v125
	v_cvt_pk_bf16_f32 v113, v126, v127
	v_mul_f32_e32 v125, v125, v125
	v_mul_f32_e32 v127, v127, v127
	v_mul_f32_e32 v211, v117, v117
	v_mul_f32_e32 v216, v119, v119
	v_pk_add_f32 v[122:123], v[122:123], v[218:219]
	v_pk_add_f32 v[212:213], v[114:115], v[226:227]
	v_cvt_pk_bf16_f32 v114, v120, v121
	v_cvt_pk_bf16_f32 v115, v122, v123
	v_mul_f32_e32 v121, v121, v121
	v_mul_f32_e32 v217, v215, v215
	global_store_dwordx4 v[228:229], v[112:115], off
	v_fmac_f32_e32 v125, v124, v124
	v_fmac_f32_e32 v127, v126, v126
	v_cvt_pk_bf16_f32 v112, v116, v117
	v_fmac_f32_e32 v211, v116, v116
	v_fmac_f32_e32 v216, v118, v118
	v_mul_f32_e32 v123, v123, v123
	v_mul_f32_e32 v218, v213, v213
	v_fmac_f32_e32 v121, v120, v120
	v_cvt_pk_bf16_f32 v113, v118, v119
	v_cvt_pk_bf16_f32 v114, v214, v215
	v_cvt_pk_bf16_f32 v115, v212, v213
	v_fmac_f32_e32 v217, v214, v214
	v_add_f32_e32 v116, v125, v127
	global_store_dwordx4 v[228:229], v[112:115], off offset:256
	v_fmac_f32_e32 v123, v122, v122
	v_fmac_f32_e32 v218, v212, v212
	v_add_f32_e32 v112, v211, v216
	v_add_f32_e32 v113, v116, v121
	v_add_f32_e32 v112, v112, v217
	v_add_f32_e32 v113, v123, v113
	v_add_f32_e32 v112, v218, v112
	v_add_f32_e32 v112, v113, v112
	v_mov_b32_e32 v113, v112
	s_nop 1
	v_permlane16_swap_b32_e32 v112, v113
	v_add_f32_e32 v112, v112, v113
	v_mov_b32_e32 v113, v112
	s_nop 1
	v_permlane32_swap_b32_e32 v112, v113
	s_and_saveexec_b64 s[40:41], s[6:7]
	s_cbranch_execz .LBB0_356
	v_lshlrev_b64 v[114:115], 6, v[194:195]
	v_lshl_add_u64 v[114:115], s[16:17], 0, v[114:115]
	v_lshl_add_u64 v[114:115], s[38:39], 2, v[114:115]
	s_lshl_b32 s12, s62, 2
	v_lshl_add_u64 v[114:115], v[114:115], 0, s[12:13]
	v_add_f32_e32 v112, v112, v113
	global_store_dword v[114:115], v112, off

; __device__ __forceinline__ unsigned xb_ld(unsigned* p)              { return __hip_atomic_load(p, __ATOMIC_RELAXED, __HIP_MEMORY_SCOPE_AGENT); }
; __device__ __forceinline__ void xcd_barrier_complete(unsigned* bar, unsigned x, unsigned& nloc, unsigned& nx) {
;     const unsigned G = gridDim.x * gridDim.y * gridDim.z;
;     unsigned sum, cnt, mine, sp = 0u;
;     for (;;) {
;         sum = 0u; cnt = 0u; mine = 0u;
; #pragma unroll
;         for (unsigned j = 0; j < 16; ++j) { const unsigned c = xb_ld(&bar[XB_XCNT(j)]); sum += c; cnt += (c > 0u) ? 1u : 0u; mine = (j == x) ? c : mine; }
; __device__ __forceinline__ void xcd_barrier(const XcdBarrier& b) {
;     asm volatile("s_waitcnt vmcnt(0)" ::: "memory");
;     __syncthreads();
;     if (threadIdx.x == 0) {
;         unsigned* bar = b.bar;
;         __builtin_amdgcn_s_waitcnt(0);
;         unsigned nloc = b.st[0], nx = b.st[1];
;         if (nloc == 0u) { xcd_barrier_complete(bar, b.x, nloc, nx); b.st[0] = nloc; b.st[1] = nx; }
.LBB0_373:
	s_nop 0
	s_nop 0
	s_nop 0
	s_nop 0
	s_nop 0
	s_nop 0
	s_nop 0
	s_nop 0
	s_nop 0
	s_nop 0
	s_nop 0
	s_nop 0
	s_nop 0
	s_nop 0
	s_nop 0
	s_nop 0
	s_nop 0
	s_nop 0
	s_nop 0
	s_nop 0
	s_nop 0
	s_nop 0
	s_nop 0
	s_nop 0
	s_nop 0
	s_nop 0
	s_nop 0
	s_nop 0
	s_nop 0
	s_nop 0
	s_nop 0
	s_nop 0
	s_nop 0
	s_nop 0
	s_nop 0
	s_nop 0
	s_nop 0
	s_nop 0
	s_nop 0
	s_nop 0
	s_nop 0
	s_nop 0
	s_nop 0
	s_cmp_gt_i32 s31, 4
	s_cselect_b64 s[0:1], -1, 0
	s_and_b64 s[4:5], s[10:11], s[0:1]
	s_andn2_b64 vcc, exec, s[4:5]
	s_cbranch_vccnz .LBB0_423
	s_waitcnt vmcnt(0)
	s_waitcnt vmcnt(0) lgkmcnt(0)
	s_barrier
	s_and_saveexec_b64 s[4:5], s[8:9]
	s_cbranch_execz .LBB0_422
	s_add_i32 s6, 0, 0x25ff0
	v_mov_b32_e32 v0, s6
	s_waitcnt vmcnt(0) expcnt(0) lgkmcnt(0)
	ds_read_b32 v2, v0
	s_add_i32 s6, 0, 0x25ff4
	v_mov_b32_e32 v0, s6
	ds_read_b32 v0, v0
	s_waitcnt lgkmcnt(1)
	v_cmp_ne_u32_e32 vcc, 0, v2
	s_cbranch_vccnz .LBB0_390
	s_load_dwordx2 s[12:13], s[52:53], 0x4
	s_add_u32 s6, s28, 0x3e800200
	s_addc_u32 s7, s29, 0
	s_add_u32 s10, s28, 0x3e800400
	s_addc_u32 s11, s29, 0
	s_waitcnt lgkmcnt(0)
	s_mul_i32 s60, s12, s3
	s_add_u32 s12, s28, 0x3e800500
	s_mul_i32 s60, s60, s13
	s_addc_u32 s13, s29, 0
	s_add_u32 s14, s28, 0x3e800600
	s_addc_u32 s15, s29, 0
	s_add_u32 s16, s28, 0x3e800700
	s_addc_u32 s17, s29, 0
	s_add_u32 s18, s28, 0x3e800800
	s_addc_u32 s19, s29, 0
	s_add_u32 s20, s28, 0x3e800900
	s_addc_u32 s21, s29, 0
	s_add_u32 s22, s28, 0x3e800a00
	s_addc_u32 s23, s29, 0
	s_add_u32 s24, s28, 0x3e800b00
	s_addc_u32 s25, s29, 0
	s_add_u32 s36, s28, 0x3e800c00
	s_addc_u32 s37, s29, 0
	s_add_u32 s38, s28, 0x3e800d00
	s_addc_u32 s39, s29, 0
	s_add_u32 s40, s28, 0x3e800e00
	s_addc_u32 s41, s29, 0
	s_add_u32 s42, s28, 0x3e800f00
	s_addc_u32 s43, s29, 0
	s_add_u32 s44, s28, 0x3e801000
	s_addc_u32 s45, s29, 0
	s_add_u32 s46, s28, 0x3e801100
	s_addc_u32 s47, s29, 0
	s_add_u32 s48, s28, 0x3e801200
	s_addc_u32 s49, s29, 0
	s_add_u32 s50, s28, 0x3e801300
	s_addc_u32 s51, s29, 0
	s_mov_b32 s61, 1
	v_mov_b32_e32 v16, 0
	s_branch .LBB0_378

; #define PG8_STAGE(bufoff, gbase, voff) do { _Pragma("unroll") for (int _i = 0; _i < 2; ++_i) \
;         __builtin_amdgcn_global_load_lds((const unsigned*)((const char*)(gbase) + (voff)[_i]), (LAS unsigned*)(lds + (bufoff) + ldsw + _i * 8192), 16, 0, 0); } while (0)
; #define PG8_WAIT_V(n) asm volatile("s_waitcnt vmcnt(" #n ")" ::: "memory")
; #define PG8_BAR __builtin_amdgcn_s_barrier()
; template <class Epi, class Ptrs>
; __device__ __forceinline__ void gemm_phase(LAS unsigned char* lds, const int K, const StaticOrder& S, const Ptrs& P, const Epi& E) {
;     ...
;     for (int i = 0; i < 2; ++i) { int R, C; stage_rc(tid * 16 + i * 8192, R, C); const int Rb = (R & ~31) + perm32(R & 31);
;         voffA[i] = (unsigned)(R * K + C) * 2u; voffB[i] = (unsigned)(Rb * K + C) * 2u; }
;     const size_t kstep = (size_t)(BK * 2);
;     const size_t hstep = (size_t)HALF * K * 2;
;     const unsigned ldsw = (unsigned)wid * 1024u;
;     const int aoff = lds_byte(wr * 64 + fr, fq * 8), boff = lds_byte(wc * 32 + fr, fq * 8);
;     ...
;     PG8_STAGE(PG8_SB(0, 0), cB, voffB); PG8_STAGE(PG8_SA(0, 0), cA, voffA); PG8_STAGE(PG8_SB(0, 1), cB + hstep, voffB); PG8_STAGE(PG8_SA(0, 1), cA + hstep, voffA);
;     if (wr == 1) PG8_BAR;
;     PG8_WAIT_V(4); PG8_BAR;
;     PG8_STAGE(PG8_SB(1, 0), cB + kstep, voffB); PG8_STAGE(PG8_SA(1, 0), cA + kstep, voffA); PG8_STAGE(PG8_SB(1, 1), cB + hstep + kstep, voffB);
;     PG8_WAIT_V(6); PG8_BAR;
.LBB0_427:
	s_nop 0
	s_nop 0
	s_nop 0
	s_nop 0
	s_nop 0
	s_nop 0
	s_nop 0
	s_nop 0
	s_nop 0
	s_nop 0
	s_nop 0
	s_nop 0
	s_nop 0
	s_nop 0
	s_nop 0
	s_nop 0
	s_nop 0
	s_nop 0
	s_nop 0
	s_nop 0
	s_nop 0
	s_nop 0
	s_nop 0
	s_nop 0
	s_nop 0
	s_nop 0
	s_nop 0
	s_nop 0
	s_nop 0
	s_nop 0
	s_nop 0
	s_nop 0
	s_nop 0
	s_nop 0
	s_nop 0
	s_nop 0
	s_nop 0
	s_nop 0
	s_nop 0
	s_nop 0
	s_nop 0
	s_nop 0
	s_add_u32 s10, s28, 0xe000000
	s_addc_u32 s11, s29, 0
	s_lshl_b32 s4, s4, 5
	s_mov_b64 s[12:13], 0x80
	s_and_b32 s15, s4, 0x60
	s_add_i32 m0, s39, 0x18000
	v_lshl_add_u64 v[6:7], v[6:7], 0, s[12:13]
	s_ashr_i32 s60, s3, 31
	s_lshl_b32 s14, s1, 13
	s_lshl_b32 s16, s15, 7
	s_waitcnt vmcnt(4)
	s_barrier
	global_load_lds_dwordx4 v[6:7], off
	v_lshl_add_u64 v[4:5], v[4:5], 0, s[12:13]
	s_add_i32 m0, s39, 0x1a000
	s_add_i32 s61, s39, 0x8000
	s_add_i32 s62, s39, 0xa000
	global_load_lds_dwordx4 v[4:5], off
	v_lshl_add_u64 v[2:3], v[2:3], 0, s[12:13]
	s_mov_b32 m0, s61
	s_add_u32 s4, s42, 0x40080
	global_load_lds_dwordx4 v[2:3], off
	v_lshl_add_u64 v[0:1], v[0:1], 0, s[12:13]
	s_mov_b32 m0, s62
	s_addc_u32 s5, s43, 0
	global_load_lds_dwordx4 v[0:1], off
	s_add_i32 m0, s39, 0x1c000
	v_lshl_add_u64 v[0:1], s[4:5], 0, v[130:131]
	global_load_lds_dwordx4 v[0:1], off
	v_lshl_add_u64 v[0:1], s[4:5], 0, v[134:135]
	s_add_i32 m0, s39, 0x1e000
	s_sext_i32_i8 s69, s0
	global_load_lds_dwordx4 v[0:1], off
	v_and_b32_e32 v0, 15, v208
	v_lshlrev_b32_e32 v1, 1, v11
	v_lshlrev_b32_e32 v2, 6, v208
	s_movk_i32 s0, 0x3c0
	v_lshlrev_b32_e32 v3, 2, v208
	v_and_or_b32 v2, v2, s0, v1
	v_and_b32_e32 v3, 32, v3
	v_lshl_or_b32 v146, s1, 6, v0
	v_lshl_or_b32 v0, v0, 6, v1
	v_lshlrev_b32_e32 v1, 8, v208
	v_bitop3_b32 v147, s16, v2, v3 bitop3:0xf6
	v_and_b32_e32 v1, 0x38000, v1
	v_lshlrev_b32_e32 v2, 11, v10
	v_or3_b32 v1, v8, v1, v2
	v_add_u32_e32 v136, v1, v9
	v_lshlrev_b32_e32 v1, 4, v12
	s_waitcnt vmcnt(6)
	v_and_b32_e32 v1, 0x78000, v1
	v_bitop3_b32 v0, v0, s14, v3 bitop3:0xde
	v_or3_b32 v1, v8, v1, v2
	s_add_i32 s63, 0, 0x10000
	s_add_i32 s64, 0, 0x14000
	v_or_b32_e32 v148, s15, v11
	v_mov_b32_e32 v137, v131
	v_add_u32_e32 v138, v1, v9
	v_mov_b32_e32 v139, v131
	v_mov_b64_e32 v[140:141], 0x1800
	v_mov_b64_e32 v[142:143], 0x17ff
	v_add_u32_e32 v149, s63, v147
	v_add_u32_e32 v150, 0, v0
	v_add_u32_e32 v151, s64, v147
	s_mov_b64 s[14:15], 0x100000
	s_mov_b32 s65, 0x100000
	s_mov_b64 s[16:17], 0x120000
	s_mov_b32 s66, 0x120000
	s_mov_b64 s[18:19], 0x140000
	s_mov_b32 s67, 0x140000
	s_mov_b64 s[20:21], 0x160000
	s_mov_b32 s68, 0x160000
	s_cmpk_lt_u32 s46, 0x100
	s_cbranch_scc1 .Lsprio_2
	s_setprio 1

; #define PG8_STAGE(bufoff, gbase, voff) do { _Pragma("unroll") for (int _i = 0; _i < 2; ++_i) \
;         __builtin_amdgcn_global_load_lds((const unsigned*)((const char*)(gbase) + (voff)[_i]), (LAS unsigned*)(lds + (bufoff) + ldsw + _i * 8192), 16, 0, 0); } while (0)
; #define PG8_LDA(dst, b, h) do { _Pragma("unroll") for (int m = 0; m < 4; ++m) _Pragma("unroll") for (int k = 0; k < 2; ++k) dst[m][k] = *(const LAS bf16x8*)(lds + PG8_SA(b, h) + aoff + m * 2048 + k * 1024); } while (0)
; #define PG8_LDB(dst, b, h) do { _Pragma("unroll") for (int n = 0; n < 2; ++n) _Pragma("unroll") for (int k = 0; k < 2; ++k) dst[n][k] = *(const LAS bf16x8*)(lds + PG8_SB(b, h) + boff + n * 2048 + k * 1024); } while (0)
; #define PG8_MMA(ai, bj, At, Bt) do { __builtin_amdgcn_s_setprio(1); _Pragma("unroll") for (int m = 0; m < 4; ++m) _Pragma("unroll") for (int n = 0; n < 2; ++n) _Pragma("unroll") for (int k = 0; k < 2; ++k) \
;         acc[ai][bj][m][n] = __builtin_amdgcn_mfma_f32_16x16x32_bf16(Bt[n][k], At[m][k], acc[ai][bj][m][n], 0, 0, 0); __builtin_amdgcn_s_setprio(0); } while (0)
; #define PG8_WAIT_V(n) asm volatile("s_waitcnt vmcnt(" #n ")" ::: "memory")
; #define PG8_WAIT_L(n) asm volatile("s_waitcnt lgkmcnt(" #n ")" ::: "memory")
; template <class Epi, class Ptrs>
; __device__ __forceinline__ void gemm_phase(LAS unsigned char* lds, const int K, const StaticOrder& S, const Ptrs& P, const Epi& E) {
;     ...
;         for (int t = 0; t < nt; t += 2) {
;             const bool last = (t == nt - 2);
;             const char* a1 = cA + (size_t)(t + 1) * kstep;
;             const char* a2 = last ? nA : cA + (size_t)(t + 2) * kstep; const char* b2 = last ? nB : cB + (size_t)(t + 2) * kstep;
;             const char* a3 = a2 + kstep; const char* b3 = b2 + kstep;
;             PG8_LDB(B0, 0, 0); PG8_SCHED; PG8_LDA(At, 0, 0); PG8_STAGE(PG8_SA(1, 1), a1 + hstep, voffA);
;             PG8_WAIT_L(8); PG8_BAR; PG8_WAIT_L(0); PG8_MMA(0, 0, At, B0); PG8_BAR; PG8_SCHED;
;             PG8_LDB(B1, 0, 1); PG8_STAGE(PG8_SB(0, 0), b2, voffB);
;             PG8_BAR; PG8_WAIT_L(0); PG8_MMA(0, 1, At, B1); PG8_BAR;
;             PG8_LDA(At, 0, 1); PG8_STAGE(PG8_SA(0, 0), a2, voffA);
;             PG8_BAR; PG8_WAIT_L(0); PG8_MMA(1, 0, At, B0); PG8_BAR; PG8_SCHED;
;             PG8_STAGE(PG8_SB(0, 1), b2 + hstep, voffB);
;             PG8_WAIT_V(6); PG8_BAR; PG8_MMA(1, 1, At, B1); PG8_BAR;
.LBB0_432:
	s_add_u32 s40, s40, 0x40080
	s_addc_u32 s41, s41, 0
	s_add_u32 s23, s42, 0x100
	s_addc_u32 s25, s43, 0
	s_mov_b32 s70, -2
	v_add_u32_e32 v252, 0x18000, v147
	v_add_u32_e32 v253, 0x1c000, v147
	ds_read_b128 v[152:155], v149
	ds_read_b128 v[156:159], v149 offset:1024
	ds_read_b128 v[160:163], v149 offset:2048
	ds_read_b128 v[164:167], v149 offset:3072
	s_add_u32 s42, s40, 0xfffc0080
	s_addc_u32 s43, s41, -1
	s_cmp_eq_u32 s70, 12
	s_cselect_b32 s45, s1, s43
	s_cselect_b32 s44, s0, s42
	s_cselect_b32 s43, s37, s25
	s_cselect_b32 s42, s36, s23
	s_add_i32 m0, s39, 0xc000
	ds_read_b128 v[168:171], v150
	ds_read_b128 v[172:175], v150 offset:1024
	ds_read_b128 v[176:179], v150 offset:2048
	ds_read_b128 v[180:183], v150 offset:3072
	ds_read_b128 v[184:187], v150 offset:4096
	ds_read_b128 v[188:191], v150 offset:5120
	ds_read_b128 v[192:195], v150 offset:6144
	ds_read_b128 v[196:199], v150 offset:7168
	global_load_lds_dwordx4 v136, s[40:41]
	s_add_i32 m0, s39, 0xe000
	s_nop 0
	global_load_lds_dwordx4 v138, s[40:41]
	s_waitcnt lgkmcnt(8)
	s_waitcnt lgkmcnt(6)
	v_mfma_f32_16x16x32_bf16 v[124:127], v[152:155], v[168:171], 0
	v_mfma_f32_16x16x32_bf16 v[124:127], v[156:159], v[172:175], v[124:127]
	v_mfma_f32_16x16x32_bf16 v[120:123], v[164:167], v[172:175], 0
	v_mfma_f32_16x16x32_bf16 v[120:123], v[160:163], v[168:171], v[120:123]
	s_barrier
	s_waitcnt lgkmcnt(0)
	v_mfma_f32_16x16x32_bf16 v[104:107], v[160:163], v[176:179], 0
	v_mfma_f32_16x16x32_bf16 v[104:107], v[164:167], v[180:183], v[104:107]
	v_mfma_f32_16x16x32_bf16 v[108:111], v[156:159], v[180:183], 0
	v_mfma_f32_16x16x32_bf16 v[108:111], v[152:155], v[176:179], v[108:111]
	v_mfma_f32_16x16x32_bf16 v[92:95], v[152:155], v[184:187], 0
	v_mfma_f32_16x16x32_bf16 v[92:95], v[156:159], v[188:191], v[92:95]
	v_mfma_f32_16x16x32_bf16 v[88:91], v[164:167], v[188:191], 0
	v_mfma_f32_16x16x32_bf16 v[88:91], v[160:163], v[184:187], v[88:91]
	v_mfma_f32_16x16x32_bf16 v[72:75], v[160:163], v[192:195], 0
	v_mfma_f32_16x16x32_bf16 v[72:75], v[164:167], v[196:199], v[72:75]
	v_mfma_f32_16x16x32_bf16 v[76:79], v[156:159], v[196:199], 0
	v_mfma_f32_16x16x32_bf16 v[76:79], v[152:155], v[192:195], v[76:79]
	s_barrier
	s_add_i32 s71, s63, s51
	s_add_u32 s76, s42, 0x80
	s_addc_u32 s77, s43, 0
	s_mov_b32 m0, s71
	ds_read_b128 v[200:203], v151
	ds_read_b128 v[204:207], v151 offset:1024
	ds_read_b128 v[210:213], v151 offset:2048
	ds_read_b128 v[214:217], v151 offset:3072
	global_load_lds_dwordx4 v130, s[42:43]
	s_add_i32 m0, s71, 0x2000
	s_nop 0
	global_load_lds_dwordx4 v134, s[42:43]
	s_waitcnt lgkmcnt(0)
	v_mfma_f32_16x16x32_bf16 v[116:119], v[200:203], v[168:171], 0
	v_mfma_f32_16x16x32_bf16 v[116:119], v[204:207], v[172:175], v[116:119]
	v_mfma_f32_16x16x32_bf16 v[112:115], v[214:217], v[172:175], 0
	v_mfma_f32_16x16x32_bf16 v[112:115], v[210:213], v[168:171], v[112:115]
	s_barrier
	s_waitcnt lgkmcnt(0)
	v_mfma_f32_16x16x32_bf16 v[96:99], v[210:213], v[176:179], 0
	v_mfma_f32_16x16x32_bf16 v[96:99], v[214:217], v[180:183], v[96:99]
	v_mfma_f32_16x16x32_bf16 v[100:103], v[204:207], v[180:183], 0
	v_mfma_f32_16x16x32_bf16 v[100:103], v[200:203], v[176:179], v[100:103]
	v_mfma_f32_16x16x32_bf16 v[84:87], v[200:203], v[184:187], 0
	v_mfma_f32_16x16x32_bf16 v[84:87], v[204:207], v[188:191], v[84:87]
	v_mfma_f32_16x16x32_bf16 v[80:83], v[214:217], v[188:191], 0
	v_mfma_f32_16x16x32_bf16 v[80:83], v[210:213], v[184:187], v[80:83]
	v_mfma_f32_16x16x32_bf16 v[64:67], v[210:213], v[192:195], 0
	v_mfma_f32_16x16x32_bf16 v[64:67], v[214:217], v[196:199], v[64:67]
	v_mfma_f32_16x16x32_bf16 v[68:71], v[204:207], v[196:199], 0
	v_mfma_f32_16x16x32_bf16 v[68:71], v[200:203], v[192:195], v[68:71]
	s_barrier
	s_mov_b32 m0, s39
	s_add_u32 s78, s44, 0x80
	s_addc_u32 s79, s45, 0
	ds_read_b128 v[168:171], v150 offset:16384
	ds_read_b128 v[172:175], v150 offset:17408
	ds_read_b128 v[176:179], v150 offset:18432
	ds_read_b128 v[180:183], v150 offset:19456
	ds_read_b128 v[184:187], v150 offset:20480
	ds_read_b128 v[188:191], v150 offset:21504
	ds_read_b128 v[192:195], v150 offset:22528
	ds_read_b128 v[196:199], v150 offset:23552
	global_load_lds_dwordx4 v128, s[44:45]
	s_mov_b32 m0, s56
	s_nop 0
	global_load_lds_dwordx4 v132, s[44:45]
	s_waitcnt lgkmcnt(6)
	v_mfma_f32_16x16x32_bf16 v[60:63], v[152:155], v[168:171], 0
	v_mfma_f32_16x16x32_bf16 v[60:63], v[156:159], v[172:175], v[60:63]
	v_mfma_f32_16x16x32_bf16 v[56:59], v[164:167], v[172:175], 0
	v_mfma_f32_16x16x32_bf16 v[56:59], v[160:163], v[168:171], v[56:59]
	s_barrier
	s_waitcnt lgkmcnt(0)
	v_mfma_f32_16x16x32_bf16 v[40:43], v[160:163], v[176:179], 0
	v_mfma_f32_16x16x32_bf16 v[40:43], v[164:167], v[180:183], v[40:43]
	v_mfma_f32_16x16x32_bf16 v[44:47], v[156:159], v[180:183], 0
	v_mfma_f32_16x16x32_bf16 v[44:47], v[152:155], v[176:179], v[44:47]
	v_mfma_f32_16x16x32_bf16 v[28:31], v[152:155], v[184:187], 0
	v_mfma_f32_16x16x32_bf16 v[28:31], v[156:159], v[188:191], v[28:31]
	v_mfma_f32_16x16x32_bf16 v[24:27], v[164:167], v[188:191], 0
	v_mfma_f32_16x16x32_bf16 v[24:27], v[160:163], v[184:187], v[24:27]
	v_mfma_f32_16x16x32_bf16 v[8:11], v[160:163], v[192:195], 0
	v_mfma_f32_16x16x32_bf16 v[8:11], v[164:167], v[196:199], v[8:11]
	v_mfma_f32_16x16x32_bf16 v[12:15], v[156:159], v[196:199], 0
	v_mfma_f32_16x16x32_bf16 v[12:15], v[152:155], v[192:195], v[12:15]
	s_barrier
	s_add_u32 s72, s42, 0x40000
	s_addc_u32 s73, s43, 0
	s_add_i32 s71, s64, s51
	s_mov_b32 m0, s71
	s_nop 0
	global_load_lds_dwordx4 v130, s[72:73]
	s_add_i32 m0, s71, 0x2000
	s_nop 0
	global_load_lds_dwordx4 v134, s[72:73]
	s_waitcnt vmcnt(6)
	v_mfma_f32_16x16x32_bf16 v[52:55], v[200:203], v[168:171], 0
	v_mfma_f32_16x16x32_bf16 v[52:55], v[204:207], v[172:175], v[52:55]
	v_mfma_f32_16x16x32_bf16 v[48:51], v[214:217], v[172:175], 0
	v_mfma_f32_16x16x32_bf16 v[48:51], v[210:213], v[168:171], v[48:51]
	s_barrier
; #define PG8_STAGE(bufoff, gbase, voff) do { _Pragma("unroll") for (int _i = 0; _i < 2; ++_i) \
;         __builtin_amdgcn_global_load_lds((const unsigned*)((const char*)(gbase) + (voff)[_i]), (LAS unsigned*)(lds + (bufoff) + ldsw + _i * 8192), 16, 0, 0); } while (0)
; #define PG8_LDA(dst, b, h) do { _Pragma("unroll") for (int m = 0; m < 4; ++m) _Pragma("unroll") for (int k = 0; k < 2; ++k) dst[m][k] = *(const LAS bf16x8*)(lds + PG8_SA(b, h) + aoff + m * 2048 + k * 1024); } while (0)
; #define PG8_LDB(dst, b, h) do { _Pragma("unroll") for (int n = 0; n < 2; ++n) _Pragma("unroll") for (int k = 0; k < 2; ++k) dst[n][k] = *(const LAS bf16x8*)(lds + PG8_SB(b, h) + boff + n * 2048 + k * 1024); } while (0)
; #define PG8_MMA(ai, bj, At, Bt) do { __builtin_amdgcn_s_setprio(1); _Pragma("unroll") for (int m = 0; m < 4; ++m) _Pragma("unroll") for (int n = 0; n < 2; ++n) _Pragma("unroll") for (int k = 0; k < 2; ++k) \
;         acc[ai][bj][m][n] = __builtin_amdgcn_mfma_f32_16x16x32_bf16(Bt[n][k], At[m][k], acc[ai][bj][m][n], 0, 0, 0); __builtin_amdgcn_s_setprio(0); } while (0)
; #define PG8_WAIT_V(n) asm volatile("s_waitcnt vmcnt(" #n ")" ::: "memory")
; #define PG8_WAIT_L(n) asm volatile("s_waitcnt lgkmcnt(" #n ")" ::: "memory")
; #define PG8_BAR __builtin_amdgcn_s_barrier()
; #define PG8_SCHED __builtin_amdgcn_sched_barrier(0)
; template <class Epi, class Ptrs>
; __device__ __forceinline__ void gemm_phase(LAS unsigned char* lds, const int K, const StaticOrder& S, const Ptrs& P, const Epi& E) {
;     ...
;             PG8_BAR; PG8_WAIT_L(0); PG8_MMA(1, 0, At, B0); PG8_BAR; PG8_SCHED;
;             PG8_STAGE(PG8_SB(0, 1), b2 + hstep, voffB);
;             PG8_WAIT_V(6); PG8_BAR; PG8_MMA(1, 1, At, B1); PG8_BAR;
;             PG8_LDB(B0, 1, 0); PG8_SCHED; PG8_LDA(At, 1, 0); PG8_STAGE(PG8_SA(0, 1), a2 + hstep, voffA);
;             PG8_WAIT_L(8); PG8_BAR; PG8_WAIT_L(0); PG8_MMA(0, 0, At, B0); PG8_BAR; PG8_SCHED;
;             PG8_LDB(B1, 1, 1); PG8_STAGE(PG8_SB(1, 0), b3, voffB);
;             PG8_BAR; PG8_WAIT_L(0); PG8_MMA(0, 1, At, B1); PG8_BAR;
;             PG8_LDA(At, 1, 1); PG8_STAGE(PG8_SA(1, 0), a3, voffA);
;             PG8_BAR; PG8_WAIT_L(0); PG8_MMA(1, 0, At, B0); PG8_BAR; PG8_SCHED;
	v_mfma_f32_16x16x32_bf16 v[32:35], v[210:213], v[176:179], 0
	v_mfma_f32_16x16x32_bf16 v[32:35], v[214:217], v[180:183], v[32:35]
	v_mfma_f32_16x16x32_bf16 v[36:39], v[204:207], v[180:183], 0
	v_mfma_f32_16x16x32_bf16 v[36:39], v[200:203], v[176:179], v[36:39]
	v_mfma_f32_16x16x32_bf16 v[20:23], v[200:203], v[184:187], 0
	v_mfma_f32_16x16x32_bf16 v[20:23], v[204:207], v[188:191], v[20:23]
	v_mfma_f32_16x16x32_bf16 v[16:19], v[214:217], v[188:191], 0
	v_mfma_f32_16x16x32_bf16 v[16:19], v[210:213], v[184:187], v[16:19]
	v_mfma_f32_16x16x32_bf16 v[0:3], v[210:213], v[192:195], 0
	v_mfma_f32_16x16x32_bf16 v[0:3], v[214:217], v[196:199], v[0:3]
	v_mfma_f32_16x16x32_bf16 v[4:7], v[204:207], v[196:199], 0
	v_mfma_f32_16x16x32_bf16 v[4:7], v[200:203], v[192:195], v[4:7]
	s_barrier
	s_add_i32 s71, 0, 0x18000
	ds_read_b128 v[152:155], v252
	ds_read_b128 v[156:159], v252 offset:1024
	ds_read_b128 v[160:163], v252 offset:2048
	ds_read_b128 v[164:167], v252 offset:3072
	s_add_u32 s44, s44, 0x40000
	s_addc_u32 s45, s45, 0
	s_mov_b32 m0, s57
	ds_read_b128 v[168:171], v150 offset:32768
	ds_read_b128 v[172:175], v150 offset:33792
	ds_read_b128 v[176:179], v150 offset:34816
	ds_read_b128 v[180:183], v150 offset:35840
	ds_read_b128 v[184:187], v150 offset:36864
	ds_read_b128 v[188:191], v150 offset:37888
	ds_read_b128 v[192:195], v150 offset:38912
	ds_read_b128 v[196:199], v150 offset:39936
	global_load_lds_dwordx4 v128, s[44:45]
	s_mov_b32 m0, s58
	s_nop 0
	global_load_lds_dwordx4 v132, s[44:45]
	s_waitcnt lgkmcnt(8)
	s_waitcnt lgkmcnt(6)
	v_mfma_f32_16x16x32_bf16 v[124:127], v[152:155], v[168:171], v[124:127]
	v_mfma_f32_16x16x32_bf16 v[124:127], v[156:159], v[172:175], v[124:127]
	v_mfma_f32_16x16x32_bf16 v[120:123], v[164:167], v[172:175], v[120:123]
	v_mfma_f32_16x16x32_bf16 v[120:123], v[160:163], v[168:171], v[120:123]
	s_barrier
	s_waitcnt lgkmcnt(0)
	v_mfma_f32_16x16x32_bf16 v[104:107], v[160:163], v[176:179], v[104:107]
	v_mfma_f32_16x16x32_bf16 v[104:107], v[164:167], v[180:183], v[104:107]
	v_mfma_f32_16x16x32_bf16 v[108:111], v[156:159], v[180:183], v[108:111]
	v_mfma_f32_16x16x32_bf16 v[108:111], v[152:155], v[176:179], v[108:111]
	v_mfma_f32_16x16x32_bf16 v[92:95], v[152:155], v[184:187], v[92:95]
	v_mfma_f32_16x16x32_bf16 v[92:95], v[156:159], v[188:191], v[92:95]
	v_mfma_f32_16x16x32_bf16 v[88:91], v[164:167], v[188:191], v[88:91]
	v_mfma_f32_16x16x32_bf16 v[88:91], v[160:163], v[184:187], v[88:91]
	v_mfma_f32_16x16x32_bf16 v[72:75], v[160:163], v[192:195], v[72:75]
	v_mfma_f32_16x16x32_bf16 v[72:75], v[164:167], v[196:199], v[72:75]
	v_mfma_f32_16x16x32_bf16 v[76:79], v[156:159], v[196:199], v[76:79]
	v_mfma_f32_16x16x32_bf16 v[76:79], v[152:155], v[192:195], v[76:79]
	s_barrier
	s_add_i32 s44, 0, 0x1c000
	s_add_i32 s45, s71, s51
	s_mov_b32 m0, s45
	ds_read_b128 v[200:203], v253
	ds_read_b128 v[204:207], v253 offset:1024
	ds_read_b128 v[210:213], v253 offset:2048
	ds_read_b128 v[214:217], v253 offset:3072
	global_load_lds_dwordx4 v130, s[76:77]
	s_add_i32 m0, s45, 0x2000
	s_nop 0
	global_load_lds_dwordx4 v134, s[76:77]
	s_waitcnt lgkmcnt(0)
	v_mfma_f32_16x16x32_bf16 v[116:119], v[200:203], v[168:171], v[116:119]
	v_mfma_f32_16x16x32_bf16 v[116:119], v[204:207], v[172:175], v[116:119]
	v_mfma_f32_16x16x32_bf16 v[112:115], v[214:217], v[172:175], v[112:115]
	v_mfma_f32_16x16x32_bf16 v[112:115], v[210:213], v[168:171], v[112:115]
	s_barrier
	s_waitcnt lgkmcnt(0)
	v_mfma_f32_16x16x32_bf16 v[96:99], v[210:213], v[176:179], v[96:99]
	v_mfma_f32_16x16x32_bf16 v[96:99], v[214:217], v[180:183], v[96:99]
	v_mfma_f32_16x16x32_bf16 v[100:103], v[204:207], v[180:183], v[100:103]
	v_mfma_f32_16x16x32_bf16 v[100:103], v[200:203], v[176:179], v[100:103]
	v_mfma_f32_16x16x32_bf16 v[84:87], v[200:203], v[184:187], v[84:87]
	v_mfma_f32_16x16x32_bf16 v[84:87], v[204:207], v[188:191], v[84:87]
	v_mfma_f32_16x16x32_bf16 v[80:83], v[214:217], v[188:191], v[80:83]
	v_mfma_f32_16x16x32_bf16 v[80:83], v[210:213], v[184:187], v[80:83]
	v_mfma_f32_16x16x32_bf16 v[64:67], v[210:213], v[192:195], v[64:67]
	v_mfma_f32_16x16x32_bf16 v[64:67], v[214:217], v[196:199], v[64:67]
	v_mfma_f32_16x16x32_bf16 v[68:71], v[204:207], v[196:199], v[68:71]
	v_mfma_f32_16x16x32_bf16 v[68:71], v[200:203], v[192:195], v[68:71]
	s_barrier
	s_mov_b32 m0, s61
	ds_read_b128 v[168:171], v150 offset:49152
	ds_read_b128 v[172:175], v150 offset:50176
	ds_read_b128 v[176:179], v150 offset:51200
	ds_read_b128 v[180:183], v150 offset:52224
	ds_read_b128 v[184:187], v150 offset:53248
	ds_read_b128 v[188:191], v150 offset:54272
	ds_read_b128 v[192:195], v150 offset:55296
	ds_read_b128 v[196:199], v150 offset:56320
	global_load_lds_dwordx4 v128, s[78:79]
	s_mov_b32 m0, s62
	s_nop 0
	global_load_lds_dwordx4 v132, s[78:79]
	s_waitcnt lgkmcnt(6)
	v_mfma_f32_16x16x32_bf16 v[60:63], v[152:155], v[168:171], v[60:63]
	v_mfma_f32_16x16x32_bf16 v[60:63], v[156:159], v[172:175], v[60:63]
	v_mfma_f32_16x16x32_bf16 v[56:59], v[164:167], v[172:175], v[56:59]
	v_mfma_f32_16x16x32_bf16 v[56:59], v[160:163], v[168:171], v[56:59]
	s_barrier
	s_waitcnt lgkmcnt(0)
	v_mfma_f32_16x16x32_bf16 v[40:43], v[160:163], v[176:179], v[40:43]
	v_mfma_f32_16x16x32_bf16 v[40:43], v[164:167], v[180:183], v[40:43]
	v_mfma_f32_16x16x32_bf16 v[44:47], v[156:159], v[180:183], v[44:47]
	v_mfma_f32_16x16x32_bf16 v[44:47], v[152:155], v[176:179], v[44:47]
	v_mfma_f32_16x16x32_bf16 v[28:31], v[152:155], v[184:187], v[28:31]
	v_mfma_f32_16x16x32_bf16 v[28:31], v[156:159], v[188:191], v[28:31]
	v_mfma_f32_16x16x32_bf16 v[24:27], v[164:167], v[188:191], v[24:27]
	v_mfma_f32_16x16x32_bf16 v[24:27], v[160:163], v[184:187], v[24:27]
	v_mfma_f32_16x16x32_bf16 v[8:11], v[160:163], v[192:195], v[8:11]
	v_mfma_f32_16x16x32_bf16 v[8:11], v[164:167], v[196:199], v[8:11]
	v_mfma_f32_16x16x32_bf16 v[12:15], v[156:159], v[196:199], v[12:15]
	v_mfma_f32_16x16x32_bf16 v[12:15], v[152:155], v[192:195], v[12:15]
	s_barrier
; #define PG8_STAGE(bufoff, gbase, voff) do { _Pragma("unroll") for (int _i = 0; _i < 2; ++_i) \
;         __builtin_amdgcn_global_load_lds((const unsigned*)((const char*)(gbase) + (voff)[_i]), (LAS unsigned*)(lds + (bufoff) + ldsw + _i * 8192), 16, 0, 0); } while (0)
; #define PG8_LDA(dst, b, h) do { _Pragma("unroll") for (int m = 0; m < 4; ++m) _Pragma("unroll") for (int k = 0; k < 2; ++k) dst[m][k] = *(const LAS bf16x8*)(lds + PG8_SA(b, h) + aoff + m * 2048 + k * 1024); } while (0)
; #define PG8_LDB(dst, b, h) do { _Pragma("unroll") for (int n = 0; n < 2; ++n) _Pragma("unroll") for (int k = 0; k < 2; ++k) dst[n][k] = *(const LAS bf16x8*)(lds + PG8_SB(b, h) + boff + n * 2048 + k * 1024); } while (0)
; #define PG8_MMA(ai, bj, At, Bt) do { __builtin_amdgcn_s_setprio(1); _Pragma("unroll") for (int m = 0; m < 4; ++m) _Pragma("unroll") for (int n = 0; n < 2; ++n) _Pragma("unroll") for (int k = 0; k < 2; ++k) \
;         acc[ai][bj][m][n] = __builtin_amdgcn_mfma_f32_16x16x32_bf16(Bt[n][k], At[m][k], acc[ai][bj][m][n], 0, 0, 0); __builtin_amdgcn_s_setprio(0); } while (0)
; #define PG8_WAIT_V(n) asm volatile("s_waitcnt vmcnt(" #n ")" ::: "memory")
; template <class Epi, class Ptrs>
; __device__ __forceinline__ void gemm_phase(LAS unsigned char* lds, const int K, const StaticOrder& S, const Ptrs& P, const Epi& E) {
;     ...
;         for (int t = 0; t < nt; t += 2) {
;             const bool last = (t == nt - 2);
;             const char* a1 = cA + (size_t)(t + 1) * kstep;
;             const char* a2 = last ? nA : cA + (size_t)(t + 2) * kstep; const char* b2 = last ? nB : cB + (size_t)(t + 2) * kstep;
;             const char* a3 = a2 + kstep; const char* b3 = b2 + kstep;
;             PG8_LDB(B0, 0, 0); PG8_SCHED; PG8_LDA(At, 0, 0); PG8_STAGE(PG8_SA(1, 1), a1 + hstep, voffA);
;             PG8_WAIT_L(8); PG8_BAR; PG8_WAIT_L(0); PG8_MMA(0, 0, At, B0); PG8_BAR; PG8_SCHED;
;             PG8_LDB(B1, 0, 1); PG8_STAGE(PG8_SB(0, 0), b2, voffB);
;             PG8_BAR; PG8_WAIT_L(0); PG8_MMA(0, 1, At, B1); PG8_BAR;
;             PG8_LDA(At, 0, 1); PG8_STAGE(PG8_SA(0, 0), a2, voffA);
;             PG8_BAR; PG8_WAIT_L(0); PG8_MMA(1, 0, At, B0); PG8_BAR; PG8_SCHED;
;     ...
;             PG8_BAR; PG8_WAIT_L(0); PG8_MMA(1, 0, At, B0); PG8_BAR; PG8_SCHED;
;             PG8_STAGE(PG8_SB(1, 1), b3 + hstep, voffB);
;             PG8_WAIT_V(6); PG8_BAR; PG8_MMA(1, 1, At, B1); PG8_BAR;
	s_add_u32 s42, s42, 0x40080
	s_addc_u32 s43, s43, 0
	s_add_i32 s44, s44, s51
	s_mov_b32 m0, s44
	s_nop 0
	global_load_lds_dwordx4 v130, s[42:43]
	s_add_i32 m0, s44, 0x2000
	s_nop 0
	global_load_lds_dwordx4 v134, s[42:43]
	s_waitcnt vmcnt(6)
	v_mfma_f32_16x16x32_bf16 v[52:55], v[200:203], v[168:171], v[52:55]
	v_mfma_f32_16x16x32_bf16 v[52:55], v[204:207], v[172:175], v[52:55]
	v_mfma_f32_16x16x32_bf16 v[48:51], v[214:217], v[172:175], v[48:51]
	v_mfma_f32_16x16x32_bf16 v[48:51], v[210:213], v[168:171], v[48:51]
	s_barrier
	v_mfma_f32_16x16x32_bf16 v[32:35], v[210:213], v[176:179], v[32:35]
	v_mfma_f32_16x16x32_bf16 v[32:35], v[214:217], v[180:183], v[32:35]
	v_mfma_f32_16x16x32_bf16 v[36:39], v[204:207], v[180:183], v[36:39]
	v_mfma_f32_16x16x32_bf16 v[36:39], v[200:203], v[176:179], v[36:39]
	v_mfma_f32_16x16x32_bf16 v[20:23], v[200:203], v[184:187], v[20:23]
	v_mfma_f32_16x16x32_bf16 v[20:23], v[204:207], v[188:191], v[20:23]
	v_mfma_f32_16x16x32_bf16 v[16:19], v[214:217], v[188:191], v[16:19]
	v_mfma_f32_16x16x32_bf16 v[16:19], v[210:213], v[184:187], v[16:19]
	v_mfma_f32_16x16x32_bf16 v[0:3], v[210:213], v[192:195], v[0:3]
	v_mfma_f32_16x16x32_bf16 v[0:3], v[214:217], v[196:199], v[0:3]
	v_mfma_f32_16x16x32_bf16 v[4:7], v[204:207], v[196:199], v[4:7]
	v_mfma_f32_16x16x32_bf16 v[4:7], v[200:203], v[192:195], v[4:7]
	s_barrier
	s_add_i32 s70, s70, 2
	s_add_u32 s40, s40, 0x100
	s_addc_u32 s41, s41, 0
	s_add_u32 s23, s23, 0x100
	s_addc_u32 s25, s25, 0
	s_cmp_gt_u32 s70, 13
.LBB0_433:
	ds_read_b128 v[152:155], v149
	ds_read_b128 v[156:159], v149 offset:1024
	ds_read_b128 v[160:163], v149 offset:2048
	ds_read_b128 v[164:167], v149 offset:3072
	s_add_u32 s42, s40, 0xfffc0080
	s_addc_u32 s43, s41, -1
	s_cmp_eq_u32 s70, 12
	s_cselect_b32 s45, s1, s43
	s_cselect_b32 s44, s0, s42
	s_cselect_b32 s43, s37, s25
	s_cselect_b32 s42, s36, s23
	s_add_i32 m0, s39, 0xc000
	ds_read_b128 v[168:171], v150
	ds_read_b128 v[172:175], v150 offset:1024
	ds_read_b128 v[176:179], v150 offset:2048
	ds_read_b128 v[180:183], v150 offset:3072
	ds_read_b128 v[184:187], v150 offset:4096
	ds_read_b128 v[188:191], v150 offset:5120
	ds_read_b128 v[192:195], v150 offset:6144
	ds_read_b128 v[196:199], v150 offset:7168
	global_load_lds_dwordx4 v136, s[40:41]
	s_add_i32 m0, s39, 0xe000
	s_nop 0
	global_load_lds_dwordx4 v138, s[40:41]
	s_waitcnt lgkmcnt(8)
	s_waitcnt lgkmcnt(6)
	v_mfma_f32_16x16x32_bf16 v[124:127], v[152:155], v[168:171], v[124:127]
	v_mfma_f32_16x16x32_bf16 v[124:127], v[156:159], v[172:175], v[124:127]
	v_mfma_f32_16x16x32_bf16 v[120:123], v[164:167], v[172:175], v[120:123]
	v_mfma_f32_16x16x32_bf16 v[120:123], v[160:163], v[168:171], v[120:123]
	s_barrier
	s_waitcnt lgkmcnt(0)
	v_mfma_f32_16x16x32_bf16 v[104:107], v[160:163], v[176:179], v[104:107]
	v_mfma_f32_16x16x32_bf16 v[104:107], v[164:167], v[180:183], v[104:107]
	v_mfma_f32_16x16x32_bf16 v[108:111], v[156:159], v[180:183], v[108:111]
	v_mfma_f32_16x16x32_bf16 v[108:111], v[152:155], v[176:179], v[108:111]
	v_mfma_f32_16x16x32_bf16 v[92:95], v[152:155], v[184:187], v[92:95]
	v_mfma_f32_16x16x32_bf16 v[92:95], v[156:159], v[188:191], v[92:95]
	v_mfma_f32_16x16x32_bf16 v[88:91], v[164:167], v[188:191], v[88:91]
	v_mfma_f32_16x16x32_bf16 v[88:91], v[160:163], v[184:187], v[88:91]
	v_mfma_f32_16x16x32_bf16 v[72:75], v[160:163], v[192:195], v[72:75]
	v_mfma_f32_16x16x32_bf16 v[72:75], v[164:167], v[196:199], v[72:75]
	v_mfma_f32_16x16x32_bf16 v[76:79], v[156:159], v[196:199], v[76:79]
	v_mfma_f32_16x16x32_bf16 v[76:79], v[152:155], v[192:195], v[76:79]
	s_barrier
	s_add_i32 s71, s63, s51
	s_add_u32 s76, s42, 0x80
	s_addc_u32 s77, s43, 0
	s_mov_b32 m0, s71
	ds_read_b128 v[200:203], v151
	ds_read_b128 v[204:207], v151 offset:1024
	ds_read_b128 v[210:213], v151 offset:2048
	ds_read_b128 v[214:217], v151 offset:3072
	global_load_lds_dwordx4 v130, s[42:43]
	s_add_i32 m0, s71, 0x2000
	s_nop 0
	global_load_lds_dwordx4 v134, s[42:43]
	s_waitcnt lgkmcnt(0)
	v_mfma_f32_16x16x32_bf16 v[116:119], v[200:203], v[168:171], v[116:119]
	v_mfma_f32_16x16x32_bf16 v[116:119], v[204:207], v[172:175], v[116:119]
	v_mfma_f32_16x16x32_bf16 v[112:115], v[214:217], v[172:175], v[112:115]
	v_mfma_f32_16x16x32_bf16 v[112:115], v[210:213], v[168:171], v[112:115]
	s_barrier
	s_waitcnt lgkmcnt(0)
	v_mfma_f32_16x16x32_bf16 v[96:99], v[210:213], v[176:179], v[96:99]
	v_mfma_f32_16x16x32_bf16 v[96:99], v[214:217], v[180:183], v[96:99]
	v_mfma_f32_16x16x32_bf16 v[100:103], v[204:207], v[180:183], v[100:103]
	v_mfma_f32_16x16x32_bf16 v[100:103], v[200:203], v[176:179], v[100:103]
	v_mfma_f32_16x16x32_bf16 v[84:87], v[200:203], v[184:187], v[84:87]
	v_mfma_f32_16x16x32_bf16 v[84:87], v[204:207], v[188:191], v[84:87]
	v_mfma_f32_16x16x32_bf16 v[80:83], v[214:217], v[188:191], v[80:83]
	v_mfma_f32_16x16x32_bf16 v[80:83], v[210:213], v[184:187], v[80:83]
	v_mfma_f32_16x16x32_bf16 v[64:67], v[210:213], v[192:195], v[64:67]
	v_mfma_f32_16x16x32_bf16 v[64:67], v[214:217], v[196:199], v[64:67]
	v_mfma_f32_16x16x32_bf16 v[68:71], v[204:207], v[196:199], v[68:71]
	v_mfma_f32_16x16x32_bf16 v[68:71], v[200:203], v[192:195], v[68:71]
	s_barrier
	s_mov_b32 m0, s39
	s_add_u32 s78, s44, 0x80
	s_addc_u32 s79, s45, 0
	ds_read_b128 v[168:171], v150 offset:16384
	ds_read_b128 v[172:175], v150 offset:17408
	ds_read_b128 v[176:179], v150 offset:18432
	ds_read_b128 v[180:183], v150 offset:19456
	ds_read_b128 v[184:187], v150 offset:20480
	ds_read_b128 v[188:191], v150 offset:21504
	ds_read_b128 v[192:195], v150 offset:22528
	ds_read_b128 v[196:199], v150 offset:23552
	global_load_lds_dwordx4 v128, s[44:45]
	s_mov_b32 m0, s56
	s_nop 0
	global_load_lds_dwordx4 v132, s[44:45]
	s_waitcnt lgkmcnt(6)
	v_mfma_f32_16x16x32_bf16 v[60:63], v[152:155], v[168:171], v[60:63]
	v_mfma_f32_16x16x32_bf16 v[60:63], v[156:159], v[172:175], v[60:63]
	v_mfma_f32_16x16x32_bf16 v[56:59], v[164:167], v[172:175], v[56:59]
	v_mfma_f32_16x16x32_bf16 v[56:59], v[160:163], v[168:171], v[56:59]
	s_barrier
; #define PG8_STAGE(bufoff, gbase, voff) do { _Pragma("unroll") for (int _i = 0; _i < 2; ++_i) \
;         __builtin_amdgcn_global_load_lds((const unsigned*)((const char*)(gbase) + (voff)[_i]), (LAS unsigned*)(lds + (bufoff) + ldsw + _i * 8192), 16, 0, 0); } while (0)
; #define PG8_LDA(dst, b, h) do { _Pragma("unroll") for (int m = 0; m < 4; ++m) _Pragma("unroll") for (int k = 0; k < 2; ++k) dst[m][k] = *(const LAS bf16x8*)(lds + PG8_SA(b, h) + aoff + m * 2048 + k * 1024); } while (0)
; #define PG8_LDB(dst, b, h) do { _Pragma("unroll") for (int n = 0; n < 2; ++n) _Pragma("unroll") for (int k = 0; k < 2; ++k) dst[n][k] = *(const LAS bf16x8*)(lds + PG8_SB(b, h) + boff + n * 2048 + k * 1024); } while (0)
; #define PG8_MMA(ai, bj, At, Bt) do { __builtin_amdgcn_s_setprio(1); _Pragma("unroll") for (int m = 0; m < 4; ++m) _Pragma("unroll") for (int n = 0; n < 2; ++n) _Pragma("unroll") for (int k = 0; k < 2; ++k) \
;         acc[ai][bj][m][n] = __builtin_amdgcn_mfma_f32_16x16x32_bf16(Bt[n][k], At[m][k], acc[ai][bj][m][n], 0, 0, 0); __builtin_amdgcn_s_setprio(0); } while (0)
; #define PG8_WAIT_V(n) asm volatile("s_waitcnt vmcnt(" #n ")" ::: "memory")
; #define PG8_WAIT_L(n) asm volatile("s_waitcnt lgkmcnt(" #n ")" ::: "memory")
; #define PG8_BAR __builtin_amdgcn_s_barrier()
; #define PG8_SCHED __builtin_amdgcn_sched_barrier(0)
; template <class Epi, class Ptrs>
; __device__ __forceinline__ void gemm_phase(LAS unsigned char* lds, const int K, const StaticOrder& S, const Ptrs& P, const Epi& E) {
;     ...
;             PG8_BAR; PG8_WAIT_L(0); PG8_MMA(1, 0, At, B0); PG8_BAR; PG8_SCHED;
;             PG8_STAGE(PG8_SB(0, 1), b2 + hstep, voffB);
;             PG8_WAIT_V(6); PG8_BAR; PG8_MMA(1, 1, At, B1); PG8_BAR;
;             PG8_LDB(B0, 1, 0); PG8_SCHED; PG8_LDA(At, 1, 0); PG8_STAGE(PG8_SA(0, 1), a2 + hstep, voffA);
;             PG8_WAIT_L(8); PG8_BAR; PG8_WAIT_L(0); PG8_MMA(0, 0, At, B0); PG8_BAR; PG8_SCHED;
;             PG8_LDB(B1, 1, 1); PG8_STAGE(PG8_SB(1, 0), b3, voffB);
;             PG8_BAR; PG8_WAIT_L(0); PG8_MMA(0, 1, At, B1); PG8_BAR;
	s_waitcnt lgkmcnt(0)
	v_mfma_f32_16x16x32_bf16 v[40:43], v[160:163], v[176:179], v[40:43]
	v_mfma_f32_16x16x32_bf16 v[40:43], v[164:167], v[180:183], v[40:43]
	v_mfma_f32_16x16x32_bf16 v[44:47], v[156:159], v[180:183], v[44:47]
	v_mfma_f32_16x16x32_bf16 v[44:47], v[152:155], v[176:179], v[44:47]
	v_mfma_f32_16x16x32_bf16 v[28:31], v[152:155], v[184:187], v[28:31]
	v_mfma_f32_16x16x32_bf16 v[28:31], v[156:159], v[188:191], v[28:31]
	v_mfma_f32_16x16x32_bf16 v[24:27], v[164:167], v[188:191], v[24:27]
	v_mfma_f32_16x16x32_bf16 v[24:27], v[160:163], v[184:187], v[24:27]
	v_mfma_f32_16x16x32_bf16 v[8:11], v[160:163], v[192:195], v[8:11]
	v_mfma_f32_16x16x32_bf16 v[8:11], v[164:167], v[196:199], v[8:11]
	v_mfma_f32_16x16x32_bf16 v[12:15], v[156:159], v[196:199], v[12:15]
	v_mfma_f32_16x16x32_bf16 v[12:15], v[152:155], v[192:195], v[12:15]
	s_barrier
	s_add_u32 s72, s42, 0x40000
	s_addc_u32 s73, s43, 0
	s_add_i32 s71, s64, s51
	s_mov_b32 m0, s71
	s_nop 0
	global_load_lds_dwordx4 v130, s[72:73]
	s_add_i32 m0, s71, 0x2000
	s_nop 0
	global_load_lds_dwordx4 v134, s[72:73]
	s_waitcnt vmcnt(6)
	v_mfma_f32_16x16x32_bf16 v[52:55], v[200:203], v[168:171], v[52:55]
	v_mfma_f32_16x16x32_bf16 v[52:55], v[204:207], v[172:175], v[52:55]
	v_mfma_f32_16x16x32_bf16 v[48:51], v[214:217], v[172:175], v[48:51]
	v_mfma_f32_16x16x32_bf16 v[48:51], v[210:213], v[168:171], v[48:51]
	s_barrier
	v_mfma_f32_16x16x32_bf16 v[32:35], v[210:213], v[176:179], v[32:35]
	v_mfma_f32_16x16x32_bf16 v[32:35], v[214:217], v[180:183], v[32:35]
	v_mfma_f32_16x16x32_bf16 v[36:39], v[204:207], v[180:183], v[36:39]
	v_mfma_f32_16x16x32_bf16 v[36:39], v[200:203], v[176:179], v[36:39]
	v_mfma_f32_16x16x32_bf16 v[20:23], v[200:203], v[184:187], v[20:23]
	v_mfma_f32_16x16x32_bf16 v[20:23], v[204:207], v[188:191], v[20:23]
	v_mfma_f32_16x16x32_bf16 v[16:19], v[214:217], v[188:191], v[16:19]
	v_mfma_f32_16x16x32_bf16 v[16:19], v[210:213], v[184:187], v[16:19]
	v_mfma_f32_16x16x32_bf16 v[0:3], v[210:213], v[192:195], v[0:3]
	v_mfma_f32_16x16x32_bf16 v[0:3], v[214:217], v[196:199], v[0:3]
	v_mfma_f32_16x16x32_bf16 v[4:7], v[204:207], v[196:199], v[4:7]
	v_mfma_f32_16x16x32_bf16 v[4:7], v[200:203], v[192:195], v[4:7]
	s_barrier
	s_add_i32 s71, 0, 0x18000
	ds_read_b128 v[152:155], v252
	ds_read_b128 v[156:159], v252 offset:1024
	ds_read_b128 v[160:163], v252 offset:2048
	ds_read_b128 v[164:167], v252 offset:3072
	s_add_u32 s44, s44, 0x40000
	s_addc_u32 s45, s45, 0
	s_mov_b32 m0, s57
	ds_read_b128 v[168:171], v150 offset:32768
	ds_read_b128 v[172:175], v150 offset:33792
	ds_read_b128 v[176:179], v150 offset:34816
	ds_read_b128 v[180:183], v150 offset:35840
	ds_read_b128 v[184:187], v150 offset:36864
	ds_read_b128 v[188:191], v150 offset:37888
	ds_read_b128 v[192:195], v150 offset:38912
	ds_read_b128 v[196:199], v150 offset:39936
	global_load_lds_dwordx4 v128, s[44:45]
	s_mov_b32 m0, s58
	s_nop 0
	global_load_lds_dwordx4 v132, s[44:45]
	s_waitcnt lgkmcnt(8)
	s_waitcnt lgkmcnt(6)
	v_mfma_f32_16x16x32_bf16 v[124:127], v[152:155], v[168:171], v[124:127]
	v_mfma_f32_16x16x32_bf16 v[124:127], v[156:159], v[172:175], v[124:127]
	v_mfma_f32_16x16x32_bf16 v[120:123], v[164:167], v[172:175], v[120:123]
	v_mfma_f32_16x16x32_bf16 v[120:123], v[160:163], v[168:171], v[120:123]
	s_barrier
	s_waitcnt lgkmcnt(0)
	v_mfma_f32_16x16x32_bf16 v[104:107], v[160:163], v[176:179], v[104:107]
	v_mfma_f32_16x16x32_bf16 v[104:107], v[164:167], v[180:183], v[104:107]
	v_mfma_f32_16x16x32_bf16 v[108:111], v[156:159], v[180:183], v[108:111]
	v_mfma_f32_16x16x32_bf16 v[108:111], v[152:155], v[176:179], v[108:111]
	v_mfma_f32_16x16x32_bf16 v[92:95], v[152:155], v[184:187], v[92:95]
	v_mfma_f32_16x16x32_bf16 v[92:95], v[156:159], v[188:191], v[92:95]
	v_mfma_f32_16x16x32_bf16 v[88:91], v[164:167], v[188:191], v[88:91]
	v_mfma_f32_16x16x32_bf16 v[88:91], v[160:163], v[184:187], v[88:91]
	v_mfma_f32_16x16x32_bf16 v[72:75], v[160:163], v[192:195], v[72:75]
	v_mfma_f32_16x16x32_bf16 v[72:75], v[164:167], v[196:199], v[72:75]
	v_mfma_f32_16x16x32_bf16 v[76:79], v[156:159], v[196:199], v[76:79]
	v_mfma_f32_16x16x32_bf16 v[76:79], v[152:155], v[192:195], v[76:79]
	s_barrier
	s_add_i32 s44, 0, 0x1c000
	s_add_i32 s45, s71, s51
	s_mov_b32 m0, s45
	ds_read_b128 v[200:203], v253
	ds_read_b128 v[204:207], v253 offset:1024
	ds_read_b128 v[210:213], v253 offset:2048
	ds_read_b128 v[214:217], v253 offset:3072
	global_load_lds_dwordx4 v130, s[76:77]
	s_add_i32 m0, s45, 0x2000
	s_nop 0
	global_load_lds_dwordx4 v134, s[76:77]
	s_waitcnt lgkmcnt(0)
	v_mfma_f32_16x16x32_bf16 v[116:119], v[200:203], v[168:171], v[116:119]
	v_mfma_f32_16x16x32_bf16 v[116:119], v[204:207], v[172:175], v[116:119]
	v_mfma_f32_16x16x32_bf16 v[112:115], v[214:217], v[172:175], v[112:115]
	v_mfma_f32_16x16x32_bf16 v[112:115], v[210:213], v[168:171], v[112:115]
	s_barrier
	s_waitcnt lgkmcnt(0)
	v_mfma_f32_16x16x32_bf16 v[96:99], v[210:213], v[176:179], v[96:99]
	v_mfma_f32_16x16x32_bf16 v[96:99], v[214:217], v[180:183], v[96:99]
	v_mfma_f32_16x16x32_bf16 v[100:103], v[204:207], v[180:183], v[100:103]
	v_mfma_f32_16x16x32_bf16 v[100:103], v[200:203], v[176:179], v[100:103]
	v_mfma_f32_16x16x32_bf16 v[84:87], v[200:203], v[184:187], v[84:87]
	v_mfma_f32_16x16x32_bf16 v[84:87], v[204:207], v[188:191], v[84:87]
	v_mfma_f32_16x16x32_bf16 v[80:83], v[214:217], v[188:191], v[80:83]
	v_mfma_f32_16x16x32_bf16 v[80:83], v[210:213], v[184:187], v[80:83]
	v_mfma_f32_16x16x32_bf16 v[64:67], v[210:213], v[192:195], v[64:67]
	v_mfma_f32_16x16x32_bf16 v[64:67], v[214:217], v[196:199], v[64:67]
	v_mfma_f32_16x16x32_bf16 v[68:71], v[204:207], v[196:199], v[68:71]
	v_mfma_f32_16x16x32_bf16 v[68:71], v[200:203], v[192:195], v[68:71]
	s_barrier
; __device__ __forceinline__ unsigned cvt_pk_bf16(float lo, float hi) { unsigned r; asm volatile("v_cvt_pk_bf16_f32 %0, %1, %2" : "=v"(r) : "v"(lo), "v"(hi)); return r; }
; #define PG8_STAGE(bufoff, gbase, voff) do { _Pragma("unroll") for (int _i = 0; _i < 2; ++_i) \
;         __builtin_amdgcn_global_load_lds((const unsigned*)((const char*)(gbase) + (voff)[_i]), (LAS unsigned*)(lds + (bufoff) + ldsw + _i * 8192), 16, 0, 0); } while (0)
; #define PG8_LDA(dst, b, h) do { _Pragma("unroll") for (int m = 0; m < 4; ++m) _Pragma("unroll") for (int k = 0; k < 2; ++k) dst[m][k] = *(const LAS bf16x8*)(lds + PG8_SA(b, h) + aoff + m * 2048 + k * 1024); } while (0)
; #define PG8_WAIT_V(n) asm volatile("s_waitcnt vmcnt(" #n ")" ::: "memory")
; #define PG8_WAIT_L(n) asm volatile("s_waitcnt lgkmcnt(" #n ")" ::: "memory")
; #define PG8_BAR __builtin_amdgcn_s_barrier()
; #define PG8_SCHED __builtin_amdgcn_sched_barrier(0)
; template <class Epi, class Ptrs>
; __device__ __forceinline__ void gemm_phase(LAS unsigned char* lds, const int K, const StaticOrder& S, const Ptrs& P, const Epi& E) {
;     ...
;             PG8_BAR; PG8_WAIT_L(0); PG8_MMA(0, 1, At, B1); PG8_BAR;
;             PG8_LDA(At, 1, 1); PG8_STAGE(PG8_SA(1, 0), a3, voffA);
;             PG8_BAR; PG8_WAIT_L(0); PG8_MMA(1, 0, At, B0); PG8_BAR; PG8_SCHED;
;             PG8_STAGE(PG8_SB(1, 1), b3 + hstep, voffB);
;             PG8_WAIT_V(6); PG8_BAR; PG8_MMA(1, 1, At, B1); PG8_BAR;
;     __device__ __forceinline__ void operator()(const f32x4 (&acc)[2][2][4][2], const Unit& u, int ui, int wr, int wc, int fr, int fq) const {
;         const int row0 = u.pm * 256 + wr * 64 + fr, col0 = u.pn * 256 + wc * 32 + 8 * fq;
; #pragma unroll
;         for (int ai = 0; ai < 2; ++ai)
; #pragma unroll
;             for (int m = 0; m < 4; ++m) { bf16_t* rowp = hid + (size_t)(row0 + ai * 128 + m * 16) * DFF + col0;
; #pragma unroll
;                 for (int bj = 0; bj < 2; ++bj) { f32x4 v0 = acc[ai][bj][m][0], v1 = acc[ai][bj][m][1];
; #pragma unroll
;                     for (int j = 0; j < 4; ++j) { const float a = fmaxf(v0[j], 0.f), b = fmaxf(v1[j], 0.f); v0[j] = a * a; v1[j] = b * b; }
;                     u32x4 w; w.x = cvt_pk_bf16(v0[0], v0[1]); w.y = cvt_pk_bf16(v0[2], v0[3]); w.z = cvt_pk_bf16(v1[0], v1[1]); w.w = cvt_pk_bf16(v1[2], v1[3]);
;                     *(u32x4*)(rowp + bj * 128) = w; } }
	s_mov_b32 m0, s61
	ds_read_b128 v[168:171], v150 offset:49152
	ds_read_b128 v[172:175], v150 offset:50176
	ds_read_b128 v[176:179], v150 offset:51200
	ds_read_b128 v[180:183], v150 offset:52224
	ds_read_b128 v[184:187], v150 offset:53248
	ds_read_b128 v[188:191], v150 offset:54272
	ds_read_b128 v[192:195], v150 offset:55296
	ds_read_b128 v[196:199], v150 offset:56320
	global_load_lds_dwordx4 v128, s[78:79]
	s_mov_b32 m0, s62
	s_nop 0
	global_load_lds_dwordx4 v132, s[78:79]
	s_waitcnt lgkmcnt(6)
	v_mfma_f32_16x16x32_bf16 v[60:63], v[152:155], v[168:171], v[60:63]
	v_mfma_f32_16x16x32_bf16 v[60:63], v[156:159], v[172:175], v[60:63]
	v_mfma_f32_16x16x32_bf16 v[56:59], v[164:167], v[172:175], v[56:59]
	v_mfma_f32_16x16x32_bf16 v[56:59], v[160:163], v[168:171], v[56:59]
	s_barrier
	s_waitcnt lgkmcnt(0)
	v_mfma_f32_16x16x32_bf16 v[40:43], v[160:163], v[176:179], v[40:43]
	v_mfma_f32_16x16x32_bf16 v[40:43], v[164:167], v[180:183], v[40:43]
	v_mfma_f32_16x16x32_bf16 v[44:47], v[156:159], v[180:183], v[44:47]
	v_mfma_f32_16x16x32_bf16 v[44:47], v[152:155], v[176:179], v[44:47]
	v_mfma_f32_16x16x32_bf16 v[28:31], v[152:155], v[184:187], v[28:31]
	v_mfma_f32_16x16x32_bf16 v[28:31], v[156:159], v[188:191], v[28:31]
	v_mfma_f32_16x16x32_bf16 v[24:27], v[164:167], v[188:191], v[24:27]
	v_mfma_f32_16x16x32_bf16 v[24:27], v[160:163], v[184:187], v[24:27]
	v_mfma_f32_16x16x32_bf16 v[8:11], v[160:163], v[192:195], v[8:11]
	v_mfma_f32_16x16x32_bf16 v[8:11], v[164:167], v[196:199], v[8:11]
	v_mfma_f32_16x16x32_bf16 v[12:15], v[156:159], v[196:199], v[12:15]
	v_mfma_f32_16x16x32_bf16 v[12:15], v[152:155], v[192:195], v[12:15]
	s_barrier
	s_add_u32 s42, s42, 0x40080
	s_addc_u32 s43, s43, 0
	s_add_i32 s44, s44, s51
	s_mov_b32 m0, s44
	s_nop 0
	global_load_lds_dwordx4 v130, s[42:43]
	s_add_i32 m0, s44, 0x2000
	s_nop 0
	global_load_lds_dwordx4 v134, s[42:43]
	s_waitcnt vmcnt(6)
	v_mfma_f32_16x16x32_bf16 v[52:55], v[200:203], v[168:171], v[52:55]
	v_mfma_f32_16x16x32_bf16 v[52:55], v[204:207], v[172:175], v[52:55]
	v_mfma_f32_16x16x32_bf16 v[48:51], v[214:217], v[172:175], v[48:51]
	v_mfma_f32_16x16x32_bf16 v[48:51], v[210:213], v[168:171], v[48:51]
	s_barrier
	v_mfma_f32_16x16x32_bf16 v[32:35], v[210:213], v[176:179], v[32:35]
	v_mfma_f32_16x16x32_bf16 v[32:35], v[214:217], v[180:183], v[32:35]
	v_mfma_f32_16x16x32_bf16 v[36:39], v[204:207], v[180:183], v[36:39]
	v_mfma_f32_16x16x32_bf16 v[36:39], v[200:203], v[176:179], v[36:39]
	v_mfma_f32_16x16x32_bf16 v[20:23], v[200:203], v[184:187], v[20:23]
	v_mfma_f32_16x16x32_bf16 v[20:23], v[204:207], v[188:191], v[20:23]
	v_mfma_f32_16x16x32_bf16 v[16:19], v[214:217], v[188:191], v[16:19]
	v_mfma_f32_16x16x32_bf16 v[16:19], v[210:213], v[184:187], v[16:19]
	v_mfma_f32_16x16x32_bf16 v[0:3], v[210:213], v[192:195], v[0:3]
	v_mfma_f32_16x16x32_bf16 v[0:3], v[214:217], v[196:199], v[0:3]
	v_mfma_f32_16x16x32_bf16 v[4:7], v[204:207], v[196:199], v[4:7]
	v_mfma_f32_16x16x32_bf16 v[4:7], v[200:203], v[192:195], v[4:7]
	s_barrier
	s_add_i32 s70, s70, 2
	s_add_u32 s40, s40, 0x100
	s_addc_u32 s41, s41, 0
	s_add_u32 s23, s23, 0x100
	s_addc_u32 s25, s25, 0
	s_cmp_gt_u32 s70, 13
	s_cbranch_scc0 .LBB0_433
	v_lshl_add_u32 v152, s38, 8, v146
	v_max_f32_e32 v120, 0, v120
	v_ashrrev_i32_e32 v153, 31, v152
	v_max_f32_e32 v121, 0, v121
	v_max_f32_e32 v122, 0, v122
	v_lshl_or_b32 v144, s69, 8, v148
	v_lshlrev_b64 v[154:155], 13, v[152:153]
	v_mul_f32_e32 v153, v120, v120
	v_max_f32_e32 v120, 0, v125
	v_ashrrev_i32_e32 v145, 31, v144
	v_max_f32_e32 v124, 0, v124
	v_mul_f32_e32 v125, v121, v121
	v_max_f32_e32 v121, 0, v126
	v_mul_f32_e32 v126, v122, v122
	v_max_f32_e32 v122, 0, v127
	v_max_f32_e32 v123, 0, v123
	v_lshl_add_u64 v[154:155], s[10:11], 0, v[154:155]
	v_lshlrev_b64 v[156:157], 1, v[144:145]
	v_mul_f32_e32 v120, v120, v120
	v_max_f32_e32 v112, 0, v112
	v_lshl_add_u64 v[144:145], v[154:155], 0, v[156:157]
	v_mul_f32_e32 v124, v124, v124
	v_mul_f32_e32 v121, v121, v121
	v_mul_f32_e32 v122, v122, v122
	v_mul_f32_e32 v123, v123, v123
	v_cvt_pk_bf16_f32 v120, v124, v120
	v_max_f32_e32 v113, 0, v113
	v_max_f32_e32 v114, 0, v114
	v_cvt_pk_bf16_f32 v121, v121, v122
	v_cvt_pk_bf16_f32 v122, v153, v125
	v_cvt_pk_bf16_f32 v123, v126, v123
	global_store_dwordx4 v[144:145], v[120:123], off
	s_nop 1
	v_mul_f32_e32 v120, v112, v112
	v_max_f32_e32 v112, 0, v117
	v_max_f32_e32 v116, 0, v116
	v_mul_f32_e32 v117, v113, v113
	v_max_f32_e32 v113, 0, v118
	v_mul_f32_e32 v118, v114, v114
	v_max_f32_e32 v114, 0, v119
	v_max_f32_e32 v115, 0, v115
	v_mul_f32_e32 v112, v112, v112
	v_mul_f32_e32 v116, v116, v116
	v_mul_f32_e32 v113, v113, v113
	v_mul_f32_e32 v114, v114, v114
	v_mul_f32_e32 v115, v115, v115
	v_cvt_pk_bf16_f32 v112, v116, v112
	v_max_f32_e32 v104, 0, v104
	v_cvt_pk_bf16_f32 v113, v113, v114
	v_cvt_pk_bf16_f32 v114, v120, v117
	v_cvt_pk_bf16_f32 v115, v118, v115
	global_store_dwordx4 v[144:145], v[112:115], off offset:256
	s_nop 0
	v_max_f32_e32 v105, 0, v105
	v_or_b32_e32 v112, 16, v152
	v_max_f32_e32 v106, 0, v106
	v_ashrrev_i32_e32 v113, 31, v112
	v_mul_f32_e32 v114, v104, v104
	v_max_f32_e32 v104, 0, v109
	v_lshlrev_b64 v[112:113], 13, v[112:113]
	v_max_f32_e32 v108, 0, v108
	v_mul_f32_e32 v109, v105, v105
	v_max_f32_e32 v105, 0, v110
	v_mul_f32_e32 v110, v106, v106
	v_max_f32_e32 v106, 0, v111
	v_max_f32_e32 v107, 0, v107
	v_lshl_add_u64 v[112:113], s[10:11], 0, v[112:113]
	v_mul_f32_e32 v104, v104, v104
	v_max_f32_e32 v96, 0, v96
	v_lshl_add_u64 v[112:113], v[112:113], 0, v[156:157]
	v_mul_f32_e32 v108, v108, v108
	v_mul_f32_e32 v105, v105, v105
	v_mul_f32_e32 v106, v106, v106
	v_mul_f32_e32 v107, v107, v107
	v_cvt_pk_bf16_f32 v104, v108, v104
; __device__ __forceinline__ unsigned cvt_pk_bf16(float lo, float hi) { unsigned r; asm volatile("v_cvt_pk_bf16_f32 %0, %1, %2" : "=v"(r) : "v"(lo), "v"(hi)); return r; }
;     __device__ __forceinline__ void operator()(const f32x4 (&acc)[2][2][4][2], const Unit& u, int ui, int wr, int wc, int fr, int fq) const {
;     ...
;         for (int ai = 0; ai < 2; ++ai)
; #pragma unroll
;             for (int m = 0; m < 4; ++m) { bf16_t* rowp = hid + (size_t)(row0 + ai * 128 + m * 16) * DFF + col0;
; #pragma unroll
;                 for (int bj = 0; bj < 2; ++bj) { f32x4 v0 = acc[ai][bj][m][0], v1 = acc[ai][bj][m][1];
; #pragma unroll
;                     for (int j = 0; j < 4; ++j) { const float a = fmaxf(v0[j], 0.f), b = fmaxf(v1[j], 0.f); v0[j] = a * a; v1[j] = b * b; }
;                     u32x4 w; w.x = cvt_pk_bf16(v0[0], v0[1]); w.y = cvt_pk_bf16(v0[2], v0[3]); w.z = cvt_pk_bf16(v1[0], v1[1]); w.w = cvt_pk_bf16(v1[2], v1[3]);
;                     *(u32x4*)(rowp + bj * 128) = w; } }
	v_max_f32_e32 v97, 0, v97
	v_max_f32_e32 v98, 0, v98
	v_cvt_pk_bf16_f32 v105, v105, v106
	v_cvt_pk_bf16_f32 v106, v114, v109
	v_cvt_pk_bf16_f32 v107, v110, v107
	global_store_dwordx4 v[112:113], v[104:107], off
	s_nop 1
	v_mul_f32_e32 v104, v96, v96
	v_max_f32_e32 v96, 0, v101
	v_max_f32_e32 v100, 0, v100
	v_mul_f32_e32 v101, v97, v97
	v_max_f32_e32 v97, 0, v102
	v_mul_f32_e32 v102, v98, v98
	v_max_f32_e32 v98, 0, v103
	v_max_f32_e32 v99, 0, v99
	v_mul_f32_e32 v96, v96, v96
	v_mul_f32_e32 v100, v100, v100
	v_mul_f32_e32 v97, v97, v97
	v_mul_f32_e32 v98, v98, v98
	v_mul_f32_e32 v99, v99, v99
	v_cvt_pk_bf16_f32 v96, v100, v96
	v_max_f32_e32 v88, 0, v88
	v_cvt_pk_bf16_f32 v97, v97, v98
	v_cvt_pk_bf16_f32 v98, v104, v101
	v_cvt_pk_bf16_f32 v99, v102, v99
	global_store_dwordx4 v[112:113], v[96:99], off offset:256
	s_nop 0
	v_max_f32_e32 v89, 0, v89
	v_or_b32_e32 v96, 32, v152
	v_max_f32_e32 v90, 0, v90
	v_ashrrev_i32_e32 v97, 31, v96
	v_mul_f32_e32 v98, v88, v88
	v_max_f32_e32 v88, 0, v93
	v_lshlrev_b64 v[96:97], 13, v[96:97]
	v_max_f32_e32 v92, 0, v92
	v_mul_f32_e32 v93, v89, v89
	v_max_f32_e32 v89, 0, v94
	v_mul_f32_e32 v94, v90, v90
	v_max_f32_e32 v90, 0, v95
	v_max_f32_e32 v91, 0, v91
	v_lshl_add_u64 v[96:97], s[10:11], 0, v[96:97]
	v_mul_f32_e32 v88, v88, v88
	v_max_f32_e32 v80, 0, v80
	v_lshl_add_u64 v[96:97], v[96:97], 0, v[156:157]
	v_mul_f32_e32 v92, v92, v92
	v_mul_f32_e32 v89, v89, v89
	v_mul_f32_e32 v90, v90, v90
	v_mul_f32_e32 v91, v91, v91
	v_cvt_pk_bf16_f32 v88, v92, v88
	v_max_f32_e32 v81, 0, v81
	v_max_f32_e32 v82, 0, v82
	v_cvt_pk_bf16_f32 v89, v89, v90
	v_cvt_pk_bf16_f32 v90, v98, v93
	v_cvt_pk_bf16_f32 v91, v94, v91
	global_store_dwordx4 v[96:97], v[88:91], off
	s_nop 1
	v_mul_f32_e32 v88, v80, v80
	v_max_f32_e32 v80, 0, v85
	v_max_f32_e32 v84, 0, v84
	v_mul_f32_e32 v85, v81, v81
	v_max_f32_e32 v81, 0, v86
	v_mul_f32_e32 v86, v82, v82
	v_max_f32_e32 v82, 0, v87
	v_max_f32_e32 v83, 0, v83
	v_mul_f32_e32 v80, v80, v80
	v_mul_f32_e32 v84, v84, v84
	v_mul_f32_e32 v81, v81, v81
	v_mul_f32_e32 v82, v82, v82
	v_mul_f32_e32 v83, v83, v83
	v_cvt_pk_bf16_f32 v80, v84, v80
	v_max_f32_e32 v72, 0, v72
	v_cvt_pk_bf16_f32 v81, v81, v82
	v_cvt_pk_bf16_f32 v82, v88, v85
	v_cvt_pk_bf16_f32 v83, v86, v83
	global_store_dwordx4 v[96:97], v[80:83], off offset:256
	s_nop 0
	v_max_f32_e32 v73, 0, v73
	v_or_b32_e32 v80, 48, v152
	v_max_f32_e32 v74, 0, v74
	v_ashrrev_i32_e32 v81, 31, v80
	v_mul_f32_e32 v82, v72, v72
	v_max_f32_e32 v72, 0, v77
	v_lshlrev_b64 v[80:81], 13, v[80:81]
	v_max_f32_e32 v76, 0, v76
	v_mul_f32_e32 v77, v73, v73
	v_max_f32_e32 v73, 0, v78
	v_mul_f32_e32 v78, v74, v74
	v_max_f32_e32 v74, 0, v79
	v_max_f32_e32 v75, 0, v75
	v_lshl_add_u64 v[80:81], s[10:11], 0, v[80:81]
	v_mul_f32_e32 v72, v72, v72
	v_max_f32_e32 v64, 0, v64
	v_max_f32_e32 v65, 0, v65
	v_max_f32_e32 v66, 0, v66
	v_lshl_add_u64 v[80:81], v[80:81], 0, v[156:157]
	v_mul_f32_e32 v76, v76, v76
	v_mul_f32_e32 v73, v73, v73
	v_mul_f32_e32 v74, v74, v74
	v_mul_f32_e32 v75, v75, v75
	v_cvt_pk_bf16_f32 v72, v76, v72
	v_cvt_pk_bf16_f32 v73, v73, v74
	v_cvt_pk_bf16_f32 v74, v82, v77
	v_cvt_pk_bf16_f32 v75, v78, v75
	global_store_dwordx4 v[80:81], v[72:75], off
	v_max_f32_e32 v68, 0, v68
	v_max_f32_e32 v67, 0, v67
	v_mul_f32_e32 v72, v64, v64
	v_max_f32_e32 v64, 0, v69
	v_mul_f32_e32 v69, v65, v65
	v_max_f32_e32 v65, 0, v70
	v_mul_f32_e32 v70, v66, v66
	v_max_f32_e32 v66, 0, v71
	v_mul_f32_e32 v64, v64, v64
	v_mul_f32_e32 v65, v65, v65
	v_mul_f32_e32 v66, v66, v66
	v_max_f32_e32 v56, 0, v56
	v_mul_f32_e32 v68, v68, v68
	v_mul_f32_e32 v67, v67, v67
	v_cvt_pk_bf16_f32 v64, v68, v64
	v_cvt_pk_bf16_f32 v65, v65, v66
	v_cvt_pk_bf16_f32 v66, v72, v69
	v_max_f32_e32 v57, 0, v57
	v_max_f32_e32 v58, 0, v58
	v_cvt_pk_bf16_f32 v67, v70, v67
	global_store_dwordx4 v[80:81], v[64:67], off offset:256
	s_nop 0
	v_max_f32_e32 v60, 0, v60
	v_mul_f32_e32 v66, v56, v56
	v_max_f32_e32 v56, 0, v61
	v_mul_f32_e32 v61, v57, v57
	v_max_f32_e32 v57, 0, v62
	v_mul_f32_e32 v62, v58, v58
	v_max_f32_e32 v58, 0, v63
	v_mul_f32_e32 v60, v60, v60
	v_mul_f32_e32 v56, v56, v56
	v_max_f32_e32 v59, 0, v59
	v_mul_f32_e32 v57, v57, v57
	v_mul_f32_e32 v58, v58, v58
	v_cvt_pk_bf16_f32 v56, v60, v56
	v_add_co_u32_e32 v60, vcc, s65, v144
	v_max_f32_e32 v48, 0, v48
	v_max_f32_e32 v49, 0, v49
	v_max_f32_e32 v50, 0, v50
	v_mul_f32_e32 v59, v59, v59
	v_cvt_pk_bf16_f32 v57, v57, v58
	v_cvt_pk_bf16_f32 v58, v66, v61
	v_addc_co_u32_e32 v61, vcc, 0, v145, vcc
	v_cvt_pk_bf16_f32 v59, v62, v59
	global_store_dwordx4 v[60:61], v[56:59], off
	v_max_f32_e32 v52, 0, v52
	v_max_f32_e32 v51, 0, v51
	v_mul_f32_e32 v56, v48, v48
	v_max_f32_e32 v48, 0, v53
	v_mul_f32_e32 v53, v49, v49
	v_max_f32_e32 v49, 0, v54
	v_mul_f32_e32 v54, v50, v50
	v_max_f32_e32 v50, 0, v55
; __device__ __forceinline__ unsigned cvt_pk_bf16(float lo, float hi) { unsigned r; asm volatile("v_cvt_pk_bf16_f32 %0, %1, %2" : "=v"(r) : "v"(lo), "v"(hi)); return r; }
; #define PG8_WAIT_V(n) asm volatile("s_waitcnt vmcnt(" #n ")" ::: "memory")
; #define PG8_BAR __builtin_amdgcn_s_barrier()
; template <class Epi, class Ptrs>
; __device__ __forceinline__ void gemm_phase(LAS unsigned char* lds, const int K, const StaticOrder& S, const Ptrs& P, const Epi& E) {
;     ...
;         E(acc, cur, ui, wr, wc, fr, fq);
;         if (!has_next) break;
; #pragma unroll
;         for (int a = 0; a < 2; ++a)
; #pragma unroll
;             for (int b = 0; b < 2; ++b)
; #pragma unroll
;                 for (int m = 0; m < 4; ++m)
; #pragma unroll
;                     for (int n = 0; n < 2; ++n) acc[a][b][m][n] = (f32x4){0.f, 0.f, 0.f, 0.f};
;         cur = nxt; cA = nA; cB = nB; ++ui;
;     }
;     PG8_WAIT_V(0);
;     if (wr == 0) PG8_BAR;
;     PG8_BAR;
;     __device__ __forceinline__ void operator()(const f32x4 (&acc)[2][2][4][2], const Unit& u, int ui, int wr, int wc, int fr, int fq) const {
;     ...
;         for (int ai = 0; ai < 2; ++ai)
; #pragma unroll
;             for (int m = 0; m < 4; ++m) { bf16_t* rowp = hid + (size_t)(row0 + ai * 128 + m * 16) * DFF + col0;
; #pragma unroll
;                 for (int bj = 0; bj < 2; ++bj) { f32x4 v0 = acc[ai][bj][m][0], v1 = acc[ai][bj][m][1];
; #pragma unroll
;                     for (int j = 0; j < 4; ++j) { const float a = fmaxf(v0[j], 0.f), b = fmaxf(v1[j], 0.f); v0[j] = a * a; v1[j] = b * b; }
;                     u32x4 w; w.x = cvt_pk_bf16(v0[0], v0[1]); w.y = cvt_pk_bf16(v0[2], v0[3]); w.z = cvt_pk_bf16(v1[0], v1[1]); w.w = cvt_pk_bf16(v1[2], v1[3]);
;                     *(u32x4*)(rowp + bj * 128) = w; } }
	v_mul_f32_e32 v48, v48, v48
	v_mul_f32_e32 v49, v49, v49
	v_mul_f32_e32 v50, v50, v50
	v_max_f32_e32 v40, 0, v40
	v_lshl_add_u64 v[64:65], v[144:145], 0, s[14:15]
	v_mul_f32_e32 v52, v52, v52
	v_mul_f32_e32 v51, v51, v51
	v_cvt_pk_bf16_f32 v48, v52, v48
	v_cvt_pk_bf16_f32 v49, v49, v50
	v_cvt_pk_bf16_f32 v50, v56, v53
	v_max_f32_e32 v41, 0, v41
	v_max_f32_e32 v42, 0, v42
	v_cvt_pk_bf16_f32 v51, v54, v51
	global_store_dwordx4 v[64:65], v[48:51], off offset:256
	s_nop 0
	v_max_f32_e32 v44, 0, v44
	v_mul_f32_e32 v50, v40, v40
	v_max_f32_e32 v40, 0, v45
	v_mul_f32_e32 v45, v41, v41
	v_max_f32_e32 v41, 0, v46
	v_mul_f32_e32 v46, v42, v42
	v_max_f32_e32 v42, 0, v47
	v_mul_f32_e32 v44, v44, v44
	v_mul_f32_e32 v40, v40, v40
	v_max_f32_e32 v43, 0, v43
	v_mul_f32_e32 v41, v41, v41
	v_mul_f32_e32 v42, v42, v42
	v_cvt_pk_bf16_f32 v40, v44, v40
	v_add_co_u32_e32 v44, vcc, s66, v144
	v_max_f32_e32 v32, 0, v32
	v_max_f32_e32 v33, 0, v33
	v_max_f32_e32 v34, 0, v34
	v_mul_f32_e32 v43, v43, v43
	v_cvt_pk_bf16_f32 v41, v41, v42
	v_cvt_pk_bf16_f32 v42, v50, v45
	v_addc_co_u32_e32 v45, vcc, 0, v145, vcc
	v_cvt_pk_bf16_f32 v43, v46, v43
	global_store_dwordx4 v[44:45], v[40:43], off
	v_max_f32_e32 v36, 0, v36
	v_max_f32_e32 v35, 0, v35
	v_mul_f32_e32 v40, v32, v32
	v_max_f32_e32 v32, 0, v37
	v_mul_f32_e32 v37, v33, v33
	v_max_f32_e32 v33, 0, v38
	v_mul_f32_e32 v38, v34, v34
	v_max_f32_e32 v34, 0, v39
	v_mul_f32_e32 v32, v32, v32
	v_mul_f32_e32 v33, v33, v33
	v_mul_f32_e32 v34, v34, v34
	v_max_f32_e32 v24, 0, v24
	v_lshl_add_u64 v[48:49], v[144:145], 0, s[16:17]
	v_mul_f32_e32 v36, v36, v36
	v_mul_f32_e32 v35, v35, v35
	v_cvt_pk_bf16_f32 v32, v36, v32
	v_cvt_pk_bf16_f32 v33, v33, v34
	v_cvt_pk_bf16_f32 v34, v40, v37
	v_max_f32_e32 v25, 0, v25
	v_max_f32_e32 v26, 0, v26
	v_cvt_pk_bf16_f32 v35, v38, v35
	global_store_dwordx4 v[48:49], v[32:35], off offset:256
	s_nop 0
	v_max_f32_e32 v28, 0, v28
	v_mul_f32_e32 v34, v24, v24
	v_max_f32_e32 v24, 0, v29
	v_mul_f32_e32 v29, v25, v25
	v_max_f32_e32 v25, 0, v30
	v_mul_f32_e32 v30, v26, v26
	v_max_f32_e32 v26, 0, v31
	v_mul_f32_e32 v28, v28, v28
	v_mul_f32_e32 v24, v24, v24
	v_max_f32_e32 v27, 0, v27
	v_mul_f32_e32 v25, v25, v25
	v_mul_f32_e32 v26, v26, v26
	v_cvt_pk_bf16_f32 v24, v28, v24
	v_add_co_u32_e32 v28, vcc, s67, v144
	v_max_f32_e32 v16, 0, v16
	v_max_f32_e32 v17, 0, v17
	v_max_f32_e32 v18, 0, v18
	v_mul_f32_e32 v27, v27, v27
	v_cvt_pk_bf16_f32 v25, v25, v26
	v_cvt_pk_bf16_f32 v26, v34, v29
	v_addc_co_u32_e32 v29, vcc, 0, v145, vcc
	v_cvt_pk_bf16_f32 v27, v30, v27
	global_store_dwordx4 v[28:29], v[24:27], off
	v_max_f32_e32 v20, 0, v20
	v_max_f32_e32 v19, 0, v19
	v_mul_f32_e32 v24, v16, v16
	v_max_f32_e32 v16, 0, v21
	v_mul_f32_e32 v21, v17, v17
	v_max_f32_e32 v17, 0, v22
	v_mul_f32_e32 v22, v18, v18
	v_max_f32_e32 v18, 0, v23
	v_mul_f32_e32 v16, v16, v16
	v_mul_f32_e32 v17, v17, v17
	v_mul_f32_e32 v18, v18, v18
	v_max_f32_e32 v8, 0, v8
	v_lshl_add_u64 v[32:33], v[144:145], 0, s[18:19]
	v_mul_f32_e32 v20, v20, v20
	v_mul_f32_e32 v19, v19, v19
	v_cvt_pk_bf16_f32 v16, v20, v16
	v_cvt_pk_bf16_f32 v17, v17, v18
	v_cvt_pk_bf16_f32 v18, v24, v21
	v_max_f32_e32 v9, 0, v9
	v_max_f32_e32 v10, 0, v10
	v_cvt_pk_bf16_f32 v19, v22, v19
	global_store_dwordx4 v[32:33], v[16:19], off offset:256
	s_nop 0
	v_max_f32_e32 v12, 0, v12
	v_mul_f32_e32 v18, v8, v8
	v_max_f32_e32 v8, 0, v13
	v_mul_f32_e32 v13, v9, v9
	v_max_f32_e32 v9, 0, v14
	v_mul_f32_e32 v14, v10, v10
	v_max_f32_e32 v10, 0, v15
	v_mul_f32_e32 v12, v12, v12
	v_mul_f32_e32 v8, v8, v8
	v_max_f32_e32 v11, 0, v11
	v_mul_f32_e32 v9, v9, v9
	v_mul_f32_e32 v10, v10, v10
	v_cvt_pk_bf16_f32 v8, v12, v8
	v_add_co_u32_e32 v12, vcc, s68, v144
	v_max_f32_e32 v0, 0, v0
	v_max_f32_e32 v1, 0, v1
	v_max_f32_e32 v2, 0, v2
	v_mul_f32_e32 v11, v11, v11
	v_cvt_pk_bf16_f32 v9, v9, v10
	v_cvt_pk_bf16_f32 v10, v18, v13
	v_addc_co_u32_e32 v13, vcc, 0, v145, vcc
	v_cvt_pk_bf16_f32 v11, v14, v11
	global_store_dwordx4 v[12:13], v[8:11], off
	v_max_f32_e32 v3, 0, v3
	v_max_f32_e32 v4, 0, v4
	v_mul_f32_e32 v8, v0, v0
	v_max_f32_e32 v0, 0, v5
	v_mul_f32_e32 v5, v1, v1
	v_max_f32_e32 v1, 0, v6
	v_mul_f32_e32 v6, v2, v2
	v_max_f32_e32 v2, 0, v7
	v_lshl_add_u64 v[16:17], v[144:145], 0, s[20:21]
	v_mul_f32_e32 v0, v0, v0
	v_mul_f32_e32 v1, v1, v1
	v_mul_f32_e32 v2, v2, v2
	v_mul_f32_e32 v3, v3, v3
	s_and_b64 vcc, exec, s[4:5]
	s_mov_b32 s69, s22
	s_mov_b32 s38, s24
	s_mov_b64 s[40:41], s[0:1]
	s_mov_b64 s[42:43], s[36:37]
	v_mul_f32_e32 v4, v4, v4
	v_cvt_pk_bf16_f32 v0, v4, v0
	v_cvt_pk_bf16_f32 v1, v1, v2
	v_cvt_pk_bf16_f32 v2, v8, v5
	v_cvt_pk_bf16_f32 v3, v6, v3
	global_store_dwordx4 v[16:17], v[0:3], off offset:256
	s_cbranch_vccz .LBB0_428
	s_waitcnt vmcnt(0)
	s_setprio 0
	s_cmpk_gt_u32 s46, 0xff
	s_cbranch_scc1 .LBB0_437
	s_barrier

; #define PG8_STAGE(bufoff, gbase, voff) do { _Pragma("unroll") for (int _i = 0; _i < 2; ++_i) \
;         __builtin_amdgcn_global_load_lds((const unsigned*)((const char*)(gbase) + (voff)[_i]), (LAS unsigned*)(lds + (bufoff) + ldsw + _i * 8192), 16, 0, 0); } while (0)
; #define PG8_WAIT_V(n) asm volatile("s_waitcnt vmcnt(" #n ")" ::: "memory")
; #define PG8_BAR __builtin_amdgcn_s_barrier()
; template <class Epi, class Ptrs>
; __device__ __forceinline__ void gemm_phase(LAS unsigned char* lds, const int K, const StaticOrder& S, const Ptrs& P, const Epi& E) {
;     ...
;     for (int i = 0; i < 2; ++i) { int R, C; stage_rc(tid * 16 + i * 8192, R, C); const int Rb = (R & ~31) + perm32(R & 31);
;         voffA[i] = (unsigned)(R * K + C) * 2u; voffB[i] = (unsigned)(Rb * K + C) * 2u; }
;     const size_t kstep = (size_t)(BK * 2);
;     const size_t hstep = (size_t)HALF * K * 2;
;     const unsigned ldsw = (unsigned)wid * 1024u;
;     const int aoff = lds_byte(wr * 64 + fr, fq * 8), boff = lds_byte(wc * 32 + fr, fq * 8);
;     ...
;     Unit cur, nxt; int ui = 0;
;     if (!S.next(0, cur)) return;
;     f32x4 acc[2][2][4][2];
; #pragma unroll
;     for (int a = 0; a < 2; ++a)
; #pragma unroll
;         for (int b = 0; b < 2; ++b)
; #pragma unroll
;             for (int m = 0; m < 4; ++m)
; #pragma unroll
;                 for (int n = 0; n < 2; ++n) acc[a][b][m][n] = (f32x4){0.f, 0.f, 0.f, 0.f};
;     bf16x8 At[4][2], B0[2][2], B1[2][2];
;     const char* cA; const char* cB; P.get(cur, cA, cB);
;     PG8_STAGE(PG8_SB(0, 0), cB, voffB); PG8_STAGE(PG8_SA(0, 0), cA, voffA); PG8_STAGE(PG8_SB(0, 1), cB + hstep, voffB); PG8_STAGE(PG8_SA(0, 1), cA + hstep, voffA);
;     if (wr == 1) PG8_BAR;
;     PG8_WAIT_V(4); PG8_BAR;
;     PG8_STAGE(PG8_SB(1, 0), cB + kstep, voffB); PG8_STAGE(PG8_SA(1, 0), cA + kstep, voffA); PG8_STAGE(PG8_SB(1, 1), cB + hstep + kstep, voffB);
;     PG8_WAIT_V(6); PG8_BAR;
.LBB0_516:
	s_lshl_b32 s1, s1, 5
	s_and_b32 s1, s1, 0x60
	s_lshl_b32 s10, s0, 13
	s_lshl_b32 s11, s1, 7
	s_add_u32 s6, s28, 0x2000000
	s_mov_b64 s[8:9], 0x80
	s_addc_u32 s7, s29, 0
	s_add_i32 m0, s17, 0x18000
	v_lshl_add_u64 v[6:7], v[6:7], 0, s[8:9]
	s_waitcnt vmcnt(4)
	s_barrier
	global_load_lds_dwordx4 v[6:7], off
	v_lshl_add_u64 v[4:5], v[4:5], 0, s[8:9]
	s_add_i32 m0, s17, 0x1a000
	s_add_i32 s28, s17, 0x8000
	s_add_i32 s29, s17, 0xa000
	global_load_lds_dwordx4 v[4:5], off
	v_lshl_add_u64 v[2:3], v[2:3], 0, s[8:9]
	s_mov_b32 m0, s28
	s_add_u32 s4, s22, 0x100080
	global_load_lds_dwordx4 v[2:3], off
	v_lshl_add_u64 v[0:1], v[0:1], 0, s[8:9]
	s_mov_b32 m0, s29
	s_addc_u32 s5, s23, 0
	global_load_lds_dwordx4 v[0:1], off
	s_add_i32 m0, s17, 0x1c000
	v_lshl_add_u64 v[0:1], s[4:5], 0, v[162:163]
	global_load_lds_dwordx4 v[0:1], off
	v_lshl_add_u64 v[0:1], s[4:5], 0, v[166:167]
	s_add_i32 m0, s17, 0x1e000
	v_lshlrev_b32_e32 v2, 6, v208
	global_load_lds_dwordx4 v[0:1], off
	v_and_b32_e32 v0, 15, v208
	v_lshlrev_b32_e32 v1, 1, v11
	s_movk_i32 s4, 0x3c0
	v_lshl_or_b32 v186, s0, 6, v0
	v_and_or_b32 v2, v2, s4, v1
	v_lshlrev_b32_e32 v3, 2, v208
	v_lshl_or_b32 v0, v0, 6, v1
	v_lshlrev_b32_e32 v1, 2, v186
	s_add_i32 s0, 0, 0x20000
	v_and_b32_e32 v3, 32, v3
	v_and_b32_e32 v4, 32, v1
	v_add_u32_e32 v192, s0, v1
	v_lshlrev_b32_e32 v1, 10, v208
	v_bitop3_b32 v187, s11, v2, v3 bitop3:0xf6
	v_and_b32_e32 v1, 0xe0000, v1
	v_lshlrev_b32_e32 v2, 13, v10
	v_or3_b32 v1, v8, v1, v2
	v_add_u32_e32 v168, v1, v9
	v_lshlrev_b32_e32 v1, 6, v12
	s_waitcnt vmcnt(6)
	v_and_b32_e32 v1, 0x1e0000, v1
	v_bitop3_b32 v0, v0, s10, v4 bitop3:0xde
	v_or3_b32 v1, v8, v1, v2
	s_add_i32 s42, 0, 0x10000
	s_add_i32 s43, 0, 0x14000
	v_or_b32_e32 v188, 16, v186
	v_or_b32_e32 v189, 32, v186
	v_or_b32_e32 v190, 48, v186
	v_or_b32_e32 v191, s1, v11
	v_mov_b32_e32 v169, v163
	v_add_u32_e32 v170, v1, v9
	v_mov_b32_e32 v171, v163
	v_mov_b64_e32 v[172:173], 0x600
	v_mov_b64_e32 v[174:175], 0x5ff
	v_add_u32_e32 v193, s42, v187
	v_add_u32_e32 v194, 0, v0
	s_nop 0
	s_nop 0
	s_nop 0
	s_nop 0
	s_nop 0
	s_nop 0
	s_nop 0
	s_nop 0
	s_nop 0
	s_nop 0
	s_nop 0
	s_nop 0
	s_nop 0
	s_nop 0
	s_nop 0
	s_nop 0
	s_nop 0
	s_nop 0
	s_nop 0
	s_nop 0
	s_nop 0
	s_nop 0
	s_nop 0
	s_nop 0
	s_nop 0
	s_nop 0
	s_nop 0
	s_nop 0
	s_nop 0
	s_nop 0
	s_nop 0
	s_nop 0
	s_nop 0
	s_nop 0
	s_nop 0
	s_nop 0
	s_nop 0
	s_nop 0
	s_nop 0
	s_nop 0
	s_nop 0
	s_nop 0
	s_nop 0
	s_nop 0
	s_nop 0
	s_nop 0
	s_nop 0
	s_nop 0
	s_nop 0
	v_add_u32_e32 v195, s43, v187
	s_cmpk_lt_u32 s33, 0x100
	s_cbranch_scc1 .Lsprio_3
	s_setprio 1

; #define PG8_STAGE(bufoff, gbase, voff) do { _Pragma("unroll") for (int _i = 0; _i < 2; ++_i) \
;         __builtin_amdgcn_global_load_lds((const unsigned*)((const char*)(gbase) + (voff)[_i]), (LAS unsigned*)(lds + (bufoff) + ldsw + _i * 8192), 16, 0, 0); } while (0)
; #define PG8_LDA(dst, b, h) do { _Pragma("unroll") for (int m = 0; m < 4; ++m) _Pragma("unroll") for (int k = 0; k < 2; ++k) dst[m][k] = *(const LAS bf16x8*)(lds + PG8_SA(b, h) + aoff + m * 2048 + k * 1024); } while (0)
; #define PG8_LDB(dst, b, h) do { _Pragma("unroll") for (int n = 0; n < 2; ++n) _Pragma("unroll") for (int k = 0; k < 2; ++k) dst[n][k] = *(const LAS bf16x8*)(lds + PG8_SB(b, h) + boff + n * 2048 + k * 1024); } while (0)
; #define PG8_MMA(ai, bj, At, Bt) do { __builtin_amdgcn_s_setprio(1); _Pragma("unroll") for (int m = 0; m < 4; ++m) _Pragma("unroll") for (int n = 0; n < 2; ++n) _Pragma("unroll") for (int k = 0; k < 2; ++k) \
;         acc[ai][bj][m][n] = __builtin_amdgcn_mfma_f32_16x16x32_bf16(Bt[n][k], At[m][k], acc[ai][bj][m][n], 0, 0, 0); __builtin_amdgcn_s_setprio(0); } while (0)
; #define PG8_WAIT_V(n) asm volatile("s_waitcnt vmcnt(" #n ")" ::: "memory")
; #define PG8_WAIT_L(n) asm volatile("s_waitcnt lgkmcnt(" #n ")" ::: "memory")
; template <class Epi, class Ptrs>
; __device__ __forceinline__ void gemm_phase(LAS unsigned char* lds, const int K, const StaticOrder& S, const Ptrs& P, const Epi& E) {
;     ...
;         for (int t = 0; t < nt; t += 2) {
;             const bool last = (t == nt - 2);
;             const char* a1 = cA + (size_t)(t + 1) * kstep;
;             const char* a2 = last ? nA : cA + (size_t)(t + 2) * kstep; const char* b2 = last ? nB : cB + (size_t)(t + 2) * kstep;
;             const char* a3 = a2 + kstep; const char* b3 = b2 + kstep;
;             PG8_LDB(B0, 0, 0); PG8_SCHED; PG8_LDA(At, 0, 0); PG8_STAGE(PG8_SA(1, 1), a1 + hstep, voffA);
;             PG8_WAIT_L(8); PG8_BAR; PG8_WAIT_L(0); PG8_MMA(0, 0, At, B0); PG8_BAR; PG8_SCHED;
;             PG8_LDB(B1, 0, 1); PG8_STAGE(PG8_SB(0, 0), b2, voffB);
;             PG8_BAR; PG8_WAIT_L(0); PG8_MMA(0, 1, At, B1); PG8_BAR;
;             PG8_LDA(At, 0, 1); PG8_STAGE(PG8_SA(0, 0), a2, voffA);
;             PG8_BAR; PG8_WAIT_L(0); PG8_MMA(1, 0, At, B0); PG8_BAR; PG8_SCHED;
;             PG8_STAGE(PG8_SB(0, 1), b2 + hstep, voffB);
;             PG8_WAIT_V(6); PG8_BAR; PG8_MMA(1, 1, At, B1); PG8_BAR;
.LBB0_521:
	s_add_u32 s20, s20, 0x100080
	s_addc_u32 s21, s21, 0
	s_add_u32 s11, s22, 0x100
	s_addc_u32 s13, s23, 0
	s_mov_b32 s46, -2
	v_add_u32_e32 v252, 0x18000, v187
	v_add_u32_e32 v253, 0x1c000, v187
	ds_read_b128 v[128:131], v193
	ds_read_b128 v[132:135], v193 offset:1024
	ds_read_b128 v[136:139], v193 offset:2048
	ds_read_b128 v[140:143], v193 offset:3072
	s_add_u32 s22, s20, 0xfff00080
	s_addc_u32 s23, s21, -1
	s_cmp_eq_u32 s46, 60
	s_cselect_b32 s25, s5, s23
	s_cselect_b32 s24, s4, s22
	s_cselect_b32 s23, s15, s13
	s_cselect_b32 s22, s14, s11
	s_add_i32 m0, s17, 0xc000
	ds_read_b128 v[144:147], v194
	ds_read_b128 v[148:151], v194 offset:1024
	ds_read_b128 v[152:155], v194 offset:2048
	ds_read_b128 v[156:159], v194 offset:3072
	ds_read_b128 v[176:179], v194 offset:4096
	ds_read_b128 v[180:183], v194 offset:5120
	ds_read_b128 v[196:199], v194 offset:6144
	ds_read_b128 v[200:203], v194 offset:7168
	global_load_lds_dwordx4 v168, s[20:21]
	s_add_i32 m0, s17, 0xe000
	s_nop 0
	global_load_lds_dwordx4 v170, s[20:21]
	s_waitcnt lgkmcnt(8)
	s_waitcnt lgkmcnt(6)
	v_mfma_f32_16x16x32_bf16 v[124:127], v[128:131], v[144:147], 0
	v_mfma_f32_16x16x32_bf16 v[124:127], v[132:135], v[148:151], v[124:127]
	v_mfma_f32_16x16x32_bf16 v[120:123], v[140:143], v[148:151], 0
	v_mfma_f32_16x16x32_bf16 v[120:123], v[136:139], v[144:147], v[120:123]
	s_barrier
	s_waitcnt lgkmcnt(0)
	v_mfma_f32_16x16x32_bf16 v[104:107], v[136:139], v[152:155], 0
	v_mfma_f32_16x16x32_bf16 v[104:107], v[140:143], v[156:159], v[104:107]
	v_mfma_f32_16x16x32_bf16 v[112:115], v[132:135], v[156:159], 0
	v_mfma_f32_16x16x32_bf16 v[112:115], v[128:131], v[152:155], v[112:115]
	v_mfma_f32_16x16x32_bf16 v[92:95], v[128:131], v[176:179], 0
	v_mfma_f32_16x16x32_bf16 v[92:95], v[132:135], v[180:183], v[92:95]
	v_mfma_f32_16x16x32_bf16 v[88:91], v[140:143], v[180:183], 0
	v_mfma_f32_16x16x32_bf16 v[88:91], v[136:139], v[176:179], v[88:91]
	v_mfma_f32_16x16x32_bf16 v[72:75], v[136:139], v[196:199], 0
	v_mfma_f32_16x16x32_bf16 v[72:75], v[140:143], v[200:203], v[72:75]
	v_mfma_f32_16x16x32_bf16 v[76:79], v[132:135], v[200:203], 0
	v_mfma_f32_16x16x32_bf16 v[76:79], v[128:131], v[196:199], v[76:79]
	s_barrier
	s_add_i32 s47, s42, s34
	s_add_u32 s90, s22, 0x80
	s_addc_u32 s91, s23, 0
	s_mov_b32 m0, s47
	ds_read_b128 v[204:207], v195
	ds_read_b128 v[208:211], v195 offset:1024
	ds_read_b128 v[212:215], v195 offset:2048
	ds_read_b128 v[216:219], v195 offset:3072
	global_load_lds_dwordx4 v162, s[22:23]
	s_add_i32 m0, s47, 0x2000
	s_nop 0
	global_load_lds_dwordx4 v166, s[22:23]
	s_waitcnt lgkmcnt(0)
	v_mfma_f32_16x16x32_bf16 v[116:119], v[204:207], v[144:147], 0
	v_mfma_f32_16x16x32_bf16 v[116:119], v[208:211], v[148:151], v[116:119]
	v_mfma_f32_16x16x32_bf16 v[108:111], v[216:219], v[148:151], 0
	v_mfma_f32_16x16x32_bf16 v[108:111], v[212:215], v[144:147], v[108:111]
	s_barrier
	s_waitcnt lgkmcnt(0)
	v_mfma_f32_16x16x32_bf16 v[96:99], v[212:215], v[152:155], 0
	v_mfma_f32_16x16x32_bf16 v[96:99], v[216:219], v[156:159], v[96:99]
	v_mfma_f32_16x16x32_bf16 v[100:103], v[208:211], v[156:159], 0
	v_mfma_f32_16x16x32_bf16 v[100:103], v[204:207], v[152:155], v[100:103]
	v_mfma_f32_16x16x32_bf16 v[84:87], v[204:207], v[176:179], 0
	v_mfma_f32_16x16x32_bf16 v[84:87], v[208:211], v[180:183], v[84:87]
	v_mfma_f32_16x16x32_bf16 v[80:83], v[216:219], v[180:183], 0
	v_mfma_f32_16x16x32_bf16 v[80:83], v[212:215], v[176:179], v[80:83]
	v_mfma_f32_16x16x32_bf16 v[64:67], v[212:215], v[196:199], 0
	v_mfma_f32_16x16x32_bf16 v[64:67], v[216:219], v[200:203], v[64:67]
	v_mfma_f32_16x16x32_bf16 v[68:71], v[208:211], v[200:203], 0
	v_mfma_f32_16x16x32_bf16 v[68:71], v[204:207], v[196:199], v[68:71]
	s_barrier
	s_mov_b32 m0, s17
	s_add_u32 s92, s24, 0x80
	s_addc_u32 s93, s25, 0
	ds_read_b128 v[144:147], v194 offset:16384
	ds_read_b128 v[148:151], v194 offset:17408
	ds_read_b128 v[152:155], v194 offset:18432
	ds_read_b128 v[156:159], v194 offset:19456
	ds_read_b128 v[176:179], v194 offset:20480
	ds_read_b128 v[180:183], v194 offset:21504
	ds_read_b128 v[196:199], v194 offset:22528
	ds_read_b128 v[200:203], v194 offset:23552
	global_load_lds_dwordx4 v160, s[24:25]
	s_mov_b32 m0, s19
	s_nop 0
	global_load_lds_dwordx4 v164, s[24:25]
	s_waitcnt lgkmcnt(6)
	v_mfma_f32_16x16x32_bf16 v[60:63], v[128:131], v[144:147], 0
	v_mfma_f32_16x16x32_bf16 v[60:63], v[132:135], v[148:151], v[60:63]
	v_mfma_f32_16x16x32_bf16 v[56:59], v[140:143], v[148:151], 0
	v_mfma_f32_16x16x32_bf16 v[56:59], v[136:139], v[144:147], v[56:59]
	s_barrier
	s_waitcnt lgkmcnt(0)
	v_mfma_f32_16x16x32_bf16 v[40:43], v[136:139], v[152:155], 0
	v_mfma_f32_16x16x32_bf16 v[40:43], v[140:143], v[156:159], v[40:43]
	v_mfma_f32_16x16x32_bf16 v[48:51], v[132:135], v[156:159], 0
	v_mfma_f32_16x16x32_bf16 v[48:51], v[128:131], v[152:155], v[48:51]
	v_mfma_f32_16x16x32_bf16 v[32:35], v[128:131], v[176:179], 0
	v_mfma_f32_16x16x32_bf16 v[32:35], v[132:135], v[180:183], v[32:35]
	v_mfma_f32_16x16x32_bf16 v[24:27], v[140:143], v[180:183], 0
	v_mfma_f32_16x16x32_bf16 v[24:27], v[136:139], v[176:179], v[24:27]
	v_mfma_f32_16x16x32_bf16 v[8:11], v[136:139], v[196:199], 0
	v_mfma_f32_16x16x32_bf16 v[8:11], v[140:143], v[200:203], v[8:11]
	v_mfma_f32_16x16x32_bf16 v[16:19], v[132:135], v[200:203], 0
	v_mfma_f32_16x16x32_bf16 v[16:19], v[128:131], v[196:199], v[16:19]
	s_barrier
	s_add_u32 s48, s22, 0x100000
	s_addc_u32 s49, s23, 0
	s_add_i32 s47, s43, s34
	s_mov_b32 m0, s47
	s_nop 0
	global_load_lds_dwordx4 v162, s[48:49]
	s_add_i32 m0, s47, 0x2000
	s_nop 0
	global_load_lds_dwordx4 v166, s[48:49]
	s_waitcnt vmcnt(6)
	v_mfma_f32_16x16x32_bf16 v[52:55], v[204:207], v[144:147], 0
	v_mfma_f32_16x16x32_bf16 v[52:55], v[208:211], v[148:151], v[52:55]
	v_mfma_f32_16x16x32_bf16 v[44:47], v[216:219], v[148:151], 0
	v_mfma_f32_16x16x32_bf16 v[44:47], v[212:215], v[144:147], v[44:47]
	s_barrier
; #define PG8_STAGE(bufoff, gbase, voff) do { _Pragma("unroll") for (int _i = 0; _i < 2; ++_i) \
;         __builtin_amdgcn_global_load_lds((const unsigned*)((const char*)(gbase) + (voff)[_i]), (LAS unsigned*)(lds + (bufoff) + ldsw + _i * 8192), 16, 0, 0); } while (0)
; #define PG8_LDA(dst, b, h) do { _Pragma("unroll") for (int m = 0; m < 4; ++m) _Pragma("unroll") for (int k = 0; k < 2; ++k) dst[m][k] = *(const LAS bf16x8*)(lds + PG8_SA(b, h) + aoff + m * 2048 + k * 1024); } while (0)
; #define PG8_LDB(dst, b, h) do { _Pragma("unroll") for (int n = 0; n < 2; ++n) _Pragma("unroll") for (int k = 0; k < 2; ++k) dst[n][k] = *(const LAS bf16x8*)(lds + PG8_SB(b, h) + boff + n * 2048 + k * 1024); } while (0)
; #define PG8_MMA(ai, bj, At, Bt) do { __builtin_amdgcn_s_setprio(1); _Pragma("unroll") for (int m = 0; m < 4; ++m) _Pragma("unroll") for (int n = 0; n < 2; ++n) _Pragma("unroll") for (int k = 0; k < 2; ++k) \
;         acc[ai][bj][m][n] = __builtin_amdgcn_mfma_f32_16x16x32_bf16(Bt[n][k], At[m][k], acc[ai][bj][m][n], 0, 0, 0); __builtin_amdgcn_s_setprio(0); } while (0)
; #define PG8_WAIT_V(n) asm volatile("s_waitcnt vmcnt(" #n ")" ::: "memory")
; #define PG8_WAIT_L(n) asm volatile("s_waitcnt lgkmcnt(" #n ")" ::: "memory")
; #define PG8_BAR __builtin_amdgcn_s_barrier()
; #define PG8_SCHED __builtin_amdgcn_sched_barrier(0)
; template <class Epi, class Ptrs>
; __device__ __forceinline__ void gemm_phase(LAS unsigned char* lds, const int K, const StaticOrder& S, const Ptrs& P, const Epi& E) {
;     ...
;             PG8_BAR; PG8_WAIT_L(0); PG8_MMA(1, 0, At, B0); PG8_BAR; PG8_SCHED;
;             PG8_STAGE(PG8_SB(0, 1), b2 + hstep, voffB);
;             PG8_WAIT_V(6); PG8_BAR; PG8_MMA(1, 1, At, B1); PG8_BAR;
;             PG8_LDB(B0, 1, 0); PG8_SCHED; PG8_LDA(At, 1, 0); PG8_STAGE(PG8_SA(0, 1), a2 + hstep, voffA);
;             PG8_WAIT_L(8); PG8_BAR; PG8_WAIT_L(0); PG8_MMA(0, 0, At, B0); PG8_BAR; PG8_SCHED;
;             PG8_LDB(B1, 1, 1); PG8_STAGE(PG8_SB(1, 0), b3, voffB);
;             PG8_BAR; PG8_WAIT_L(0); PG8_MMA(0, 1, At, B1); PG8_BAR;
;             PG8_LDA(At, 1, 1); PG8_STAGE(PG8_SA(1, 0), a3, voffA);
;             PG8_BAR; PG8_WAIT_L(0); PG8_MMA(1, 0, At, B0); PG8_BAR; PG8_SCHED;
	v_mfma_f32_16x16x32_bf16 v[28:31], v[212:215], v[152:155], 0
	v_mfma_f32_16x16x32_bf16 v[28:31], v[216:219], v[156:159], v[28:31]
	v_mfma_f32_16x16x32_bf16 v[36:39], v[208:211], v[156:159], 0
	v_mfma_f32_16x16x32_bf16 v[36:39], v[204:207], v[152:155], v[36:39]
	v_mfma_f32_16x16x32_bf16 v[20:23], v[204:207], v[176:179], 0
	v_mfma_f32_16x16x32_bf16 v[20:23], v[208:211], v[180:183], v[20:23]
	v_mfma_f32_16x16x32_bf16 v[12:15], v[216:219], v[180:183], 0
	v_mfma_f32_16x16x32_bf16 v[12:15], v[212:215], v[176:179], v[12:15]
	v_mfma_f32_16x16x32_bf16 v[0:3], v[212:215], v[196:199], 0
	v_mfma_f32_16x16x32_bf16 v[0:3], v[216:219], v[200:203], v[0:3]
	v_mfma_f32_16x16x32_bf16 v[4:7], v[208:211], v[200:203], 0
	v_mfma_f32_16x16x32_bf16 v[4:7], v[204:207], v[196:199], v[4:7]
	s_barrier
	s_add_i32 s47, 0, 0x18000
	ds_read_b128 v[128:131], v252
	ds_read_b128 v[132:135], v252 offset:1024
	ds_read_b128 v[136:139], v252 offset:2048
	ds_read_b128 v[140:143], v252 offset:3072
	s_add_u32 s24, s24, 0x100000
	s_addc_u32 s25, s25, 0
	s_mov_b32 m0, s40
	ds_read_b128 v[144:147], v194 offset:32768
	ds_read_b128 v[148:151], v194 offset:33792
	ds_read_b128 v[152:155], v194 offset:34816
	ds_read_b128 v[156:159], v194 offset:35840
	ds_read_b128 v[176:179], v194 offset:36864
	ds_read_b128 v[180:183], v194 offset:37888
	ds_read_b128 v[196:199], v194 offset:38912
	ds_read_b128 v[200:203], v194 offset:39936
	global_load_lds_dwordx4 v160, s[24:25]
	s_mov_b32 m0, s41
	s_nop 0
	global_load_lds_dwordx4 v164, s[24:25]
	s_waitcnt lgkmcnt(8)
	s_waitcnt lgkmcnt(6)
	v_mfma_f32_16x16x32_bf16 v[124:127], v[128:131], v[144:147], v[124:127]
	v_mfma_f32_16x16x32_bf16 v[124:127], v[132:135], v[148:151], v[124:127]
	v_mfma_f32_16x16x32_bf16 v[120:123], v[140:143], v[148:151], v[120:123]
	v_mfma_f32_16x16x32_bf16 v[120:123], v[136:139], v[144:147], v[120:123]
	s_barrier
	s_waitcnt lgkmcnt(0)
	v_mfma_f32_16x16x32_bf16 v[104:107], v[136:139], v[152:155], v[104:107]
	v_mfma_f32_16x16x32_bf16 v[104:107], v[140:143], v[156:159], v[104:107]
	v_mfma_f32_16x16x32_bf16 v[112:115], v[132:135], v[156:159], v[112:115]
	v_mfma_f32_16x16x32_bf16 v[112:115], v[128:131], v[152:155], v[112:115]
	v_mfma_f32_16x16x32_bf16 v[92:95], v[128:131], v[176:179], v[92:95]
	v_mfma_f32_16x16x32_bf16 v[92:95], v[132:135], v[180:183], v[92:95]
	v_mfma_f32_16x16x32_bf16 v[88:91], v[140:143], v[180:183], v[88:91]
	v_mfma_f32_16x16x32_bf16 v[88:91], v[136:139], v[176:179], v[88:91]
	v_mfma_f32_16x16x32_bf16 v[72:75], v[136:139], v[196:199], v[72:75]
	v_mfma_f32_16x16x32_bf16 v[72:75], v[140:143], v[200:203], v[72:75]
	v_mfma_f32_16x16x32_bf16 v[76:79], v[132:135], v[200:203], v[76:79]
	v_mfma_f32_16x16x32_bf16 v[76:79], v[128:131], v[196:199], v[76:79]
	s_barrier
	s_add_i32 s24, 0, 0x1c000
	s_add_i32 s25, s47, s34
	s_mov_b32 m0, s25
	ds_read_b128 v[204:207], v253
	ds_read_b128 v[208:211], v253 offset:1024
	ds_read_b128 v[212:215], v253 offset:2048
	ds_read_b128 v[216:219], v253 offset:3072
	global_load_lds_dwordx4 v162, s[90:91]
	s_add_i32 m0, s25, 0x2000
	s_nop 0
	global_load_lds_dwordx4 v166, s[90:91]
	s_waitcnt lgkmcnt(0)
	v_mfma_f32_16x16x32_bf16 v[116:119], v[204:207], v[144:147], v[116:119]
	v_mfma_f32_16x16x32_bf16 v[116:119], v[208:211], v[148:151], v[116:119]
	v_mfma_f32_16x16x32_bf16 v[108:111], v[216:219], v[148:151], v[108:111]
	v_mfma_f32_16x16x32_bf16 v[108:111], v[212:215], v[144:147], v[108:111]
	s_barrier
	s_waitcnt lgkmcnt(0)
	v_mfma_f32_16x16x32_bf16 v[96:99], v[212:215], v[152:155], v[96:99]
	v_mfma_f32_16x16x32_bf16 v[96:99], v[216:219], v[156:159], v[96:99]
	v_mfma_f32_16x16x32_bf16 v[100:103], v[208:211], v[156:159], v[100:103]
	v_mfma_f32_16x16x32_bf16 v[100:103], v[204:207], v[152:155], v[100:103]
	v_mfma_f32_16x16x32_bf16 v[84:87], v[204:207], v[176:179], v[84:87]
	v_mfma_f32_16x16x32_bf16 v[84:87], v[208:211], v[180:183], v[84:87]
	v_mfma_f32_16x16x32_bf16 v[80:83], v[216:219], v[180:183], v[80:83]
	v_mfma_f32_16x16x32_bf16 v[80:83], v[212:215], v[176:179], v[80:83]
	v_mfma_f32_16x16x32_bf16 v[64:67], v[212:215], v[196:199], v[64:67]
	v_mfma_f32_16x16x32_bf16 v[64:67], v[216:219], v[200:203], v[64:67]
	v_mfma_f32_16x16x32_bf16 v[68:71], v[208:211], v[200:203], v[68:71]
	v_mfma_f32_16x16x32_bf16 v[68:71], v[204:207], v[196:199], v[68:71]
	s_barrier
	s_mov_b32 m0, s28
	ds_read_b128 v[144:147], v194 offset:49152
	ds_read_b128 v[148:151], v194 offset:50176
	ds_read_b128 v[152:155], v194 offset:51200
	ds_read_b128 v[156:159], v194 offset:52224
	ds_read_b128 v[176:179], v194 offset:53248
	ds_read_b128 v[180:183], v194 offset:54272
	ds_read_b128 v[196:199], v194 offset:55296
	ds_read_b128 v[200:203], v194 offset:56320
	global_load_lds_dwordx4 v160, s[92:93]
	s_mov_b32 m0, s29
	s_nop 0
	global_load_lds_dwordx4 v164, s[92:93]
	s_waitcnt lgkmcnt(6)
	v_mfma_f32_16x16x32_bf16 v[60:63], v[128:131], v[144:147], v[60:63]
	v_mfma_f32_16x16x32_bf16 v[60:63], v[132:135], v[148:151], v[60:63]
	v_mfma_f32_16x16x32_bf16 v[56:59], v[140:143], v[148:151], v[56:59]
	v_mfma_f32_16x16x32_bf16 v[56:59], v[136:139], v[144:147], v[56:59]
	s_barrier
	s_waitcnt lgkmcnt(0)
	v_mfma_f32_16x16x32_bf16 v[40:43], v[136:139], v[152:155], v[40:43]
	v_mfma_f32_16x16x32_bf16 v[40:43], v[140:143], v[156:159], v[40:43]
	v_mfma_f32_16x16x32_bf16 v[48:51], v[132:135], v[156:159], v[48:51]
	v_mfma_f32_16x16x32_bf16 v[48:51], v[128:131], v[152:155], v[48:51]
	v_mfma_f32_16x16x32_bf16 v[32:35], v[128:131], v[176:179], v[32:35]
	v_mfma_f32_16x16x32_bf16 v[32:35], v[132:135], v[180:183], v[32:35]
	v_mfma_f32_16x16x32_bf16 v[24:27], v[140:143], v[180:183], v[24:27]
	v_mfma_f32_16x16x32_bf16 v[24:27], v[136:139], v[176:179], v[24:27]
	v_mfma_f32_16x16x32_bf16 v[8:11], v[136:139], v[196:199], v[8:11]
	v_mfma_f32_16x16x32_bf16 v[8:11], v[140:143], v[200:203], v[8:11]
	v_mfma_f32_16x16x32_bf16 v[16:19], v[132:135], v[200:203], v[16:19]
	v_mfma_f32_16x16x32_bf16 v[16:19], v[128:131], v[196:199], v[16:19]
	s_barrier
; #define PG8_STAGE(bufoff, gbase, voff) do { _Pragma("unroll") for (int _i = 0; _i < 2; ++_i) \
;         __builtin_amdgcn_global_load_lds((const unsigned*)((const char*)(gbase) + (voff)[_i]), (LAS unsigned*)(lds + (bufoff) + ldsw + _i * 8192), 16, 0, 0); } while (0)
; #define PG8_LDA(dst, b, h) do { _Pragma("unroll") for (int m = 0; m < 4; ++m) _Pragma("unroll") for (int k = 0; k < 2; ++k) dst[m][k] = *(const LAS bf16x8*)(lds + PG8_SA(b, h) + aoff + m * 2048 + k * 1024); } while (0)
; #define PG8_LDB(dst, b, h) do { _Pragma("unroll") for (int n = 0; n < 2; ++n) _Pragma("unroll") for (int k = 0; k < 2; ++k) dst[n][k] = *(const LAS bf16x8*)(lds + PG8_SB(b, h) + boff + n * 2048 + k * 1024); } while (0)
; #define PG8_MMA(ai, bj, At, Bt) do { __builtin_amdgcn_s_setprio(1); _Pragma("unroll") for (int m = 0; m < 4; ++m) _Pragma("unroll") for (int n = 0; n < 2; ++n) _Pragma("unroll") for (int k = 0; k < 2; ++k) \
;         acc[ai][bj][m][n] = __builtin_amdgcn_mfma_f32_16x16x32_bf16(Bt[n][k], At[m][k], acc[ai][bj][m][n], 0, 0, 0); __builtin_amdgcn_s_setprio(0); } while (0)
; #define PG8_WAIT_V(n) asm volatile("s_waitcnt vmcnt(" #n ")" ::: "memory")
; template <class Epi, class Ptrs>
; __device__ __forceinline__ void gemm_phase(LAS unsigned char* lds, const int K, const StaticOrder& S, const Ptrs& P, const Epi& E) {
;     ...
;         for (int t = 0; t < nt; t += 2) {
;             const bool last = (t == nt - 2);
;             const char* a1 = cA + (size_t)(t + 1) * kstep;
;             const char* a2 = last ? nA : cA + (size_t)(t + 2) * kstep; const char* b2 = last ? nB : cB + (size_t)(t + 2) * kstep;
;             const char* a3 = a2 + kstep; const char* b3 = b2 + kstep;
;             PG8_LDB(B0, 0, 0); PG8_SCHED; PG8_LDA(At, 0, 0); PG8_STAGE(PG8_SA(1, 1), a1 + hstep, voffA);
;             PG8_WAIT_L(8); PG8_BAR; PG8_WAIT_L(0); PG8_MMA(0, 0, At, B0); PG8_BAR; PG8_SCHED;
;             PG8_LDB(B1, 0, 1); PG8_STAGE(PG8_SB(0, 0), b2, voffB);
;             PG8_BAR; PG8_WAIT_L(0); PG8_MMA(0, 1, At, B1); PG8_BAR;
;             PG8_LDA(At, 0, 1); PG8_STAGE(PG8_SA(0, 0), a2, voffA);
;             PG8_BAR; PG8_WAIT_L(0); PG8_MMA(1, 0, At, B0); PG8_BAR; PG8_SCHED;
;     ...
;             PG8_BAR; PG8_WAIT_L(0); PG8_MMA(1, 0, At, B0); PG8_BAR; PG8_SCHED;
;             PG8_STAGE(PG8_SB(1, 1), b3 + hstep, voffB);
;             PG8_WAIT_V(6); PG8_BAR; PG8_MMA(1, 1, At, B1); PG8_BAR;
	s_add_u32 s22, s22, 0x100080
	s_addc_u32 s23, s23, 0
	s_add_i32 s24, s24, s34
	s_mov_b32 m0, s24
	s_nop 0
	global_load_lds_dwordx4 v162, s[22:23]
	s_add_i32 m0, s24, 0x2000
	s_nop 0
	global_load_lds_dwordx4 v166, s[22:23]
	s_waitcnt vmcnt(6)
	v_mfma_f32_16x16x32_bf16 v[52:55], v[204:207], v[144:147], v[52:55]
	v_mfma_f32_16x16x32_bf16 v[52:55], v[208:211], v[148:151], v[52:55]
	v_mfma_f32_16x16x32_bf16 v[44:47], v[216:219], v[148:151], v[44:47]
	v_mfma_f32_16x16x32_bf16 v[44:47], v[212:215], v[144:147], v[44:47]
	s_barrier
	v_mfma_f32_16x16x32_bf16 v[28:31], v[212:215], v[152:155], v[28:31]
	v_mfma_f32_16x16x32_bf16 v[28:31], v[216:219], v[156:159], v[28:31]
	v_mfma_f32_16x16x32_bf16 v[36:39], v[208:211], v[156:159], v[36:39]
	v_mfma_f32_16x16x32_bf16 v[36:39], v[204:207], v[152:155], v[36:39]
	v_mfma_f32_16x16x32_bf16 v[20:23], v[204:207], v[176:179], v[20:23]
	v_mfma_f32_16x16x32_bf16 v[20:23], v[208:211], v[180:183], v[20:23]
	v_mfma_f32_16x16x32_bf16 v[12:15], v[216:219], v[180:183], v[12:15]
	v_mfma_f32_16x16x32_bf16 v[12:15], v[212:215], v[176:179], v[12:15]
	v_mfma_f32_16x16x32_bf16 v[0:3], v[212:215], v[196:199], v[0:3]
	v_mfma_f32_16x16x32_bf16 v[0:3], v[216:219], v[200:203], v[0:3]
	v_mfma_f32_16x16x32_bf16 v[4:7], v[208:211], v[200:203], v[4:7]
	v_mfma_f32_16x16x32_bf16 v[4:7], v[204:207], v[196:199], v[4:7]
	s_barrier
	s_add_i32 s46, s46, 2
	s_add_u32 s20, s20, 0x100
	s_addc_u32 s21, s21, 0
	s_add_u32 s11, s11, 0x100
	s_addc_u32 s13, s13, 0
	s_cmp_gt_u32 s46, 61
.LBB0_522:
	ds_read_b128 v[128:131], v193
	ds_read_b128 v[132:135], v193 offset:1024
	ds_read_b128 v[136:139], v193 offset:2048
	ds_read_b128 v[140:143], v193 offset:3072
	s_add_u32 s22, s20, 0xfff00080
	s_addc_u32 s23, s21, -1
	s_cmp_eq_u32 s46, 60
	s_cselect_b32 s25, s5, s23
	s_cselect_b32 s24, s4, s22
	s_cselect_b32 s23, s15, s13
	s_cselect_b32 s22, s14, s11
	s_add_i32 m0, s17, 0xc000
	ds_read_b128 v[144:147], v194
	ds_read_b128 v[148:151], v194 offset:1024
	ds_read_b128 v[152:155], v194 offset:2048
	ds_read_b128 v[156:159], v194 offset:3072
	ds_read_b128 v[176:179], v194 offset:4096
	ds_read_b128 v[180:183], v194 offset:5120
	ds_read_b128 v[196:199], v194 offset:6144
	ds_read_b128 v[200:203], v194 offset:7168
	global_load_lds_dwordx4 v168, s[20:21]
	s_add_i32 m0, s17, 0xe000
	s_nop 0
	global_load_lds_dwordx4 v170, s[20:21]
	s_waitcnt lgkmcnt(8)
	s_waitcnt lgkmcnt(6)
	v_mfma_f32_16x16x32_bf16 v[124:127], v[128:131], v[144:147], v[124:127]
	v_mfma_f32_16x16x32_bf16 v[124:127], v[132:135], v[148:151], v[124:127]
	v_mfma_f32_16x16x32_bf16 v[120:123], v[140:143], v[148:151], v[120:123]
	v_mfma_f32_16x16x32_bf16 v[120:123], v[136:139], v[144:147], v[120:123]
	s_barrier
	s_waitcnt lgkmcnt(0)
	v_mfma_f32_16x16x32_bf16 v[104:107], v[136:139], v[152:155], v[104:107]
	v_mfma_f32_16x16x32_bf16 v[104:107], v[140:143], v[156:159], v[104:107]
	v_mfma_f32_16x16x32_bf16 v[112:115], v[132:135], v[156:159], v[112:115]
	v_mfma_f32_16x16x32_bf16 v[112:115], v[128:131], v[152:155], v[112:115]
	v_mfma_f32_16x16x32_bf16 v[92:95], v[128:131], v[176:179], v[92:95]
	v_mfma_f32_16x16x32_bf16 v[92:95], v[132:135], v[180:183], v[92:95]
	v_mfma_f32_16x16x32_bf16 v[88:91], v[140:143], v[180:183], v[88:91]
	v_mfma_f32_16x16x32_bf16 v[88:91], v[136:139], v[176:179], v[88:91]
	v_mfma_f32_16x16x32_bf16 v[72:75], v[136:139], v[196:199], v[72:75]
	v_mfma_f32_16x16x32_bf16 v[72:75], v[140:143], v[200:203], v[72:75]
	v_mfma_f32_16x16x32_bf16 v[76:79], v[132:135], v[200:203], v[76:79]
	v_mfma_f32_16x16x32_bf16 v[76:79], v[128:131], v[196:199], v[76:79]
	s_barrier
	s_add_i32 s47, s42, s34
	s_add_u32 s90, s22, 0x80
	s_addc_u32 s91, s23, 0
	s_mov_b32 m0, s47
	ds_read_b128 v[204:207], v195
	ds_read_b128 v[208:211], v195 offset:1024
	ds_read_b128 v[212:215], v195 offset:2048
	ds_read_b128 v[216:219], v195 offset:3072
	global_load_lds_dwordx4 v162, s[22:23]
	s_add_i32 m0, s47, 0x2000
	s_nop 0
	global_load_lds_dwordx4 v166, s[22:23]
	s_waitcnt lgkmcnt(0)
	v_mfma_f32_16x16x32_bf16 v[116:119], v[204:207], v[144:147], v[116:119]
	v_mfma_f32_16x16x32_bf16 v[116:119], v[208:211], v[148:151], v[116:119]
	v_mfma_f32_16x16x32_bf16 v[108:111], v[216:219], v[148:151], v[108:111]
	v_mfma_f32_16x16x32_bf16 v[108:111], v[212:215], v[144:147], v[108:111]
	s_barrier
	s_waitcnt lgkmcnt(0)
	v_mfma_f32_16x16x32_bf16 v[96:99], v[212:215], v[152:155], v[96:99]
	v_mfma_f32_16x16x32_bf16 v[96:99], v[216:219], v[156:159], v[96:99]
	v_mfma_f32_16x16x32_bf16 v[100:103], v[208:211], v[156:159], v[100:103]
	v_mfma_f32_16x16x32_bf16 v[100:103], v[204:207], v[152:155], v[100:103]
	v_mfma_f32_16x16x32_bf16 v[84:87], v[204:207], v[176:179], v[84:87]
	v_mfma_f32_16x16x32_bf16 v[84:87], v[208:211], v[180:183], v[84:87]
	v_mfma_f32_16x16x32_bf16 v[80:83], v[216:219], v[180:183], v[80:83]
	v_mfma_f32_16x16x32_bf16 v[80:83], v[212:215], v[176:179], v[80:83]
	v_mfma_f32_16x16x32_bf16 v[64:67], v[212:215], v[196:199], v[64:67]
	v_mfma_f32_16x16x32_bf16 v[64:67], v[216:219], v[200:203], v[64:67]
	v_mfma_f32_16x16x32_bf16 v[68:71], v[208:211], v[200:203], v[68:71]
	v_mfma_f32_16x16x32_bf16 v[68:71], v[204:207], v[196:199], v[68:71]
	s_barrier
	s_mov_b32 m0, s17
	s_add_u32 s92, s24, 0x80
	s_addc_u32 s93, s25, 0
	ds_read_b128 v[144:147], v194 offset:16384
	ds_read_b128 v[148:151], v194 offset:17408
	ds_read_b128 v[152:155], v194 offset:18432
	ds_read_b128 v[156:159], v194 offset:19456
	ds_read_b128 v[176:179], v194 offset:20480
	ds_read_b128 v[180:183], v194 offset:21504
	ds_read_b128 v[196:199], v194 offset:22528
	ds_read_b128 v[200:203], v194 offset:23552
	global_load_lds_dwordx4 v160, s[24:25]
	s_mov_b32 m0, s19
	s_nop 0
	global_load_lds_dwordx4 v164, s[24:25]
	s_waitcnt lgkmcnt(6)
	v_mfma_f32_16x16x32_bf16 v[60:63], v[128:131], v[144:147], v[60:63]
	v_mfma_f32_16x16x32_bf16 v[60:63], v[132:135], v[148:151], v[60:63]
	v_mfma_f32_16x16x32_bf16 v[56:59], v[140:143], v[148:151], v[56:59]
	v_mfma_f32_16x16x32_bf16 v[56:59], v[136:139], v[144:147], v[56:59]
	s_barrier
; #define PG8_STAGE(bufoff, gbase, voff) do { _Pragma("unroll") for (int _i = 0; _i < 2; ++_i) \
;         __builtin_amdgcn_global_load_lds((const unsigned*)((const char*)(gbase) + (voff)[_i]), (LAS unsigned*)(lds + (bufoff) + ldsw + _i * 8192), 16, 0, 0); } while (0)
; #define PG8_LDA(dst, b, h) do { _Pragma("unroll") for (int m = 0; m < 4; ++m) _Pragma("unroll") for (int k = 0; k < 2; ++k) dst[m][k] = *(const LAS bf16x8*)(lds + PG8_SA(b, h) + aoff + m * 2048 + k * 1024); } while (0)
; #define PG8_LDB(dst, b, h) do { _Pragma("unroll") for (int n = 0; n < 2; ++n) _Pragma("unroll") for (int k = 0; k < 2; ++k) dst[n][k] = *(const LAS bf16x8*)(lds + PG8_SB(b, h) + boff + n * 2048 + k * 1024); } while (0)
; #define PG8_MMA(ai, bj, At, Bt) do { __builtin_amdgcn_s_setprio(1); _Pragma("unroll") for (int m = 0; m < 4; ++m) _Pragma("unroll") for (int n = 0; n < 2; ++n) _Pragma("unroll") for (int k = 0; k < 2; ++k) \
;         acc[ai][bj][m][n] = __builtin_amdgcn_mfma_f32_16x16x32_bf16(Bt[n][k], At[m][k], acc[ai][bj][m][n], 0, 0, 0); __builtin_amdgcn_s_setprio(0); } while (0)
; #define PG8_WAIT_V(n) asm volatile("s_waitcnt vmcnt(" #n ")" ::: "memory")
; #define PG8_WAIT_L(n) asm volatile("s_waitcnt lgkmcnt(" #n ")" ::: "memory")
; #define PG8_BAR __builtin_amdgcn_s_barrier()
; #define PG8_SCHED __builtin_amdgcn_sched_barrier(0)
; template <class Epi, class Ptrs>
; __device__ __forceinline__ void gemm_phase(LAS unsigned char* lds, const int K, const StaticOrder& S, const Ptrs& P, const Epi& E) {
;     ...
;             PG8_BAR; PG8_WAIT_L(0); PG8_MMA(1, 0, At, B0); PG8_BAR; PG8_SCHED;
;             PG8_STAGE(PG8_SB(0, 1), b2 + hstep, voffB);
;             PG8_WAIT_V(6); PG8_BAR; PG8_MMA(1, 1, At, B1); PG8_BAR;
;             PG8_LDB(B0, 1, 0); PG8_SCHED; PG8_LDA(At, 1, 0); PG8_STAGE(PG8_SA(0, 1), a2 + hstep, voffA);
;             PG8_WAIT_L(8); PG8_BAR; PG8_WAIT_L(0); PG8_MMA(0, 0, At, B0); PG8_BAR; PG8_SCHED;
;             PG8_LDB(B1, 1, 1); PG8_STAGE(PG8_SB(1, 0), b3, voffB);
;             PG8_BAR; PG8_WAIT_L(0); PG8_MMA(0, 1, At, B1); PG8_BAR;
;             PG8_LDA(At, 1, 1); PG8_STAGE(PG8_SA(1, 0), a3, voffA);
;             PG8_BAR; PG8_WAIT_L(0); PG8_MMA(1, 0, At, B0); PG8_BAR; PG8_SCHED;
	s_waitcnt lgkmcnt(0)
	v_mfma_f32_16x16x32_bf16 v[40:43], v[136:139], v[152:155], v[40:43]
	v_mfma_f32_16x16x32_bf16 v[40:43], v[140:143], v[156:159], v[40:43]
	v_mfma_f32_16x16x32_bf16 v[48:51], v[132:135], v[156:159], v[48:51]
	v_mfma_f32_16x16x32_bf16 v[48:51], v[128:131], v[152:155], v[48:51]
	v_mfma_f32_16x16x32_bf16 v[32:35], v[128:131], v[176:179], v[32:35]
	v_mfma_f32_16x16x32_bf16 v[32:35], v[132:135], v[180:183], v[32:35]
	v_mfma_f32_16x16x32_bf16 v[24:27], v[140:143], v[180:183], v[24:27]
	v_mfma_f32_16x16x32_bf16 v[24:27], v[136:139], v[176:179], v[24:27]
	v_mfma_f32_16x16x32_bf16 v[8:11], v[136:139], v[196:199], v[8:11]
	v_mfma_f32_16x16x32_bf16 v[8:11], v[140:143], v[200:203], v[8:11]
	v_mfma_f32_16x16x32_bf16 v[16:19], v[132:135], v[200:203], v[16:19]
	v_mfma_f32_16x16x32_bf16 v[16:19], v[128:131], v[196:199], v[16:19]
	s_barrier
	s_add_u32 s48, s22, 0x100000
	s_addc_u32 s49, s23, 0
	s_add_i32 s47, s43, s34
	s_mov_b32 m0, s47
	s_nop 0
	global_load_lds_dwordx4 v162, s[48:49]
	s_add_i32 m0, s47, 0x2000
	s_nop 0
	global_load_lds_dwordx4 v166, s[48:49]
	s_waitcnt vmcnt(6)
	v_mfma_f32_16x16x32_bf16 v[52:55], v[204:207], v[144:147], v[52:55]
	v_mfma_f32_16x16x32_bf16 v[52:55], v[208:211], v[148:151], v[52:55]
	v_mfma_f32_16x16x32_bf16 v[44:47], v[216:219], v[148:151], v[44:47]
	v_mfma_f32_16x16x32_bf16 v[44:47], v[212:215], v[144:147], v[44:47]
	s_barrier
	v_mfma_f32_16x16x32_bf16 v[28:31], v[212:215], v[152:155], v[28:31]
	v_mfma_f32_16x16x32_bf16 v[28:31], v[216:219], v[156:159], v[28:31]
	v_mfma_f32_16x16x32_bf16 v[36:39], v[208:211], v[156:159], v[36:39]
	v_mfma_f32_16x16x32_bf16 v[36:39], v[204:207], v[152:155], v[36:39]
	v_mfma_f32_16x16x32_bf16 v[20:23], v[204:207], v[176:179], v[20:23]
	v_mfma_f32_16x16x32_bf16 v[20:23], v[208:211], v[180:183], v[20:23]
	v_mfma_f32_16x16x32_bf16 v[12:15], v[216:219], v[180:183], v[12:15]
	v_mfma_f32_16x16x32_bf16 v[12:15], v[212:215], v[176:179], v[12:15]
	v_mfma_f32_16x16x32_bf16 v[0:3], v[212:215], v[196:199], v[0:3]
	v_mfma_f32_16x16x32_bf16 v[0:3], v[216:219], v[200:203], v[0:3]
	v_mfma_f32_16x16x32_bf16 v[4:7], v[208:211], v[200:203], v[4:7]
	v_mfma_f32_16x16x32_bf16 v[4:7], v[204:207], v[196:199], v[4:7]
	s_barrier
	s_add_i32 s47, 0, 0x18000
	ds_read_b128 v[128:131], v252
	ds_read_b128 v[132:135], v252 offset:1024
	ds_read_b128 v[136:139], v252 offset:2048
	ds_read_b128 v[140:143], v252 offset:3072
	s_add_u32 s24, s24, 0x100000
	s_addc_u32 s25, s25, 0
	s_mov_b32 m0, s40
	ds_read_b128 v[144:147], v194 offset:32768
	ds_read_b128 v[148:151], v194 offset:33792
	ds_read_b128 v[152:155], v194 offset:34816
	ds_read_b128 v[156:159], v194 offset:35840
	ds_read_b128 v[176:179], v194 offset:36864
	ds_read_b128 v[180:183], v194 offset:37888
	ds_read_b128 v[196:199], v194 offset:38912
	ds_read_b128 v[200:203], v194 offset:39936
	global_load_lds_dwordx4 v160, s[24:25]
	s_mov_b32 m0, s41
	s_nop 0
	global_load_lds_dwordx4 v164, s[24:25]
	s_waitcnt lgkmcnt(8)
	s_waitcnt lgkmcnt(6)
	v_mfma_f32_16x16x32_bf16 v[124:127], v[128:131], v[144:147], v[124:127]
	v_mfma_f32_16x16x32_bf16 v[124:127], v[132:135], v[148:151], v[124:127]
	v_mfma_f32_16x16x32_bf16 v[120:123], v[140:143], v[148:151], v[120:123]
	v_mfma_f32_16x16x32_bf16 v[120:123], v[136:139], v[144:147], v[120:123]
	s_barrier
	s_waitcnt lgkmcnt(0)
	v_mfma_f32_16x16x32_bf16 v[104:107], v[136:139], v[152:155], v[104:107]
	v_mfma_f32_16x16x32_bf16 v[104:107], v[140:143], v[156:159], v[104:107]
	v_mfma_f32_16x16x32_bf16 v[112:115], v[132:135], v[156:159], v[112:115]
	v_mfma_f32_16x16x32_bf16 v[112:115], v[128:131], v[152:155], v[112:115]
	v_mfma_f32_16x16x32_bf16 v[92:95], v[128:131], v[176:179], v[92:95]
	v_mfma_f32_16x16x32_bf16 v[92:95], v[132:135], v[180:183], v[92:95]
	v_mfma_f32_16x16x32_bf16 v[88:91], v[140:143], v[180:183], v[88:91]
	v_mfma_f32_16x16x32_bf16 v[88:91], v[136:139], v[176:179], v[88:91]
	v_mfma_f32_16x16x32_bf16 v[72:75], v[136:139], v[196:199], v[72:75]
	v_mfma_f32_16x16x32_bf16 v[72:75], v[140:143], v[200:203], v[72:75]
	v_mfma_f32_16x16x32_bf16 v[76:79], v[132:135], v[200:203], v[76:79]
	v_mfma_f32_16x16x32_bf16 v[76:79], v[128:131], v[196:199], v[76:79]
	s_barrier
	s_add_i32 s24, 0, 0x1c000
	s_add_i32 s25, s47, s34
	s_mov_b32 m0, s25
	ds_read_b128 v[204:207], v253
	ds_read_b128 v[208:211], v253 offset:1024
	ds_read_b128 v[212:215], v253 offset:2048
	ds_read_b128 v[216:219], v253 offset:3072
	global_load_lds_dwordx4 v162, s[90:91]
	s_add_i32 m0, s25, 0x2000
	s_nop 0
	global_load_lds_dwordx4 v166, s[90:91]
	s_waitcnt lgkmcnt(0)
	v_mfma_f32_16x16x32_bf16 v[116:119], v[204:207], v[144:147], v[116:119]
	v_mfma_f32_16x16x32_bf16 v[116:119], v[208:211], v[148:151], v[116:119]
	v_mfma_f32_16x16x32_bf16 v[108:111], v[216:219], v[148:151], v[108:111]
	v_mfma_f32_16x16x32_bf16 v[108:111], v[212:215], v[144:147], v[108:111]
	s_barrier
	s_waitcnt lgkmcnt(0)
	v_mfma_f32_16x16x32_bf16 v[96:99], v[212:215], v[152:155], v[96:99]
	v_mfma_f32_16x16x32_bf16 v[96:99], v[216:219], v[156:159], v[96:99]
	v_mfma_f32_16x16x32_bf16 v[100:103], v[208:211], v[156:159], v[100:103]
	v_mfma_f32_16x16x32_bf16 v[100:103], v[204:207], v[152:155], v[100:103]
	v_mfma_f32_16x16x32_bf16 v[84:87], v[204:207], v[176:179], v[84:87]
	v_mfma_f32_16x16x32_bf16 v[84:87], v[208:211], v[180:183], v[84:87]
	v_mfma_f32_16x16x32_bf16 v[80:83], v[216:219], v[180:183], v[80:83]
	v_mfma_f32_16x16x32_bf16 v[80:83], v[212:215], v[176:179], v[80:83]
	v_mfma_f32_16x16x32_bf16 v[64:67], v[212:215], v[196:199], v[64:67]
	v_mfma_f32_16x16x32_bf16 v[64:67], v[216:219], v[200:203], v[64:67]
	v_mfma_f32_16x16x32_bf16 v[68:71], v[208:211], v[200:203], v[68:71]
	v_mfma_f32_16x16x32_bf16 v[68:71], v[204:207], v[196:199], v[68:71]
	s_barrier
; #define PG8_STAGE(bufoff, gbase, voff) do { _Pragma("unroll") for (int _i = 0; _i < 2; ++_i) \
;         __builtin_amdgcn_global_load_lds((const unsigned*)((const char*)(gbase) + (voff)[_i]), (LAS unsigned*)(lds + (bufoff) + ldsw + _i * 8192), 16, 0, 0); } while (0)
; #define PG8_LDA(dst, b, h) do { _Pragma("unroll") for (int m = 0; m < 4; ++m) _Pragma("unroll") for (int k = 0; k < 2; ++k) dst[m][k] = *(const LAS bf16x8*)(lds + PG8_SA(b, h) + aoff + m * 2048 + k * 1024); } while (0)
; #define PG8_MMA(ai, bj, At, Bt) do { __builtin_amdgcn_s_setprio(1); _Pragma("unroll") for (int m = 0; m < 4; ++m) _Pragma("unroll") for (int n = 0; n < 2; ++n) _Pragma("unroll") for (int k = 0; k < 2; ++k) \
;         acc[ai][bj][m][n] = __builtin_amdgcn_mfma_f32_16x16x32_bf16(Bt[n][k], At[m][k], acc[ai][bj][m][n], 0, 0, 0); __builtin_amdgcn_s_setprio(0); } while (0)
; #define PG8_WAIT_V(n) asm volatile("s_waitcnt vmcnt(" #n ")" ::: "memory")
; #define PG8_WAIT_L(n) asm volatile("s_waitcnt lgkmcnt(" #n ")" ::: "memory")
; #define PG8_BAR __builtin_amdgcn_s_barrier()
; #define PG8_SCHED __builtin_amdgcn_sched_barrier(0)
; template <class Epi, class Ptrs>
; __device__ __forceinline__ void gemm_phase(LAS unsigned char* lds, const int K, const StaticOrder& S, const Ptrs& P, const Epi& E) {
;     ...
;             PG8_BAR; PG8_WAIT_L(0); PG8_MMA(0, 1, At, B1); PG8_BAR;
;             PG8_LDA(At, 1, 1); PG8_STAGE(PG8_SA(1, 0), a3, voffA);
;             PG8_BAR; PG8_WAIT_L(0); PG8_MMA(1, 0, At, B0); PG8_BAR; PG8_SCHED;
;             PG8_STAGE(PG8_SB(1, 1), b3 + hstep, voffB);
;             PG8_WAIT_V(6); PG8_BAR; PG8_MMA(1, 1, At, B1); PG8_BAR;
;     __device__ __forceinline__ void operator()(const f32x4 (&acc)[2][2][4][2], const Unit& u, int ui, int wr, int wc, int fr, int fq) const {
;         const int rl0 = wr * 64 + fr, col0 = u.pn * 256 + wc * 32 + 8 * fq;
;         u32x4 xv[2][4][2];
; #pragma unroll
;         for (int ai = 0; ai < 2; ++ai)
; #pragma unroll
;             for (int m = 0; m < 4; ++m)
; #pragma unroll
;                 for (int bj = 0; bj < 2; ++bj) xv[ai][m][bj] = *(const u32x4*)(xb + (size_t)(u.pm * 256 + rl0 + ai * 128 + m * 16) * DM + col0 + bj * 128);
	s_mov_b32 m0, s28
	ds_read_b128 v[144:147], v194 offset:49152
	ds_read_b128 v[148:151], v194 offset:50176
	ds_read_b128 v[152:155], v194 offset:51200
	ds_read_b128 v[156:159], v194 offset:52224
	ds_read_b128 v[176:179], v194 offset:53248
	ds_read_b128 v[180:183], v194 offset:54272
	ds_read_b128 v[196:199], v194 offset:55296
	ds_read_b128 v[200:203], v194 offset:56320
	global_load_lds_dwordx4 v160, s[92:93]
	s_mov_b32 m0, s29
	s_nop 0
	global_load_lds_dwordx4 v164, s[92:93]
	s_waitcnt lgkmcnt(6)
	v_mfma_f32_16x16x32_bf16 v[60:63], v[128:131], v[144:147], v[60:63]
	v_mfma_f32_16x16x32_bf16 v[60:63], v[132:135], v[148:151], v[60:63]
	v_mfma_f32_16x16x32_bf16 v[56:59], v[140:143], v[148:151], v[56:59]
	v_mfma_f32_16x16x32_bf16 v[56:59], v[136:139], v[144:147], v[56:59]
	s_barrier
	s_waitcnt lgkmcnt(0)
	v_mfma_f32_16x16x32_bf16 v[40:43], v[136:139], v[152:155], v[40:43]
	v_mfma_f32_16x16x32_bf16 v[40:43], v[140:143], v[156:159], v[40:43]
	v_mfma_f32_16x16x32_bf16 v[48:51], v[132:135], v[156:159], v[48:51]
	v_mfma_f32_16x16x32_bf16 v[48:51], v[128:131], v[152:155], v[48:51]
	v_mfma_f32_16x16x32_bf16 v[32:35], v[128:131], v[176:179], v[32:35]
	v_mfma_f32_16x16x32_bf16 v[32:35], v[132:135], v[180:183], v[32:35]
	v_mfma_f32_16x16x32_bf16 v[24:27], v[140:143], v[180:183], v[24:27]
	v_mfma_f32_16x16x32_bf16 v[24:27], v[136:139], v[176:179], v[24:27]
	v_mfma_f32_16x16x32_bf16 v[8:11], v[136:139], v[196:199], v[8:11]
	v_mfma_f32_16x16x32_bf16 v[8:11], v[140:143], v[200:203], v[8:11]
	v_mfma_f32_16x16x32_bf16 v[16:19], v[132:135], v[200:203], v[16:19]
	v_mfma_f32_16x16x32_bf16 v[16:19], v[128:131], v[196:199], v[16:19]
	s_barrier
	s_add_u32 s22, s22, 0x100080
	s_addc_u32 s23, s23, 0
	s_add_i32 s24, s24, s34
	s_mov_b32 m0, s24
	s_nop 0
	global_load_lds_dwordx4 v162, s[22:23]
	s_add_i32 m0, s24, 0x2000
	s_nop 0
	global_load_lds_dwordx4 v166, s[22:23]
	s_waitcnt vmcnt(6)
	v_mfma_f32_16x16x32_bf16 v[52:55], v[204:207], v[144:147], v[52:55]
	v_mfma_f32_16x16x32_bf16 v[52:55], v[208:211], v[148:151], v[52:55]
	v_mfma_f32_16x16x32_bf16 v[44:47], v[216:219], v[148:151], v[44:47]
	v_mfma_f32_16x16x32_bf16 v[44:47], v[212:215], v[144:147], v[44:47]
	s_barrier
	v_mfma_f32_16x16x32_bf16 v[28:31], v[212:215], v[152:155], v[28:31]
	v_mfma_f32_16x16x32_bf16 v[28:31], v[216:219], v[156:159], v[28:31]
	v_mfma_f32_16x16x32_bf16 v[36:39], v[208:211], v[156:159], v[36:39]
	v_mfma_f32_16x16x32_bf16 v[36:39], v[204:207], v[152:155], v[36:39]
	v_mfma_f32_16x16x32_bf16 v[20:23], v[204:207], v[176:179], v[20:23]
	v_mfma_f32_16x16x32_bf16 v[20:23], v[208:211], v[180:183], v[20:23]
	v_mfma_f32_16x16x32_bf16 v[12:15], v[216:219], v[180:183], v[12:15]
	v_mfma_f32_16x16x32_bf16 v[12:15], v[212:215], v[176:179], v[12:15]
	v_mfma_f32_16x16x32_bf16 v[0:3], v[212:215], v[196:199], v[0:3]
	v_mfma_f32_16x16x32_bf16 v[0:3], v[216:219], v[200:203], v[0:3]
	v_mfma_f32_16x16x32_bf16 v[4:7], v[208:211], v[200:203], v[4:7]
	v_mfma_f32_16x16x32_bf16 v[4:7], v[204:207], v[196:199], v[4:7]
	s_barrier
	s_add_i32 s46, s46, 2
	s_add_u32 s20, s20, 0x100
	s_addc_u32 s21, s21, 0
	s_add_u32 s11, s11, 0x100
	s_addc_u32 s13, s13, 0
	s_cmp_gt_u32 s46, 61
	s_cbranch_scc0 .LBB0_522
	s_lshl_b32 s11, s18, 8
	v_lshl_or_b32 v128, s16, 8, v191
	v_add_u32_e32 v130, s11, v186
	v_ashrrev_i32_e32 v129, 31, v128
	v_ashrrev_i32_e32 v131, 31, v130
	v_lshl_add_u64 v[132:133], v[128:129], 1, s[6:7]
	v_lshlrev_b64 v[134:135], 11, v[130:131]
	v_lshl_add_u64 v[134:135], v[132:133], 0, v[134:135]
	global_load_dwordx4 v[198:201], v[134:135], off
	global_load_dwordx4 v[202:205], v[134:135], off offset:256
	v_or_b32_e32 v134, 16, v130
	v_ashrrev_i32_e32 v135, 31, v134
	v_lshlrev_b64 v[134:135], 11, v[134:135]
	v_lshl_add_u64 v[134:135], v[132:133], 0, v[134:135]
	global_load_dwordx4 v[206:209], v[134:135], off
	global_load_dwordx4 v[210:213], v[134:135], off offset:256
	v_or_b32_e32 v136, 32, v130
	v_ashrrev_i32_e32 v137, 31, v136
	v_or_b32_e32 v138, 48, v130
	v_add_u32_e32 v184, 0x80, v130
	v_add_u32_e32 v182, 0x90, v130
	v_add_u32_e32 v180, 0xa0, v130
	v_add_u32_e32 v178, 0xb0, v130
	v_lshlrev_b64 v[176:177], 2, v[128:129]
	v_lshlrev_b64 v[128:129], 12, v[130:131]
	v_lshlrev_b64 v[130:131], 11, v[136:137]
	v_lshl_add_u64 v[130:131], v[132:133], 0, v[130:131]
	global_load_dwordx4 v[214:217], v[130:131], off
	v_ashrrev_i32_e32 v139, 31, v138
	v_ashrrev_i32_e32 v185, 31, v184
	v_ashrrev_i32_e32 v183, 31, v182
	v_ashrrev_i32_e32 v181, 31, v180
	v_ashrrev_i32_e32 v179, 31, v178
	v_lshlrev_b64 v[134:135], 11, v[138:139]
	v_lshlrev_b64 v[136:137], 11, v[184:185]
	v_lshlrev_b64 v[138:139], 11, v[182:183]
	v_lshl_add_u32 v196, s45, 10, v192
	v_lshlrev_b64 v[140:141], 11, v[180:181]
	v_lshlrev_b64 v[142:143], 11, v[178:179]
	v_lshl_add_u64 v[128:129], s[26:27], 0, v[128:129]
	v_lshl_add_u64 v[134:135], v[132:133], 0, v[134:135]
	v_lshl_add_u64 v[136:137], v[132:133], 0, v[136:137]
	v_lshl_add_u64 v[138:139], v[132:133], 0, v[138:139]
	ds_read2_b32 v[230:231], v196 offset1:16
	v_lshl_add_u64 v[234:235], v[132:133], 0, v[140:141]
	v_lshl_add_u64 v[236:237], v[132:133], 0, v[142:143]
	v_lshl_add_u64 v[238:239], v[128:129], 0, v[176:177]
	global_load_dwordx4 v[218:221], v[130:131], off offset:256
	global_load_dwordx4 v[222:225], v[134:135], off
	global_load_dwordx4 v[226:229], v[134:135], off offset:256
	global_load_dwordx4 v[156:159], v[136:137], off
	global_load_dwordx4 v[152:155], v[136:137], off offset:256
	global_load_dwordx4 v[148:151], v[138:139], off
	global_load_dwordx4 v[144:147], v[138:139], off offset:256
	global_load_dwordx4 v[140:143], v[234:235], off
	s_nop 0
	global_load_dwordx4 v[136:139], v[234:235], off offset:256
	global_load_dwordx4 v[132:135], v[236:237], off
	global_load_dwordx4 v[128:131], v[236:237], off offset:256
	v_add_u32_e32 v232, s11, v188
	v_ashrrev_i32_e32 v233, 31, v232
	s_and_b64 vcc, exec, s[0:1]
	s_mov_b32 s16, s10
	s_mov_b32 s18, s12
	s_mov_b64 s[20:21], s[4:5]
	s_mov_b64 s[22:23], s[14:15]
	s_mov_b32 s45, s44
	s_waitcnt vmcnt(0)
; __device__ __forceinline__ float bf_lo(unsigned w) { return __uint_as_float(w << 16); }
; __device__ __forceinline__ float bf_hi(unsigned w) { return __uint_as_float(w & 0xffff0000u); }
;     __device__ __forceinline__ void operator()(const f32x4 (&acc)[2][2][4][2], const Unit& u, int ui, int wr, int wc, int fr, int fq) const {
;     ...
; #pragma unroll
;         for (int ai = 0; ai < 2; ++ai)
; #pragma unroll
;             for (int m = 0; m < 4; ++m) { const int rl = rl0 + ai * 128 + m * 16; float* rowp = out + (size_t)(u.pm * 256 + rl) * DM + col0;
;                 const float r2 = tab[ui * 256 + rl];
; #pragma unroll
;                 for (int bj = 0; bj < 2; ++bj) { const u32x4 x = xv[ai][m][bj];
;                     const f32x4 x0 = {bf_lo(x.x), bf_hi(x.x), bf_lo(x.y), bf_hi(x.y)}, x1 = {bf_lo(x.z), bf_hi(x.z), bf_lo(x.w), bf_hi(x.w)};
;                     *(f32x4*)(rowp + bj * 128) = acc[ai][bj][m][0] * r2 + x0; *(f32x4*)(rowp + bj * 128 + 4) = acc[ai][bj][m][1] * r2 + x1; } }
	v_lshlrev_b32_e32 v234, 16, v198
	v_and_b32_e32 v235, 0xffff0000, v198
	v_lshlrev_b32_e32 v198, 16, v199
	v_and_b32_e32 v199, 0xffff0000, v199
	v_lshlrev_b32_e32 v242, 16, v204
	v_and_b32_e32 v243, 0xffff0000, v204
	v_lshlrev_b32_e32 v236, 16, v200
	v_and_b32_e32 v237, 0xffff0000, v200
	v_lshlrev_b32_e32 v200, 16, v201
	v_and_b32_e32 v201, 0xffff0000, v201
	v_lshlrev_b32_e32 v240, 16, v202
	v_and_b32_e32 v241, 0xffff0000, v202
	v_lshlrev_b32_e32 v202, 16, v203
	v_and_b32_e32 v203, 0xffff0000, v203
	v_lshlrev_b32_e32 v204, 16, v205
	v_and_b32_e32 v205, 0xffff0000, v205
	s_waitcnt lgkmcnt(0)
	v_pk_fma_f32 v[126:127], v[126:127], v[230:231], v[198:199] op_sel_hi:[1,0,1]
	v_pk_fma_f32 v[124:125], v[124:125], v[230:231], v[234:235] op_sel_hi:[1,0,1]
	v_pk_fma_f32 v[108:109], v[108:109], v[230:231], v[242:243] op_sel_hi:[1,0,1]
	v_pk_fma_f32 v[122:123], v[122:123], v[230:231], v[200:201] op_sel_hi:[1,0,1]
	v_pk_fma_f32 v[120:121], v[120:121], v[230:231], v[236:237] op_sel_hi:[1,0,1]
	v_pk_fma_f32 v[118:119], v[118:119], v[230:231], v[202:203] op_sel_hi:[1,0,1]
	v_pk_fma_f32 v[116:117], v[116:117], v[230:231], v[240:241] op_sel_hi:[1,0,1]
	v_pk_fma_f32 v[110:111], v[110:111], v[230:231], v[204:205] op_sel_hi:[1,0,1]
	global_store_dwordx4 v[238:239], v[124:127], off
	global_store_dwordx4 v[238:239], v[120:123], off offset:16
	global_store_dwordx4 v[238:239], v[116:119], off offset:512
	global_store_dwordx4 v[238:239], v[108:111], off offset:528
	v_mov_b32_e32 v122, v231
	v_lshlrev_b32_e32 v118, 16, v208
	v_lshlrev_b64 v[108:109], 12, v[232:233]
	v_lshl_add_u64 v[108:109], s[26:27], 0, v[108:109]
	v_lshl_add_u64 v[116:117], v[108:109], 0, v[176:177]
	v_lshlrev_b32_e32 v108, 16, v206
	v_and_b32_e32 v109, 0xffff0000, v206
	v_lshlrev_b32_e32 v110, 16, v207
	v_and_b32_e32 v111, 0xffff0000, v207
	v_pk_fma_f32 v[110:111], v[114:115], v[122:123], v[110:111] op_sel_hi:[1,0,1]
	v_pk_fma_f32 v[108:109], v[112:113], v[122:123], v[108:109] op_sel_hi:[1,0,1]
	global_store_dwordx4 v[116:117], v[108:111], off
	v_and_b32_e32 v119, 0xffff0000, v208
	v_lshlrev_b32_e32 v120, 16, v209
	v_lshlrev_b32_e32 v108, 16, v212
	v_and_b32_e32 v109, 0xffff0000, v212
	v_lshlrev_b32_e32 v110, 16, v213
	v_and_b32_e32 v111, 0xffff0000, v213
	v_pk_fma_f32 v[98:99], v[98:99], v[122:123], v[110:111] op_sel_hi:[1,0,1]
	v_pk_fma_f32 v[96:97], v[96:97], v[122:123], v[108:109] op_sel_hi:[1,0,1]
	v_and_b32_e32 v121, 0xffff0000, v209
	global_store_dwordx4 v[116:117], v[96:99], off offset:528
	ds_read2_b32 v[98:99], v196 offset0:32 offset1:48
	v_pk_fma_f32 v[106:107], v[106:107], v[122:123], v[120:121] op_sel_hi:[1,0,1]
	v_pk_fma_f32 v[104:105], v[104:105], v[122:123], v[118:119] op_sel_hi:[1,0,1]
	v_add_u32_e32 v96, s11, v189
	global_store_dwordx4 v[116:117], v[104:107], off offset:16
	v_ashrrev_i32_e32 v97, 31, v96
	v_lshlrev_b64 v[96:97], 12, v[96:97]
	v_lshlrev_b32_e32 v104, 16, v210
	v_and_b32_e32 v105, 0xffff0000, v210
	v_lshlrev_b32_e32 v106, 16, v211
	v_and_b32_e32 v107, 0xffff0000, v211
	v_pk_fma_f32 v[102:103], v[102:103], v[122:123], v[106:107] op_sel_hi:[1,0,1]
	v_pk_fma_f32 v[100:101], v[100:101], v[122:123], v[104:105] op_sel_hi:[1,0,1]
	global_store_dwordx4 v[116:117], v[100:103], off offset:512
	v_lshl_add_u64 v[96:97], s[26:27], 0, v[96:97]
	v_lshl_add_u64 v[96:97], v[96:97], 0, v[176:177]
	v_lshlrev_b32_e32 v100, 16, v214
	v_and_b32_e32 v101, 0xffff0000, v214
	v_lshlrev_b32_e32 v102, 16, v215
	v_and_b32_e32 v103, 0xffff0000, v215
	s_waitcnt lgkmcnt(0)
	v_pk_fma_f32 v[94:95], v[94:95], v[98:99], v[102:103] op_sel_hi:[1,0,1]
	v_pk_fma_f32 v[92:93], v[92:93], v[98:99], v[100:101] op_sel_hi:[1,0,1]
	global_store_dwordx4 v[96:97], v[92:95], off
	v_lshlrev_b32_e32 v104, 16, v216
	v_and_b32_e32 v105, 0xffff0000, v216
	v_lshlrev_b32_e32 v92, 16, v220
	v_and_b32_e32 v93, 0xffff0000, v220
	v_lshlrev_b32_e32 v94, 16, v221
	v_and_b32_e32 v95, 0xffff0000, v221
	v_lshlrev_b32_e32 v106, 16, v217
	v_and_b32_e32 v107, 0xffff0000, v217
	v_pk_fma_f32 v[82:83], v[82:83], v[98:99], v[94:95] op_sel_hi:[1,0,1]
	v_pk_fma_f32 v[80:81], v[80:81], v[98:99], v[92:93] op_sel_hi:[1,0,1]
	v_pk_fma_f32 v[90:91], v[90:91], v[98:99], v[106:107] op_sel_hi:[1,0,1]
	v_pk_fma_f32 v[88:89], v[88:89], v[98:99], v[104:105] op_sel_hi:[1,0,1]
	global_store_dwordx4 v[96:97], v[80:83], off offset:528
	global_store_dwordx4 v[96:97], v[88:91], off offset:16
	s_nop 0
	v_add_u32_e32 v80, s11, v190
	v_lshlrev_b32_e32 v88, 16, v218
	v_and_b32_e32 v89, 0xffff0000, v218
	v_lshlrev_b32_e32 v90, 16, v219
	v_and_b32_e32 v91, 0xffff0000, v219
	v_ashrrev_i32_e32 v81, 31, v80
	v_pk_fma_f32 v[86:87], v[86:87], v[98:99], v[90:91] op_sel_hi:[1,0,1]
	v_pk_fma_f32 v[84:85], v[84:85], v[98:99], v[88:89] op_sel_hi:[1,0,1]
	v_lshlrev_b64 v[80:81], 12, v[80:81]
	global_store_dwordx4 v[96:97], v[84:87], off offset:512
	v_lshl_add_u64 v[80:81], s[26:27], 0, v[80:81]
	v_lshlrev_b32_e32 v82, 16, v222
	v_and_b32_e32 v83, 0xffff0000, v222
	v_lshlrev_b32_e32 v84, 16, v223
	v_and_b32_e32 v85, 0xffff0000, v223
	v_mov_b32_e32 v90, v99
	v_lshl_add_u64 v[80:81], v[80:81], 0, v[176:177]
	v_pk_fma_f32 v[78:79], v[78:79], v[90:91], v[84:85] op_sel_hi:[1,0,1]
	v_pk_fma_f32 v[76:77], v[76:77], v[90:91], v[82:83] op_sel_hi:[1,0,1]
	global_store_dwordx4 v[80:81], v[76:79], off
	v_lshlrev_b32_e32 v86, 16, v224
	v_and_b32_e32 v87, 0xffff0000, v224
	v_lshlrev_b32_e32 v76, 16, v228
	v_and_b32_e32 v77, 0xffff0000, v228
	v_lshlrev_b32_e32 v78, 16, v229
	v_and_b32_e32 v79, 0xffff0000, v229
	v_pk_fma_f32 v[66:67], v[66:67], v[90:91], v[78:79] op_sel_hi:[1,0,1]
	v_pk_fma_f32 v[64:65], v[64:65], v[90:91], v[76:77] op_sel_hi:[1,0,1]
	v_lshlrev_b32_e32 v88, 16, v225
	v_and_b32_e32 v89, 0xffff0000, v225
	global_store_dwordx4 v[80:81], v[64:67], off offset:528
	ds_read2_b32 v[66:67], v196 offset0:128 offset1:144
	v_pk_fma_f32 v[74:75], v[74:75], v[90:91], v[88:89] op_sel_hi:[1,0,1]
	v_pk_fma_f32 v[72:73], v[72:73], v[90:91], v[86:87] op_sel_hi:[1,0,1]
	global_store_dwordx4 v[80:81], v[72:75], off offset:16
	v_lshlrev_b64 v[64:65], 12, v[184:185]
	v_lshl_add_u64 v[64:65], s[26:27], 0, v[64:65]
	v_lshlrev_b32_e32 v72, 16, v226
	v_and_b32_e32 v73, 0xffff0000, v226
	v_lshlrev_b32_e32 v74, 16, v227
	v_and_b32_e32 v75, 0xffff0000, v227
	v_pk_fma_f32 v[70:71], v[70:71], v[90:91], v[74:75] op_sel_hi:[1,0,1]
	v_pk_fma_f32 v[68:69], v[68:69], v[90:91], v[72:73] op_sel_hi:[1,0,1]
	global_store_dwordx4 v[80:81], v[68:71], off offset:512
	v_lshl_add_u64 v[64:65], v[64:65], 0, v[176:177]
	v_lshlrev_b32_e32 v72, 16, v158
	v_lshlrev_b32_e32 v68, 16, v156
	v_and_b32_e32 v69, 0xffff0000, v156
	v_lshlrev_b32_e32 v70, 16, v157
	v_and_b32_e32 v71, 0xffff0000, v157
	v_and_b32_e32 v73, 0xffff0000, v158
	v_lshlrev_b32_e32 v74, 16, v159
	v_and_b32_e32 v75, 0xffff0000, v159
	s_waitcnt lgkmcnt(0)
; __device__ __forceinline__ float bf_lo(unsigned w) { return __uint_as_float(w << 16); }
; __device__ __forceinline__ float bf_hi(unsigned w) { return __uint_as_float(w & 0xffff0000u); }
; #define PG8_WAIT_V(n) asm volatile("s_waitcnt vmcnt(" #n ")" ::: "memory")
; #define PG8_BAR __builtin_amdgcn_s_barrier()
; template <class Epi, class Ptrs>
; __device__ __forceinline__ void gemm_phase(LAS unsigned char* lds, const int K, const StaticOrder& S, const Ptrs& P, const Epi& E) {
;     ...
;         if (!has_next) break;
; #pragma unroll
;         for (int a = 0; a < 2; ++a)
; #pragma unroll
;             for (int b = 0; b < 2; ++b)
; #pragma unroll
;                 for (int m = 0; m < 4; ++m)
; #pragma unroll
;                     for (int n = 0; n < 2; ++n) acc[a][b][m][n] = (f32x4){0.f, 0.f, 0.f, 0.f};
;         cur = nxt; cA = nA; cB = nB; ++ui;
;     }
;     PG8_WAIT_V(0);
;     if (wr == 0) PG8_BAR;
;     PG8_BAR;
;     __device__ __forceinline__ void operator()(const f32x4 (&acc)[2][2][4][2], const Unit& u, int ui, int wr, int wc, int fr, int fq) const {
;     ...
; #pragma unroll
;         for (int ai = 0; ai < 2; ++ai)
; #pragma unroll
;             for (int m = 0; m < 4; ++m) { const int rl = rl0 + ai * 128 + m * 16; float* rowp = out + (size_t)(u.pm * 256 + rl) * DM + col0;
;                 const float r2 = tab[ui * 256 + rl];
; #pragma unroll
;                 for (int bj = 0; bj < 2; ++bj) { const u32x4 x = xv[ai][m][bj];
;                     const f32x4 x0 = {bf_lo(x.x), bf_hi(x.x), bf_lo(x.y), bf_hi(x.y)}, x1 = {bf_lo(x.z), bf_hi(x.z), bf_lo(x.w), bf_hi(x.w)};
;                     *(f32x4*)(rowp + bj * 128) = acc[ai][bj][m][0] * r2 + x0; *(f32x4*)(rowp + bj * 128 + 4) = acc[ai][bj][m][1] * r2 + x1; } }
	v_pk_fma_f32 v[62:63], v[62:63], v[66:67], v[70:71] op_sel_hi:[1,0,1]
	v_pk_fma_f32 v[60:61], v[60:61], v[66:67], v[68:69] op_sel_hi:[1,0,1]
	global_store_dwordx4 v[64:65], v[60:63], off
	v_pk_fma_f32 v[58:59], v[58:59], v[66:67], v[74:75] op_sel_hi:[1,0,1]
	v_pk_fma_f32 v[56:57], v[56:57], v[66:67], v[72:73] op_sel_hi:[1,0,1]
	v_lshlrev_b32_e32 v60, 16, v154
	v_and_b32_e32 v61, 0xffff0000, v154
	v_lshlrev_b32_e32 v62, 16, v155
	v_and_b32_e32 v63, 0xffff0000, v155
	global_store_dwordx4 v[64:65], v[56:59], off offset:16
	v_pk_fma_f32 v[46:47], v[46:47], v[66:67], v[62:63] op_sel_hi:[1,0,1]
	v_pk_fma_f32 v[44:45], v[44:45], v[66:67], v[60:61] op_sel_hi:[1,0,1]
	v_lshlrev_b32_e32 v56, 16, v152
	v_and_b32_e32 v57, 0xffff0000, v152
	v_lshlrev_b32_e32 v58, 16, v153
	v_and_b32_e32 v59, 0xffff0000, v153
	v_pk_fma_f32 v[54:55], v[54:55], v[66:67], v[58:59] op_sel_hi:[1,0,1]
	v_pk_fma_f32 v[52:53], v[52:53], v[66:67], v[56:57] op_sel_hi:[1,0,1]
	global_store_dwordx4 v[64:65], v[44:47], off offset:528
	global_store_dwordx4 v[64:65], v[52:55], off offset:512
	v_lshlrev_b32_e32 v56, 16, v151
	v_lshlrev_b64 v[44:45], 12, v[182:183]
	v_lshl_add_u64 v[44:45], s[26:27], 0, v[44:45]
	v_lshlrev_b32_e32 v54, 16, v150
	v_and_b32_e32 v55, 0xffff0000, v150
	v_and_b32_e32 v57, 0xffff0000, v151
	v_mov_b32_e32 v58, v67
	v_lshl_add_u64 v[52:53], v[44:45], 0, v[176:177]
	v_pk_fma_f32 v[42:43], v[42:43], v[58:59], v[56:57] op_sel_hi:[1,0,1]
	v_pk_fma_f32 v[40:41], v[40:41], v[58:59], v[54:55] op_sel_hi:[1,0,1]
	v_lshlrev_b32_e32 v44, 16, v148
	v_and_b32_e32 v45, 0xffff0000, v148
	v_lshlrev_b32_e32 v46, 16, v149
	v_and_b32_e32 v47, 0xffff0000, v149
	global_store_dwordx4 v[52:53], v[40:43], off offset:16
	v_pk_fma_f32 v[46:47], v[50:51], v[58:59], v[46:47] op_sel_hi:[1,0,1]
	v_pk_fma_f32 v[44:45], v[48:49], v[58:59], v[44:45] op_sel_hi:[1,0,1]
	v_lshlrev_b32_e32 v40, 16, v144
	v_and_b32_e32 v41, 0xffff0000, v144
	v_lshlrev_b32_e32 v42, 16, v145
	v_and_b32_e32 v43, 0xffff0000, v145
	v_pk_fma_f32 v[38:39], v[38:39], v[58:59], v[42:43] op_sel_hi:[1,0,1]
	v_pk_fma_f32 v[36:37], v[36:37], v[58:59], v[40:41] op_sel_hi:[1,0,1]
	global_store_dwordx4 v[52:53], v[44:47], off
	global_store_dwordx4 v[52:53], v[36:39], off offset:512
	ds_read2_b32 v[38:39], v196 offset0:160 offset1:176
	v_lshlrev_b32_e32 v44, 16, v146
	v_and_b32_e32 v45, 0xffff0000, v146
	v_lshlrev_b32_e32 v46, 16, v147
	v_and_b32_e32 v47, 0xffff0000, v147
	v_pk_fma_f32 v[30:31], v[30:31], v[58:59], v[46:47] op_sel_hi:[1,0,1]
	v_pk_fma_f32 v[28:29], v[28:29], v[58:59], v[44:45] op_sel_hi:[1,0,1]
	global_store_dwordx4 v[52:53], v[28:31], off offset:528
	v_lshlrev_b32_e32 v40, 16, v142
	v_and_b32_e32 v41, 0xffff0000, v142
	v_lshlrev_b64 v[28:29], 12, v[180:181]
	v_lshl_add_u64 v[28:29], s[26:27], 0, v[28:29]
	v_lshl_add_u64 v[36:37], v[28:29], 0, v[176:177]
	v_lshlrev_b32_e32 v28, 16, v140
	v_and_b32_e32 v29, 0xffff0000, v140
	v_lshlrev_b32_e32 v30, 16, v141
	v_and_b32_e32 v31, 0xffff0000, v141
	s_waitcnt lgkmcnt(0)
	v_pk_fma_f32 v[30:31], v[34:35], v[38:39], v[30:31] op_sel_hi:[1,0,1]
	v_pk_fma_f32 v[28:29], v[32:33], v[38:39], v[28:29] op_sel_hi:[1,0,1]
	v_lshlrev_b32_e32 v42, 16, v143
	v_and_b32_e32 v43, 0xffff0000, v143
	global_store_dwordx4 v[36:37], v[28:31], off
	v_pk_fma_f32 v[26:27], v[26:27], v[38:39], v[42:43] op_sel_hi:[1,0,1]
	v_pk_fma_f32 v[24:25], v[24:25], v[38:39], v[40:41] op_sel_hi:[1,0,1]
	v_lshlrev_b32_e32 v28, 16, v138
	v_and_b32_e32 v29, 0xffff0000, v138
	v_lshlrev_b32_e32 v30, 16, v139
	v_and_b32_e32 v31, 0xffff0000, v139
	v_pk_fma_f32 v[14:15], v[14:15], v[38:39], v[30:31] op_sel_hi:[1,0,1]
	v_pk_fma_f32 v[12:13], v[12:13], v[38:39], v[28:29] op_sel_hi:[1,0,1]
	global_store_dwordx4 v[36:37], v[24:27], off offset:16
	global_store_dwordx4 v[36:37], v[12:15], off offset:528
	s_nop 0
	v_lshlrev_b32_e32 v24, 16, v136
	v_and_b32_e32 v25, 0xffff0000, v136
	v_lshlrev_b32_e32 v26, 16, v137
	v_and_b32_e32 v27, 0xffff0000, v137
	v_lshlrev_b64 v[12:13], 12, v[178:179]
	v_pk_fma_f32 v[22:23], v[22:23], v[38:39], v[26:27] op_sel_hi:[1,0,1]
	v_pk_fma_f32 v[20:21], v[20:21], v[38:39], v[24:25] op_sel_hi:[1,0,1]
	v_lshl_add_u64 v[12:13], s[26:27], 0, v[12:13]
	global_store_dwordx4 v[36:37], v[20:23], off offset:512
	v_lshlrev_b32_e32 v14, 16, v133
	v_and_b32_e32 v15, 0xffff0000, v133
	v_lshl_add_u64 v[20:21], v[12:13], 0, v[176:177]
	v_lshlrev_b32_e32 v12, 16, v132
	v_and_b32_e32 v13, 0xffff0000, v132
	v_lshlrev_b32_e32 v22, 16, v134
	v_and_b32_e32 v23, 0xffff0000, v134
	v_lshlrev_b32_e32 v24, 16, v135
	v_and_b32_e32 v25, 0xffff0000, v135
	v_mov_b32_e32 v26, v39
	v_pk_fma_f32 v[14:15], v[18:19], v[26:27], v[14:15] op_sel_hi:[1,0,1]
	v_pk_fma_f32 v[12:13], v[16:17], v[26:27], v[12:13] op_sel_hi:[1,0,1]
	v_pk_fma_f32 v[10:11], v[10:11], v[26:27], v[24:25] op_sel_hi:[1,0,1]
	v_pk_fma_f32 v[8:9], v[8:9], v[26:27], v[22:23] op_sel_hi:[1,0,1]
	global_store_dwordx4 v[20:21], v[12:15], off
	global_store_dwordx4 v[20:21], v[8:11], off offset:16
	s_nop 0
	v_lshlrev_b32_e32 v12, 16, v130
	v_lshlrev_b32_e32 v8, 16, v128
	v_and_b32_e32 v9, 0xffff0000, v128
	v_lshlrev_b32_e32 v10, 16, v129
	v_and_b32_e32 v11, 0xffff0000, v129
	v_and_b32_e32 v13, 0xffff0000, v130
	v_lshlrev_b32_e32 v14, 16, v131
	v_and_b32_e32 v15, 0xffff0000, v131
	v_pk_fma_f32 v[6:7], v[6:7], v[26:27], v[10:11] op_sel_hi:[1,0,1]
	v_pk_fma_f32 v[4:5], v[4:5], v[26:27], v[8:9] op_sel_hi:[1,0,1]
	v_pk_fma_f32 v[2:3], v[2:3], v[26:27], v[14:15] op_sel_hi:[1,0,1]
	v_pk_fma_f32 v[0:1], v[0:1], v[26:27], v[12:13] op_sel_hi:[1,0,1]
	global_store_dwordx4 v[20:21], v[4:7], off offset:512
	global_store_dwordx4 v[20:21], v[0:3], off offset:528
	s_cbranch_vccz .LBB0_517
	s_waitcnt vmcnt(0)
	s_setprio 0
	s_cmpk_gt_u32 s33, 0xff
	s_cbranch_scc1 .LBB0_526
	s_barrier
